# residual epilogues: row-sum lane exchange via v_permlane16/32_swap instead of ds_bpermute round trips
# baseline (speedup 1.0000x reference)
; __device__ __forceinline__ unsigned cvt_pk_bf16(float lo, float hi) { unsigned r; asm volatile("v_cvt_pk_bf16_f32 %0, %1, %2" : "=v"(r) : "v"(lo), "v"(hi)); return r; }
;     __device__ __forceinline__ void operator()(const f32x4 (&acc)[2][2][4][2], const pg8::Unit& u, int wr, int wc, int fr, int fq) const {
;         const int row0 = u.pm * 256 + wr * 64 + fr, col0 = u.pn * 256 + wc * 32 + 8 * fq;
;         u32x4 xin[2][4][2];
; #pragma unroll
;         for (int ai = 0; ai < 2; ++ai)
; #pragma unroll
;             for (int m = 0; m < 4; ++m)
; #pragma unroll
;                 for (int bj = 0; bj < 2; ++bj) xin[ai][m][bj] = *(const u32x4*)(XB + (size_t)(row0 + ai * 128 + m * 16) * D + col0 + bj * 128);
; #pragma unroll
;         for (int ai = 0; ai < 2; ++ai)
; #pragma unroll
;             for (int m = 0; m < 4; ++m) { const size_t ro = (size_t)(row0 + ai * 128 + m * 16) * D + col0; float sq = 0.f;
; #pragma unroll
;                 for (int bj = 0; bj < 2; ++bj) { const u32x4 xb = xin[ai][m][bj];
;                     const f32x4 x0 = (f32x4){bf_lo(xb.x), bf_hi(xb.x), bf_lo(xb.y), bf_hi(xb.y)} + acc[ai][bj][m][0] * s, x1 = (f32x4){bf_lo(xb.z), bf_hi(xb.z), bf_lo(xb.w), bf_hi(xb.w)} + acc[ai][bj][m][1] * s;
;                     sq += (x0[0] * x0[0] + x0[1] * x0[1]) + (x0[2] * x0[2] + x0[3] * x0[3]) + (x1[0] * x1[0] + x1[1] * x1[1]) + (x1[2] * x1[2] + x1[3] * x1[3]);
;                     u32x4 w; w.x = cvt_pk_bf16(x0[0], x0[1]); w.y = cvt_pk_bf16(x0[2], x0[3]); w.z = cvt_pk_bf16(x1[0], x1[1]); w.w = cvt_pk_bf16(x1[2], x1[3]);
;                     *(u32x4*)(XB + ro + bj * 128) = w; }
;                 sq += __shfl_xor(sq, 16); sq += __shfl_xor(sq, 32);
;                 if (fq == 0) SSo[(size_t)(u.pn * 4 + wc) * T + row0 + ai * 128 + m * 16] = sq; }
.LBB0_312:
	v_lshl_or_b32 v204, s71, 8, v222
	v_lshl_add_u32 v202, s72, 8, v220
	v_ashrrev_i32_e32 v205, 31, v204
	v_lshlrev_b64 v[236:237], 1, v[204:205]
	v_ashrrev_i32_e32 v203, 31, v202
	v_lshl_add_u64 v[96:97], s[36:37], 0, v[236:237]
	v_lshlrev_b64 v[238:239], 11, v[202:203]
	v_lshl_add_u64 v[98:99], v[96:97], 0, v[238:239]
	global_load_dwordx4 v[228:231], v[98:99], off
	global_load_dwordx4 v[232:235], v[98:99], off offset:256
	v_or_b32_e32 v98, 16, v202
	v_or_b32_e32 v108, 32, v202
	v_or_b32_e32 v110, 48, v202
	v_ashrrev_i32_e32 v99, 31, v98
	v_ashrrev_i32_e32 v109, 31, v108
	v_ashrrev_i32_e32 v111, 31, v110
	v_lshlrev_b64 v[218:219], 11, v[98:99]
	v_lshlrev_b64 v[216:217], 11, v[108:109]
	v_lshlrev_b64 v[214:215], 11, v[110:111]
	v_lshl_add_u64 v[212:213], v[238:239], 0, s[16:17]
	v_lshl_add_u64 v[210:211], v[238:239], 0, s[18:19]
	v_lshl_add_u64 v[208:209], v[238:239], 0, s[42:43]
	v_lshl_add_u64 v[206:207], v[238:239], 0, s[46:47]
	v_lshl_add_u64 v[98:99], v[96:97], 0, v[218:219]
	v_lshl_add_u64 v[108:109], v[96:97], 0, v[216:217]
	v_lshl_add_u64 v[110:111], v[96:97], 0, v[214:215]
	v_lshl_add_u64 v[120:121], v[96:97], 0, v[212:213]
	v_lshl_add_u64 v[122:123], v[96:97], 0, v[210:211]
	v_lshl_add_u64 v[240:241], v[96:97], 0, v[208:209]
	v_lshl_add_u64 v[96:97], v[96:97], 0, v[206:207]
	global_load_dwordx4 v[180:183], v[98:99], off
	global_load_dwordx4 v[176:179], v[98:99], off offset:256
	global_load_dwordx4 v[172:175], v[108:109], off
	global_load_dwordx4 v[168:171], v[108:109], off offset:256
	global_load_dwordx4 v[164:167], v[110:111], off
	global_load_dwordx4 v[160:163], v[110:111], off offset:256
	global_load_dwordx4 v[156:159], v[120:121], off
	global_load_dwordx4 v[152:155], v[120:121], off offset:256
	global_load_dwordx4 v[148:151], v[122:123], off
	global_load_dwordx4 v[144:147], v[122:123], off offset:256
	global_load_dwordx4 v[128:131], v[240:241], off
	s_nop 0
	global_load_dwordx4 v[120:123], v[240:241], off offset:256
	global_load_dwordx4 v[108:111], v[96:97], off
	s_nop 0
	global_load_dwordx4 v[96:99], v[96:97], off offset:256
	s_lshl_b32 s20, s71, 2
	s_or_b32 s20, s20, s61
	s_ashr_i32 s21, s20, 31
	s_lshl_b64 s[20:21], s[20:21], 17
	s_waitcnt vmcnt(0)
	v_lshlrev_b32_e32 v240, 16, v228
	v_and_b32_e32 v241, 0xffff0000, v228
	v_lshlrev_b32_e32 v228, 16, v229
	v_and_b32_e32 v229, 0xffff0000, v229
	v_lshlrev_b32_e32 v242, 16, v230
	v_and_b32_e32 v243, 0xffff0000, v230
	v_lshlrev_b32_e32 v244, 16, v232
	v_and_b32_e32 v245, 0xffff0000, v232
	v_lshlrev_b32_e32 v232, 16, v233
	v_and_b32_e32 v233, 0xffff0000, v233
	v_lshlrev_b32_e32 v246, 16, v234
	v_and_b32_e32 v247, 0xffff0000, v234
	v_lshlrev_b32_e32 v234, 16, v235
	v_and_b32_e32 v235, 0xffff0000, v235
	v_pk_fma_f32 v[142:143], v[142:143], 0.5, v[228:229] op_sel_hi:[1,0,1]
	v_pk_fma_f32 v[140:141], v[140:141], 0.5, v[240:241] op_sel_hi:[1,0,1]
	v_lshlrev_b32_e32 v230, 16, v231
	v_and_b32_e32 v231, 0xffff0000, v231
	v_pk_fma_f32 v[136:137], v[136:137], 0.5, v[242:243] op_sel_hi:[1,0,1]
	v_pk_fma_f32 v[228:229], v[134:135], 0.5, v[232:233] op_sel_hi:[1,0,1]
	v_pk_fma_f32 v[232:233], v[126:127], 0.5, v[234:235] op_sel_hi:[1,0,1]
	v_pk_fma_f32 v[234:235], v[124:125], 0.5, v[246:247] op_sel_hi:[1,0,1]
	v_mul_f32_e32 v124, v141, v141
	v_mul_f32_e32 v125, v143, v143
	v_pk_fma_f32 v[138:139], v[138:139], 0.5, v[230:231] op_sel_hi:[1,0,1]
	v_pk_fma_f32 v[230:231], v[132:133], 0.5, v[244:245] op_sel_hi:[1,0,1]
	v_mul_f32_e32 v126, v137, v137
	v_fmac_f32_e32 v124, v140, v140
	v_fmac_f32_e32 v125, v142, v142
	v_mul_f32_e32 v127, v139, v139
	v_cvt_pk_bf16_f32 v132, v140, v141
	v_cvt_pk_bf16_f32 v133, v142, v143
	v_cvt_pk_bf16_f32 v134, v136, v137
	v_cvt_pk_bf16_f32 v135, v138, v139
	v_mul_f32_e32 v137, v231, v231
	v_mul_f32_e32 v139, v229, v229
	v_fmac_f32_e32 v126, v136, v136
	v_add_f32_e32 v124, v124, v125
	v_fmac_f32_e32 v137, v230, v230
	v_fmac_f32_e32 v139, v228, v228
	v_add_f32_e32 v124, v126, v124
	v_mul_f32_e32 v126, v235, v235
	v_add_f32_e32 v125, v137, v139
	v_fmac_f32_e32 v126, v234, v234
	v_add_f32_e32 v125, v126, v125
	v_mul_f32_e32 v126, v233, v233
	v_fmac_f32_e32 v127, v138, v138
	v_fmac_f32_e32 v126, v232, v232
	v_add_f32_e32 v124, v127, v124
	v_add_f32_e32 v125, v126, v125
	v_and_b32_e32 v126, 64, v226
	v_add_f32_e32 v125, v124, v125
	v_add_u32_e32 v138, 64, v126
	v_lshl_add_u64 v[126:127], s[36:37], 0, v[238:239]
	v_lshl_add_u64 v[136:137], v[126:127], 0, v[236:237]
	v_mov_b32_e32 v139, v125
	s_nop 1
	v_permlane16_swap_b32_e32 v139, v125
	global_store_dwordx4 v[136:137], v[132:135], off
	s_waitcnt lgkmcnt(0)
	v_add_f32_e32 v126, v125, v139
	v_cvt_pk_bf16_f32 v132, v230, v231
	v_cvt_pk_bf16_f32 v133, v228, v229
	v_cvt_pk_bf16_f32 v134, v234, v235
	v_cvt_pk_bf16_f32 v135, v232, v233
	global_store_dwordx4 v[136:137], v[132:135], off offset:256
	s_nop 0
	v_mov_b32_e32 v127, v126
	s_nop 1
	v_permlane32_swap_b32_e32 v127, v126
	s_and_saveexec_b64 s[34:35], s[4:5]
	s_cbranch_execz .LBB0_314
	s_add_u32 s50, s59, s20
	s_addc_u32 s51, s60, s21
	v_lshl_add_u64 v[132:133], v[202:203], 2, s[50:51]
	s_waitcnt lgkmcnt(0)
	v_add_f32_e32 v126, v126, v127
	global_store_dword v[132:133], v126, off
; __device__ __forceinline__ unsigned cvt_pk_bf16(float lo, float hi) { unsigned r; asm volatile("v_cvt_pk_bf16_f32 %0, %1, %2" : "=v"(r) : "v"(lo), "v"(hi)); return r; }
;     __device__ __forceinline__ void operator()(const f32x4 (&acc)[2][2][4][2], const pg8::Unit& u, int wr, int wc, int fr, int fq) const {
;     ...
;             for (int m = 0; m < 4; ++m) { const size_t ro = (size_t)(row0 + ai * 128 + m * 16) * D + col0; float sq = 0.f;
; #pragma unroll
;                 for (int bj = 0; bj < 2; ++bj) { const u32x4 xb = xin[ai][m][bj];
;                     const f32x4 x0 = (f32x4){bf_lo(xb.x), bf_hi(xb.x), bf_lo(xb.y), bf_hi(xb.y)} + acc[ai][bj][m][0] * s, x1 = (f32x4){bf_lo(xb.z), bf_hi(xb.z), bf_lo(xb.w), bf_hi(xb.w)} + acc[ai][bj][m][1] * s;
;                     sq += (x0[0] * x0[0] + x0[1] * x0[1]) + (x0[2] * x0[2] + x0[3] * x0[3]) + (x1[0] * x1[0] + x1[1] * x1[1]) + (x1[2] * x1[2] + x1[3] * x1[3]);
;                     u32x4 w; w.x = cvt_pk_bf16(x0[0], x0[1]); w.y = cvt_pk_bf16(x0[2], x0[3]); w.z = cvt_pk_bf16(x1[0], x1[1]); w.w = cvt_pk_bf16(x1[2], x1[3]);
;                     *(u32x4*)(XB + ro + bj * 128) = w; }
;                 sq += __shfl_xor(sq, 16); sq += __shfl_xor(sq, 32);
;                 if (fq == 0) SSo[(size_t)(u.pn * 4 + wc) * T + row0 + ai * 128 + m * 16] = sq; }
.LBB0_314:
	s_or_b64 exec, exec, s[34:35]
	v_lshlrev_b32_e32 v126, 16, v180
	s_waitcnt lgkmcnt(0)
	v_and_b32_e32 v127, 0xffff0000, v180
	v_lshlrev_b32_e32 v132, 16, v181
	v_and_b32_e32 v133, 0xffff0000, v181
	v_pk_fma_f32 v[118:119], v[118:119], 0.5, v[132:133] op_sel_hi:[1,0,1]
	v_pk_fma_f32 v[116:117], v[116:117], 0.5, v[126:127] op_sel_hi:[1,0,1]
	v_lshlrev_b32_e32 v126, 16, v182
	v_and_b32_e32 v127, 0xffff0000, v182
	v_lshlrev_b32_e32 v132, 16, v183
	v_and_b32_e32 v133, 0xffff0000, v183
	v_pk_fma_f32 v[132:133], v[114:115], 0.5, v[132:133] op_sel_hi:[1,0,1]
	v_pk_fma_f32 v[114:115], v[112:113], 0.5, v[126:127] op_sel_hi:[1,0,1]
	v_mul_f32_e32 v112, v117, v117
	v_mul_f32_e32 v113, v119, v119
	v_fmac_f32_e32 v112, v116, v116
	v_fmac_f32_e32 v113, v118, v118
	v_add_f32_e32 v112, v112, v113
	v_mul_f32_e32 v113, v115, v115
	v_fmac_f32_e32 v113, v114, v114
	v_add_f32_e32 v112, v113, v112
	v_mul_f32_e32 v113, v133, v133
	v_fmac_f32_e32 v113, v132, v132
	v_add_f32_e32 v126, v113, v112
	v_cvt_pk_bf16_f32 v112, v116, v117
	v_cvt_pk_bf16_f32 v113, v118, v119
	v_lshlrev_b32_e32 v116, 16, v176
	v_and_b32_e32 v117, 0xffff0000, v176
	v_lshlrev_b32_e32 v118, 16, v177
	v_and_b32_e32 v119, 0xffff0000, v177
	v_pk_fma_f32 v[106:107], v[106:107], 0.5, v[118:119] op_sel_hi:[1,0,1]
	v_pk_fma_f32 v[104:105], v[104:105], 0.5, v[116:117] op_sel_hi:[1,0,1]
	v_lshlrev_b32_e32 v116, 16, v178
	v_and_b32_e32 v117, 0xffff0000, v178
	v_pk_fma_f32 v[116:117], v[100:101], 0.5, v[116:117] op_sel_hi:[1,0,1]
	v_mul_f32_e32 v100, v105, v105
	v_mul_f32_e32 v101, v107, v107
	v_fmac_f32_e32 v100, v104, v104
	v_fmac_f32_e32 v101, v106, v106
	v_lshlrev_b32_e32 v118, 16, v179
	v_and_b32_e32 v119, 0xffff0000, v179
	v_add_f32_e32 v100, v100, v101
	v_mul_f32_e32 v101, v117, v117
	v_pk_fma_f32 v[118:119], v[102:103], 0.5, v[118:119] op_sel_hi:[1,0,1]
	v_fmac_f32_e32 v101, v116, v116
	v_add_f32_e32 v100, v101, v100
	v_mul_f32_e32 v101, v119, v119
	v_fmac_f32_e32 v101, v118, v118
	v_add_f32_e32 v100, v101, v100
	v_add_f32_e32 v103, v126, v100
	v_cvt_pk_bf16_f32 v114, v114, v115
	v_cvt_pk_bf16_f32 v115, v132, v133
	v_mov_b32_e32 v132, v103
	s_nop 1
	v_permlane16_swap_b32_e32 v132, v103
	v_lshl_add_u64 v[100:101], s[36:37], 0, v[218:219]
	v_lshl_add_u64 v[126:127], v[204:205], 1, v[100:101]
	global_store_dwordx4 v[126:127], v[112:115], off
	v_cvt_pk_bf16_f32 v102, v104, v105
	s_waitcnt lgkmcnt(0)
	v_add_f32_e32 v100, v103, v132
	v_mov_b32_e32 v101, v100
	s_nop 1
	v_permlane32_swap_b32_e32 v101, v100
	v_cvt_pk_bf16_f32 v103, v106, v107
	v_cvt_pk_bf16_f32 v104, v116, v117
	v_cvt_pk_bf16_f32 v105, v118, v119
	global_store_dwordx4 v[126:127], v[102:105], off offset:256
	s_and_saveexec_b64 s[34:35], s[4:5]
	s_cbranch_execz .LBB0_316
	s_add_u32 s50, s59, s20
	s_addc_u32 s51, s60, s21
	v_lshl_add_u64 v[102:103], v[202:203], 2, s[50:51]
	s_waitcnt lgkmcnt(0)
	v_add_f32_e32 v100, v100, v101
	global_store_dword v[102:103], v100, off offset:64
.LBB0_316:
	s_or_b64 exec, exec, s[34:35]
	v_lshlrev_b32_e32 v100, 16, v172
	s_waitcnt lgkmcnt(0)
	v_and_b32_e32 v101, 0xffff0000, v172
	v_lshlrev_b32_e32 v102, 16, v173
	v_and_b32_e32 v103, 0xffff0000, v173
	v_pk_fma_f32 v[94:95], v[94:95], 0.5, v[102:103] op_sel_hi:[1,0,1]
	v_pk_fma_f32 v[92:93], v[92:93], 0.5, v[100:101] op_sel_hi:[1,0,1]
	v_lshlrev_b32_e32 v100, 16, v174
	v_and_b32_e32 v101, 0xffff0000, v174
	v_lshlrev_b32_e32 v102, 16, v175
	v_and_b32_e32 v103, 0xffff0000, v175
	v_pk_fma_f32 v[102:103], v[90:91], 0.5, v[102:103] op_sel_hi:[1,0,1]
	v_pk_fma_f32 v[90:91], v[88:89], 0.5, v[100:101] op_sel_hi:[1,0,1]
	v_mul_f32_e32 v88, v93, v93
	v_mul_f32_e32 v89, v95, v95
	v_fmac_f32_e32 v88, v92, v92
	v_fmac_f32_e32 v89, v94, v94
	v_add_f32_e32 v88, v88, v89
	v_mul_f32_e32 v89, v91, v91
	v_fmac_f32_e32 v89, v90, v90
	v_add_f32_e32 v88, v89, v88
	v_mul_f32_e32 v89, v103, v103
	v_fmac_f32_e32 v89, v102, v102
	v_add_f32_e32 v100, v89, v88
	v_cvt_pk_bf16_f32 v88, v92, v93
	v_cvt_pk_bf16_f32 v89, v94, v95
	v_lshlrev_b32_e32 v92, 16, v168
	v_and_b32_e32 v93, 0xffff0000, v168
	v_lshlrev_b32_e32 v94, 16, v169
	v_and_b32_e32 v95, 0xffff0000, v169
	v_pk_fma_f32 v[86:87], v[86:87], 0.5, v[94:95] op_sel_hi:[1,0,1]
	v_pk_fma_f32 v[84:85], v[84:85], 0.5, v[92:93] op_sel_hi:[1,0,1]
	v_lshlrev_b32_e32 v92, 16, v170
	v_and_b32_e32 v93, 0xffff0000, v170
	v_pk_fma_f32 v[92:93], v[80:81], 0.5, v[92:93] op_sel_hi:[1,0,1]
	v_mul_f32_e32 v80, v85, v85
	v_mul_f32_e32 v81, v87, v87
	v_fmac_f32_e32 v80, v84, v84
	v_fmac_f32_e32 v81, v86, v86
	v_lshlrev_b32_e32 v94, 16, v171
	v_and_b32_e32 v95, 0xffff0000, v171
	v_add_f32_e32 v80, v80, v81
	v_mul_f32_e32 v81, v93, v93
	v_pk_fma_f32 v[94:95], v[82:83], 0.5, v[94:95] op_sel_hi:[1,0,1]
	v_fmac_f32_e32 v81, v92, v92
	v_add_f32_e32 v80, v81, v80
	v_mul_f32_e32 v81, v95, v95
	v_fmac_f32_e32 v81, v94, v94
	v_add_f32_e32 v80, v81, v80
	v_add_f32_e32 v83, v100, v80
	v_cvt_pk_bf16_f32 v90, v90, v91
	v_cvt_pk_bf16_f32 v91, v102, v103
	v_mov_b32_e32 v102, v83
	s_nop 1
	v_permlane16_swap_b32_e32 v102, v83
	v_lshl_add_u64 v[80:81], s[36:37], 0, v[216:217]
	v_lshl_add_u64 v[100:101], v[204:205], 1, v[80:81]
	global_store_dwordx4 v[100:101], v[88:91], off
	v_cvt_pk_bf16_f32 v82, v84, v85
	s_waitcnt lgkmcnt(0)
	v_add_f32_e32 v80, v83, v102
	v_mov_b32_e32 v81, v80
	s_nop 1
	v_permlane32_swap_b32_e32 v81, v80
	v_cvt_pk_bf16_f32 v83, v86, v87
	v_cvt_pk_bf16_f32 v84, v92, v93
	v_cvt_pk_bf16_f32 v85, v94, v95
	global_store_dwordx4 v[100:101], v[82:85], off offset:256
	s_and_saveexec_b64 s[34:35], s[4:5]
	s_cbranch_execz .LBB0_318
	s_add_u32 s50, s59, s20
	s_addc_u32 s51, s60, s21
	v_lshl_add_u64 v[82:83], v[202:203], 2, s[50:51]
	s_waitcnt lgkmcnt(0)
	v_add_f32_e32 v80, v80, v81
	global_store_dword v[82:83], v80, off offset:128
; __device__ __forceinline__ unsigned cvt_pk_bf16(float lo, float hi) { unsigned r; asm volatile("v_cvt_pk_bf16_f32 %0, %1, %2" : "=v"(r) : "v"(lo), "v"(hi)); return r; }
;     __device__ __forceinline__ void operator()(const f32x4 (&acc)[2][2][4][2], const pg8::Unit& u, int wr, int wc, int fr, int fq) const {
;     ...
;             for (int m = 0; m < 4; ++m) { const size_t ro = (size_t)(row0 + ai * 128 + m * 16) * D + col0; float sq = 0.f;
; #pragma unroll
;                 for (int bj = 0; bj < 2; ++bj) { const u32x4 xb = xin[ai][m][bj];
;                     const f32x4 x0 = (f32x4){bf_lo(xb.x), bf_hi(xb.x), bf_lo(xb.y), bf_hi(xb.y)} + acc[ai][bj][m][0] * s, x1 = (f32x4){bf_lo(xb.z), bf_hi(xb.z), bf_lo(xb.w), bf_hi(xb.w)} + acc[ai][bj][m][1] * s;
;                     sq += (x0[0] * x0[0] + x0[1] * x0[1]) + (x0[2] * x0[2] + x0[3] * x0[3]) + (x1[0] * x1[0] + x1[1] * x1[1]) + (x1[2] * x1[2] + x1[3] * x1[3]);
;                     u32x4 w; w.x = cvt_pk_bf16(x0[0], x0[1]); w.y = cvt_pk_bf16(x0[2], x0[3]); w.z = cvt_pk_bf16(x1[0], x1[1]); w.w = cvt_pk_bf16(x1[2], x1[3]);
;                     *(u32x4*)(XB + ro + bj * 128) = w; }
;                 sq += __shfl_xor(sq, 16); sq += __shfl_xor(sq, 32);
;                 if (fq == 0) SSo[(size_t)(u.pn * 4 + wc) * T + row0 + ai * 128 + m * 16] = sq; }
.LBB0_318:
	s_or_b64 exec, exec, s[34:35]
	v_lshlrev_b32_e32 v80, 16, v164
	s_waitcnt lgkmcnt(0)
	v_and_b32_e32 v81, 0xffff0000, v164
	v_lshlrev_b32_e32 v82, 16, v165
	v_and_b32_e32 v83, 0xffff0000, v165
	v_pk_fma_f32 v[78:79], v[78:79], 0.5, v[82:83] op_sel_hi:[1,0,1]
	v_pk_fma_f32 v[76:77], v[76:77], 0.5, v[80:81] op_sel_hi:[1,0,1]
	v_lshlrev_b32_e32 v80, 16, v166
	v_and_b32_e32 v81, 0xffff0000, v166
	v_lshlrev_b32_e32 v82, 16, v167
	v_and_b32_e32 v83, 0xffff0000, v167
	v_pk_fma_f32 v[82:83], v[74:75], 0.5, v[82:83] op_sel_hi:[1,0,1]
	v_pk_fma_f32 v[74:75], v[72:73], 0.5, v[80:81] op_sel_hi:[1,0,1]
	v_mul_f32_e32 v72, v77, v77
	v_mul_f32_e32 v73, v79, v79
	v_fmac_f32_e32 v72, v76, v76
	v_fmac_f32_e32 v73, v78, v78
	v_add_f32_e32 v72, v72, v73
	v_mul_f32_e32 v73, v75, v75
	v_fmac_f32_e32 v73, v74, v74
	v_add_f32_e32 v72, v73, v72
	v_mul_f32_e32 v73, v83, v83
	v_fmac_f32_e32 v73, v82, v82
	v_add_f32_e32 v80, v73, v72
	v_cvt_pk_bf16_f32 v72, v76, v77
	v_cvt_pk_bf16_f32 v73, v78, v79
	v_lshlrev_b32_e32 v76, 16, v160
	v_and_b32_e32 v77, 0xffff0000, v160
	v_lshlrev_b32_e32 v78, 16, v161
	v_and_b32_e32 v79, 0xffff0000, v161
	v_pk_fma_f32 v[70:71], v[70:71], 0.5, v[78:79] op_sel_hi:[1,0,1]
	v_pk_fma_f32 v[68:69], v[68:69], 0.5, v[76:77] op_sel_hi:[1,0,1]
	v_lshlrev_b32_e32 v76, 16, v162
	v_and_b32_e32 v77, 0xffff0000, v162
	v_pk_fma_f32 v[76:77], v[64:65], 0.5, v[76:77] op_sel_hi:[1,0,1]
	v_mul_f32_e32 v64, v69, v69
	v_mul_f32_e32 v65, v71, v71
	v_fmac_f32_e32 v64, v68, v68
	v_fmac_f32_e32 v65, v70, v70
	v_lshlrev_b32_e32 v78, 16, v163
	v_and_b32_e32 v79, 0xffff0000, v163
	v_add_f32_e32 v64, v64, v65
	v_mul_f32_e32 v65, v77, v77
	v_pk_fma_f32 v[78:79], v[66:67], 0.5, v[78:79] op_sel_hi:[1,0,1]
	v_fmac_f32_e32 v65, v76, v76
	v_add_f32_e32 v64, v65, v64
	v_mul_f32_e32 v65, v79, v79
	v_fmac_f32_e32 v65, v78, v78
	v_add_f32_e32 v64, v65, v64
	v_add_f32_e32 v67, v80, v64
	v_cvt_pk_bf16_f32 v74, v74, v75
	v_cvt_pk_bf16_f32 v75, v82, v83
	v_mov_b32_e32 v82, v67
	s_nop 1
	v_permlane16_swap_b32_e32 v82, v67
	v_lshl_add_u64 v[64:65], s[36:37], 0, v[214:215]
	v_lshl_add_u64 v[80:81], v[204:205], 1, v[64:65]
	global_store_dwordx4 v[80:81], v[72:75], off
	v_cvt_pk_bf16_f32 v66, v68, v69
	s_waitcnt lgkmcnt(0)
	v_add_f32_e32 v64, v67, v82
	v_mov_b32_e32 v65, v64
	s_nop 1
	v_permlane32_swap_b32_e32 v65, v64
	v_cvt_pk_bf16_f32 v67, v70, v71
	v_cvt_pk_bf16_f32 v68, v76, v77
	v_cvt_pk_bf16_f32 v69, v78, v79
	global_store_dwordx4 v[80:81], v[66:69], off offset:256
	s_and_saveexec_b64 s[34:35], s[4:5]
	s_cbranch_execz .LBB0_320
	s_add_u32 s50, s59, s20
	s_addc_u32 s51, s60, s21
	v_lshl_add_u64 v[66:67], v[202:203], 2, s[50:51]
	s_waitcnt lgkmcnt(0)
	v_add_f32_e32 v64, v64, v65
	global_store_dword v[66:67], v64, off offset:192
.LBB0_320:
	s_or_b64 exec, exec, s[34:35]
	v_lshlrev_b32_e32 v64, 16, v156
	s_waitcnt lgkmcnt(0)
	v_and_b32_e32 v65, 0xffff0000, v156
	v_lshlrev_b32_e32 v66, 16, v157
	v_and_b32_e32 v67, 0xffff0000, v157
	v_pk_fma_f32 v[62:63], v[62:63], 0.5, v[66:67] op_sel_hi:[1,0,1]
	v_pk_fma_f32 v[60:61], v[60:61], 0.5, v[64:65] op_sel_hi:[1,0,1]
	v_lshlrev_b32_e32 v64, 16, v158
	v_and_b32_e32 v65, 0xffff0000, v158
	v_lshlrev_b32_e32 v66, 16, v159
	v_and_b32_e32 v67, 0xffff0000, v159
	v_pk_fma_f32 v[66:67], v[58:59], 0.5, v[66:67] op_sel_hi:[1,0,1]
	v_pk_fma_f32 v[58:59], v[56:57], 0.5, v[64:65] op_sel_hi:[1,0,1]
	v_mul_f32_e32 v56, v61, v61
	v_mul_f32_e32 v57, v63, v63
	v_fmac_f32_e32 v56, v60, v60
	v_fmac_f32_e32 v57, v62, v62
	v_add_f32_e32 v56, v56, v57
	v_mul_f32_e32 v57, v59, v59
	v_fmac_f32_e32 v57, v58, v58
	v_add_f32_e32 v56, v57, v56
	v_mul_f32_e32 v57, v67, v67
	v_fmac_f32_e32 v57, v66, v66
	v_add_f32_e32 v64, v57, v56
	v_cvt_pk_bf16_f32 v56, v60, v61
	v_cvt_pk_bf16_f32 v57, v62, v63
	v_lshlrev_b32_e32 v60, 16, v152
	v_and_b32_e32 v61, 0xffff0000, v152
	v_lshlrev_b32_e32 v62, 16, v153
	v_and_b32_e32 v63, 0xffff0000, v153
	v_pk_fma_f32 v[54:55], v[54:55], 0.5, v[62:63] op_sel_hi:[1,0,1]
	v_pk_fma_f32 v[52:53], v[52:53], 0.5, v[60:61] op_sel_hi:[1,0,1]
	v_lshlrev_b32_e32 v60, 16, v154
	v_and_b32_e32 v61, 0xffff0000, v154
	v_pk_fma_f32 v[60:61], v[48:49], 0.5, v[60:61] op_sel_hi:[1,0,1]
	v_mul_f32_e32 v48, v53, v53
	v_mul_f32_e32 v49, v55, v55
	v_fmac_f32_e32 v48, v52, v52
	v_fmac_f32_e32 v49, v54, v54
	v_lshlrev_b32_e32 v62, 16, v155
	v_and_b32_e32 v63, 0xffff0000, v155
	v_add_f32_e32 v48, v48, v49
	v_mul_f32_e32 v49, v61, v61
	v_pk_fma_f32 v[62:63], v[50:51], 0.5, v[62:63] op_sel_hi:[1,0,1]
	v_fmac_f32_e32 v49, v60, v60
	v_add_f32_e32 v48, v49, v48
	v_mul_f32_e32 v49, v63, v63
	v_fmac_f32_e32 v49, v62, v62
	v_add_f32_e32 v48, v49, v48
	v_add_f32_e32 v51, v64, v48
	v_cvt_pk_bf16_f32 v58, v58, v59
	v_cvt_pk_bf16_f32 v59, v66, v67
	v_mov_b32_e32 v66, v51
	s_nop 1
	v_permlane16_swap_b32_e32 v66, v51
	v_lshl_add_u64 v[48:49], s[36:37], 0, v[212:213]
	v_lshl_add_u64 v[64:65], v[204:205], 1, v[48:49]
	global_store_dwordx4 v[64:65], v[56:59], off
	v_cvt_pk_bf16_f32 v50, v52, v53
	s_waitcnt lgkmcnt(0)
	v_add_f32_e32 v48, v51, v66
	v_mov_b32_e32 v49, v48
	s_nop 1
	v_permlane32_swap_b32_e32 v49, v48
	v_cvt_pk_bf16_f32 v51, v54, v55
	v_cvt_pk_bf16_f32 v52, v60, v61
	v_cvt_pk_bf16_f32 v53, v62, v63
	global_store_dwordx4 v[64:65], v[50:53], off offset:256
	s_and_saveexec_b64 s[34:35], s[4:5]
	s_cbranch_execz .LBB0_322
	s_add_u32 s50, s59, s20
	s_addc_u32 s51, s60, s21
	v_lshl_add_u64 v[50:51], v[202:203], 2, s[50:51]
	s_waitcnt lgkmcnt(0)
	v_add_f32_e32 v48, v48, v49
	global_store_dword v[50:51], v48, off offset:512
; __device__ __forceinline__ unsigned cvt_pk_bf16(float lo, float hi) { unsigned r; asm volatile("v_cvt_pk_bf16_f32 %0, %1, %2" : "=v"(r) : "v"(lo), "v"(hi)); return r; }
;     __device__ __forceinline__ void operator()(const f32x4 (&acc)[2][2][4][2], const pg8::Unit& u, int wr, int wc, int fr, int fq) const {
;     ...
;             for (int m = 0; m < 4; ++m) { const size_t ro = (size_t)(row0 + ai * 128 + m * 16) * D + col0; float sq = 0.f;
; #pragma unroll
;                 for (int bj = 0; bj < 2; ++bj) { const u32x4 xb = xin[ai][m][bj];
;                     const f32x4 x0 = (f32x4){bf_lo(xb.x), bf_hi(xb.x), bf_lo(xb.y), bf_hi(xb.y)} + acc[ai][bj][m][0] * s, x1 = (f32x4){bf_lo(xb.z), bf_hi(xb.z), bf_lo(xb.w), bf_hi(xb.w)} + acc[ai][bj][m][1] * s;
;                     sq += (x0[0] * x0[0] + x0[1] * x0[1]) + (x0[2] * x0[2] + x0[3] * x0[3]) + (x1[0] * x1[0] + x1[1] * x1[1]) + (x1[2] * x1[2] + x1[3] * x1[3]);
;                     u32x4 w; w.x = cvt_pk_bf16(x0[0], x0[1]); w.y = cvt_pk_bf16(x0[2], x0[3]); w.z = cvt_pk_bf16(x1[0], x1[1]); w.w = cvt_pk_bf16(x1[2], x1[3]);
;                     *(u32x4*)(XB + ro + bj * 128) = w; }
;                 sq += __shfl_xor(sq, 16); sq += __shfl_xor(sq, 32);
;                 if (fq == 0) SSo[(size_t)(u.pn * 4 + wc) * T + row0 + ai * 128 + m * 16] = sq; }
.LBB0_322:
	s_or_b64 exec, exec, s[34:35]
	v_lshlrev_b32_e32 v48, 16, v148
	s_waitcnt lgkmcnt(0)
	v_and_b32_e32 v49, 0xffff0000, v148
	v_lshlrev_b32_e32 v50, 16, v149
	v_and_b32_e32 v51, 0xffff0000, v149
	v_pk_fma_f32 v[46:47], v[46:47], 0.5, v[50:51] op_sel_hi:[1,0,1]
	v_pk_fma_f32 v[44:45], v[44:45], 0.5, v[48:49] op_sel_hi:[1,0,1]
	v_lshlrev_b32_e32 v48, 16, v150
	v_and_b32_e32 v49, 0xffff0000, v150
	v_lshlrev_b32_e32 v50, 16, v151
	v_and_b32_e32 v51, 0xffff0000, v151
	v_pk_fma_f32 v[50:51], v[42:43], 0.5, v[50:51] op_sel_hi:[1,0,1]
	v_pk_fma_f32 v[42:43], v[40:41], 0.5, v[48:49] op_sel_hi:[1,0,1]
	v_mul_f32_e32 v40, v45, v45
	v_mul_f32_e32 v41, v47, v47
	v_fmac_f32_e32 v40, v44, v44
	v_fmac_f32_e32 v41, v46, v46
	v_add_f32_e32 v40, v40, v41
	v_mul_f32_e32 v41, v43, v43
	v_fmac_f32_e32 v41, v42, v42
	v_add_f32_e32 v40, v41, v40
	v_mul_f32_e32 v41, v51, v51
	v_fmac_f32_e32 v41, v50, v50
	v_add_f32_e32 v48, v41, v40
	v_cvt_pk_bf16_f32 v40, v44, v45
	v_cvt_pk_bf16_f32 v41, v46, v47
	v_lshlrev_b32_e32 v44, 16, v144
	v_and_b32_e32 v45, 0xffff0000, v144
	v_lshlrev_b32_e32 v46, 16, v145
	v_and_b32_e32 v47, 0xffff0000, v145
	v_pk_fma_f32 v[38:39], v[38:39], 0.5, v[46:47] op_sel_hi:[1,0,1]
	v_pk_fma_f32 v[36:37], v[36:37], 0.5, v[44:45] op_sel_hi:[1,0,1]
	v_lshlrev_b32_e32 v44, 16, v146
	v_and_b32_e32 v45, 0xffff0000, v146
	v_pk_fma_f32 v[44:45], v[32:33], 0.5, v[44:45] op_sel_hi:[1,0,1]
	v_mul_f32_e32 v32, v37, v37
	v_mul_f32_e32 v33, v39, v39
	v_fmac_f32_e32 v32, v36, v36
	v_fmac_f32_e32 v33, v38, v38
	v_lshlrev_b32_e32 v46, 16, v147
	v_and_b32_e32 v47, 0xffff0000, v147
	v_add_f32_e32 v32, v32, v33
	v_mul_f32_e32 v33, v45, v45
	v_pk_fma_f32 v[46:47], v[34:35], 0.5, v[46:47] op_sel_hi:[1,0,1]
	v_fmac_f32_e32 v33, v44, v44
	v_add_f32_e32 v32, v33, v32
	v_mul_f32_e32 v33, v47, v47
	v_fmac_f32_e32 v33, v46, v46
	v_add_f32_e32 v32, v33, v32
	v_add_f32_e32 v35, v48, v32
	v_cvt_pk_bf16_f32 v42, v42, v43
	v_cvt_pk_bf16_f32 v43, v50, v51
	v_mov_b32_e32 v50, v35
	s_nop 1
	v_permlane16_swap_b32_e32 v50, v35
	v_lshl_add_u64 v[32:33], s[36:37], 0, v[210:211]
	v_lshl_add_u64 v[48:49], v[204:205], 1, v[32:33]
	global_store_dwordx4 v[48:49], v[40:43], off
	v_cvt_pk_bf16_f32 v34, v36, v37
	s_waitcnt lgkmcnt(0)
	v_add_f32_e32 v32, v35, v50
	v_mov_b32_e32 v33, v32
	s_nop 1
	v_permlane32_swap_b32_e32 v33, v32
	v_cvt_pk_bf16_f32 v35, v38, v39
	v_cvt_pk_bf16_f32 v36, v44, v45
	v_cvt_pk_bf16_f32 v37, v46, v47
	global_store_dwordx4 v[48:49], v[34:37], off offset:256
	s_and_saveexec_b64 s[34:35], s[4:5]
	s_cbranch_execz .LBB0_324
	s_add_u32 s50, s59, s20
	s_addc_u32 s51, s60, s21
	v_lshl_add_u64 v[34:35], v[202:203], 2, s[50:51]
	s_waitcnt lgkmcnt(0)
	v_add_f32_e32 v32, v32, v33
	global_store_dword v[34:35], v32, off offset:576
; __device__ __forceinline__ unsigned cvt_pk_bf16(float lo, float hi) { unsigned r; asm volatile("v_cvt_pk_bf16_f32 %0, %1, %2" : "=v"(r) : "v"(lo), "v"(hi)); return r; }
;     __device__ __forceinline__ void operator()(const f32x4 (&acc)[2][2][4][2], const pg8::Unit& u, int wr, int wc, int fr, int fq) const {
;     ...
;             for (int m = 0; m < 4; ++m) { const size_t ro = (size_t)(row0 + ai * 128 + m * 16) * D + col0; float sq = 0.f;
; #pragma unroll
;                 for (int bj = 0; bj < 2; ++bj) { const u32x4 xb = xin[ai][m][bj];
;                     const f32x4 x0 = (f32x4){bf_lo(xb.x), bf_hi(xb.x), bf_lo(xb.y), bf_hi(xb.y)} + acc[ai][bj][m][0] * s, x1 = (f32x4){bf_lo(xb.z), bf_hi(xb.z), bf_lo(xb.w), bf_hi(xb.w)} + acc[ai][bj][m][1] * s;
;                     sq += (x0[0] * x0[0] + x0[1] * x0[1]) + (x0[2] * x0[2] + x0[3] * x0[3]) + (x1[0] * x1[0] + x1[1] * x1[1]) + (x1[2] * x1[2] + x1[3] * x1[3]);
;                     u32x4 w; w.x = cvt_pk_bf16(x0[0], x0[1]); w.y = cvt_pk_bf16(x0[2], x0[3]); w.z = cvt_pk_bf16(x1[0], x1[1]); w.w = cvt_pk_bf16(x1[2], x1[3]);
;                     *(u32x4*)(XB + ro + bj * 128) = w; }
;                 sq += __shfl_xor(sq, 16); sq += __shfl_xor(sq, 32);
;                 if (fq == 0) SSo[(size_t)(u.pn * 4 + wc) * T + row0 + ai * 128 + m * 16] = sq; }
.LBB0_324:
	s_or_b64 exec, exec, s[34:35]
	v_lshlrev_b32_e32 v32, 16, v128
	s_waitcnt lgkmcnt(0)
	v_and_b32_e32 v33, 0xffff0000, v128
	v_lshlrev_b32_e32 v34, 16, v129
	v_and_b32_e32 v35, 0xffff0000, v129
	v_pk_fma_f32 v[30:31], v[30:31], 0.5, v[34:35] op_sel_hi:[1,0,1]
	v_pk_fma_f32 v[28:29], v[28:29], 0.5, v[32:33] op_sel_hi:[1,0,1]
	v_lshlrev_b32_e32 v32, 16, v130
	v_and_b32_e32 v33, 0xffff0000, v130
	v_lshlrev_b32_e32 v34, 16, v131
	v_and_b32_e32 v35, 0xffff0000, v131
	v_pk_fma_f32 v[34:35], v[26:27], 0.5, v[34:35] op_sel_hi:[1,0,1]
	v_pk_fma_f32 v[26:27], v[24:25], 0.5, v[32:33] op_sel_hi:[1,0,1]
	v_mul_f32_e32 v24, v29, v29
	v_mul_f32_e32 v25, v31, v31
	v_fmac_f32_e32 v24, v28, v28
	v_fmac_f32_e32 v25, v30, v30
	v_add_f32_e32 v24, v24, v25
	v_mul_f32_e32 v25, v27, v27
	v_fmac_f32_e32 v25, v26, v26
	v_add_f32_e32 v24, v25, v24
	v_mul_f32_e32 v25, v35, v35
	v_fmac_f32_e32 v25, v34, v34
	v_add_f32_e32 v32, v25, v24
	v_cvt_pk_bf16_f32 v24, v28, v29
	v_cvt_pk_bf16_f32 v25, v30, v31
	v_lshlrev_b32_e32 v28, 16, v120
	v_and_b32_e32 v29, 0xffff0000, v120
	v_lshlrev_b32_e32 v30, 16, v121
	v_and_b32_e32 v31, 0xffff0000, v121
	v_pk_fma_f32 v[22:23], v[22:23], 0.5, v[30:31] op_sel_hi:[1,0,1]
	v_pk_fma_f32 v[20:21], v[20:21], 0.5, v[28:29] op_sel_hi:[1,0,1]
	v_lshlrev_b32_e32 v28, 16, v122
	v_and_b32_e32 v29, 0xffff0000, v122
	v_pk_fma_f32 v[28:29], v[16:17], 0.5, v[28:29] op_sel_hi:[1,0,1]
	v_mul_f32_e32 v16, v21, v21
	v_mul_f32_e32 v17, v23, v23
	v_fmac_f32_e32 v16, v20, v20
	v_fmac_f32_e32 v17, v22, v22
	v_lshlrev_b32_e32 v30, 16, v123
	v_and_b32_e32 v31, 0xffff0000, v123
	v_add_f32_e32 v16, v16, v17
	v_mul_f32_e32 v17, v29, v29
	v_pk_fma_f32 v[30:31], v[18:19], 0.5, v[30:31] op_sel_hi:[1,0,1]
	v_fmac_f32_e32 v17, v28, v28
	v_add_f32_e32 v16, v17, v16
	v_mul_f32_e32 v17, v31, v31
	v_fmac_f32_e32 v17, v30, v30
	v_add_f32_e32 v16, v17, v16
	v_add_f32_e32 v19, v32, v16
	v_cvt_pk_bf16_f32 v26, v26, v27
	v_cvt_pk_bf16_f32 v27, v34, v35
	v_mov_b32_e32 v34, v19
	s_nop 1
	v_permlane16_swap_b32_e32 v34, v19
	v_lshl_add_u64 v[16:17], s[36:37], 0, v[208:209]
	v_lshl_add_u64 v[32:33], v[204:205], 1, v[16:17]
	global_store_dwordx4 v[32:33], v[24:27], off
	v_cvt_pk_bf16_f32 v18, v20, v21
	s_waitcnt lgkmcnt(0)
	v_add_f32_e32 v16, v19, v34
	v_mov_b32_e32 v17, v16
	s_nop 1
	v_permlane32_swap_b32_e32 v17, v16
	v_cvt_pk_bf16_f32 v19, v22, v23
	v_cvt_pk_bf16_f32 v20, v28, v29
	v_cvt_pk_bf16_f32 v21, v30, v31
	global_store_dwordx4 v[32:33], v[18:21], off offset:256
	s_and_saveexec_b64 s[34:35], s[4:5]
	s_cbranch_execz .LBB0_326
	s_add_u32 s50, s59, s20
	s_addc_u32 s51, s60, s21
	v_lshl_add_u64 v[18:19], v[202:203], 2, s[50:51]
	s_waitcnt lgkmcnt(0)
	v_add_f32_e32 v16, v16, v17
	global_store_dword v[18:19], v16, off offset:640
.LBB0_326:
	s_or_b64 exec, exec, s[34:35]
	v_lshlrev_b32_e32 v16, 16, v108
	s_waitcnt lgkmcnt(0)
	v_and_b32_e32 v17, 0xffff0000, v108
	v_lshlrev_b32_e32 v18, 16, v109
	v_and_b32_e32 v19, 0xffff0000, v109
	v_pk_fma_f32 v[14:15], v[14:15], 0.5, v[18:19] op_sel_hi:[1,0,1]
	v_pk_fma_f32 v[12:13], v[12:13], 0.5, v[16:17] op_sel_hi:[1,0,1]
	v_lshlrev_b32_e32 v16, 16, v110
	v_and_b32_e32 v17, 0xffff0000, v110
	v_lshlrev_b32_e32 v18, 16, v111
	v_and_b32_e32 v19, 0xffff0000, v111
	v_pk_fma_f32 v[18:19], v[10:11], 0.5, v[18:19] op_sel_hi:[1,0,1]
	v_pk_fma_f32 v[10:11], v[8:9], 0.5, v[16:17] op_sel_hi:[1,0,1]
	v_mul_f32_e32 v8, v13, v13
	v_mul_f32_e32 v9, v15, v15
	v_fmac_f32_e32 v8, v12, v12
	v_fmac_f32_e32 v9, v14, v14
	v_add_f32_e32 v8, v8, v9
	v_mul_f32_e32 v9, v11, v11
	v_fmac_f32_e32 v9, v10, v10
	v_add_f32_e32 v8, v9, v8
	v_mul_f32_e32 v9, v19, v19
	v_fmac_f32_e32 v9, v18, v18
	v_add_f32_e32 v16, v9, v8
	v_cvt_pk_bf16_f32 v8, v12, v13
	v_cvt_pk_bf16_f32 v9, v14, v15
	v_lshlrev_b32_e32 v12, 16, v96
	v_and_b32_e32 v13, 0xffff0000, v96
	v_lshlrev_b32_e32 v14, 16, v97
	v_and_b32_e32 v15, 0xffff0000, v97
	v_pk_fma_f32 v[6:7], v[6:7], 0.5, v[14:15] op_sel_hi:[1,0,1]
	v_pk_fma_f32 v[4:5], v[4:5], 0.5, v[12:13] op_sel_hi:[1,0,1]
	v_lshlrev_b32_e32 v12, 16, v98
	v_and_b32_e32 v13, 0xffff0000, v98
	v_pk_fma_f32 v[12:13], v[0:1], 0.5, v[12:13] op_sel_hi:[1,0,1]
	v_mul_f32_e32 v0, v5, v5
	v_mul_f32_e32 v1, v7, v7
	v_fmac_f32_e32 v0, v4, v4
	v_fmac_f32_e32 v1, v6, v6
	v_lshlrev_b32_e32 v14, 16, v99
	v_and_b32_e32 v15, 0xffff0000, v99
	v_add_f32_e32 v0, v0, v1
	v_mul_f32_e32 v1, v13, v13
	v_pk_fma_f32 v[14:15], v[2:3], 0.5, v[14:15] op_sel_hi:[1,0,1]
	v_fmac_f32_e32 v1, v12, v12
	v_add_f32_e32 v0, v1, v0
	v_mul_f32_e32 v1, v15, v15
	v_fmac_f32_e32 v1, v14, v14
	v_add_f32_e32 v0, v1, v0
	v_add_f32_e32 v3, v16, v0
	v_cvt_pk_bf16_f32 v10, v10, v11
	v_cvt_pk_bf16_f32 v11, v18, v19
	v_mov_b32_e32 v18, v3
	s_nop 1
	v_permlane16_swap_b32_e32 v18, v3
	v_lshl_add_u64 v[0:1], s[36:37], 0, v[206:207]
	v_lshl_add_u64 v[16:17], v[204:205], 1, v[0:1]
	global_store_dwordx4 v[16:17], v[8:11], off
	v_cvt_pk_bf16_f32 v2, v4, v5
	s_waitcnt lgkmcnt(0)
	v_add_f32_e32 v0, v3, v18
	v_mov_b32_e32 v1, v0
	s_nop 1
	v_permlane32_swap_b32_e32 v1, v0
	v_cvt_pk_bf16_f32 v3, v6, v7
	v_cvt_pk_bf16_f32 v4, v12, v13
	v_cvt_pk_bf16_f32 v5, v14, v15
	global_store_dwordx4 v[16:17], v[2:5], off offset:256
	s_and_saveexec_b64 s[34:35], s[4:5]
	s_cbranch_execz .LBB0_328
	s_add_u32 s20, s59, s20
	s_addc_u32 s21, s60, s21
	v_lshl_add_u64 v[2:3], v[202:203], 2, s[20:21]
	s_waitcnt lgkmcnt(0)
	v_add_f32_e32 v0, v0, v1
	global_store_dword v[2:3], v0, off offset:704

; __device__ __forceinline__ unsigned cvt_pk_bf16(float lo, float hi) { unsigned r; asm volatile("v_cvt_pk_bf16_f32 %0, %1, %2" : "=v"(r) : "v"(lo), "v"(hi)); return r; }
;     __device__ __forceinline__ void operator()(const f32x4 (&acc)[2][2][4][2], const pg8::Unit& u, int wr, int wc, int fr, int fq) const {
;         const int row0 = u.pm * 256 + wr * 64 + fr, col0 = u.pn * 256 + wc * 32 + 8 * fq;
;         u32x4 xin[2][4][2];
; #pragma unroll
;         for (int ai = 0; ai < 2; ++ai)
; #pragma unroll
;             for (int m = 0; m < 4; ++m)
; #pragma unroll
;                 for (int bj = 0; bj < 2; ++bj) xin[ai][m][bj] = *(const u32x4*)(XB + (size_t)(row0 + ai * 128 + m * 16) * D + col0 + bj * 128);
; #pragma unroll
;         for (int ai = 0; ai < 2; ++ai)
; #pragma unroll
;             for (int m = 0; m < 4; ++m) { const size_t ro = (size_t)(row0 + ai * 128 + m * 16) * D + col0; float sq = 0.f;
; #pragma unroll
;                 for (int bj = 0; bj < 2; ++bj) { const u32x4 xb = xin[ai][m][bj];
;                     const f32x4 x0 = (f32x4){bf_lo(xb.x), bf_hi(xb.x), bf_lo(xb.y), bf_hi(xb.y)} + acc[ai][bj][m][0] * s, x1 = (f32x4){bf_lo(xb.z), bf_hi(xb.z), bf_lo(xb.w), bf_hi(xb.w)} + acc[ai][bj][m][1] * s;
;                     sq += (x0[0] * x0[0] + x0[1] * x0[1]) + (x0[2] * x0[2] + x0[3] * x0[3]) + (x1[0] * x1[0] + x1[1] * x1[1]) + (x1[2] * x1[2] + x1[3] * x1[3]);
;                     u32x4 w; w.x = cvt_pk_bf16(x0[0], x0[1]); w.y = cvt_pk_bf16(x0[2], x0[3]); w.z = cvt_pk_bf16(x1[0], x1[1]); w.w = cvt_pk_bf16(x1[2], x1[3]);
;                     *(u32x4*)(XB + ro + bj * 128) = w; }
;                 sq += __shfl_xor(sq, 16); sq += __shfl_xor(sq, 32);
;                 if (fq == 0) SSo[(size_t)(u.pn * 4 + wc) * T + row0 + ai * 128 + m * 16] = sq; }
.LBB0_708:
	v_lshl_or_b32 v204, s34, 8, v222
	v_lshl_add_u32 v202, s52, 8, v220
	v_ashrrev_i32_e32 v205, 31, v204
	v_lshlrev_b64 v[236:237], 1, v[204:205]
	v_ashrrev_i32_e32 v203, 31, v202
	v_lshl_add_u64 v[96:97], s[36:37], 0, v[236:237]
	v_lshlrev_b64 v[238:239], 11, v[202:203]
	v_lshl_add_u64 v[98:99], v[96:97], 0, v[238:239]
	global_load_dwordx4 v[228:231], v[98:99], off
	global_load_dwordx4 v[232:235], v[98:99], off offset:256
	v_or_b32_e32 v98, 16, v202
	v_or_b32_e32 v108, 32, v202
	v_or_b32_e32 v110, 48, v202
	v_ashrrev_i32_e32 v99, 31, v98
	v_ashrrev_i32_e32 v109, 31, v108
	v_ashrrev_i32_e32 v111, 31, v110
	v_lshlrev_b64 v[218:219], 11, v[98:99]
	v_lshlrev_b64 v[216:217], 11, v[108:109]
	v_lshlrev_b64 v[214:215], 11, v[110:111]
	v_lshl_add_u64 v[212:213], v[238:239], 0, s[8:9]
	v_lshl_add_u64 v[210:211], v[238:239], 0, s[16:17]
	v_lshl_add_u64 v[208:209], v[238:239], 0, s[18:19]
	v_lshl_add_u64 v[206:207], v[238:239], 0, s[38:39]
	v_lshl_add_u64 v[98:99], v[96:97], 0, v[218:219]
	v_lshl_add_u64 v[108:109], v[96:97], 0, v[216:217]
	v_lshl_add_u64 v[110:111], v[96:97], 0, v[214:215]
	v_lshl_add_u64 v[120:121], v[96:97], 0, v[212:213]
	v_lshl_add_u64 v[122:123], v[96:97], 0, v[210:211]
	v_lshl_add_u64 v[240:241], v[96:97], 0, v[208:209]
	v_lshl_add_u64 v[96:97], v[96:97], 0, v[206:207]
	global_load_dwordx4 v[180:183], v[98:99], off
	global_load_dwordx4 v[176:179], v[98:99], off offset:256
	global_load_dwordx4 v[172:175], v[108:109], off
	global_load_dwordx4 v[168:171], v[108:109], off offset:256
	global_load_dwordx4 v[164:167], v[110:111], off
	global_load_dwordx4 v[160:163], v[110:111], off offset:256
	global_load_dwordx4 v[156:159], v[120:121], off
	global_load_dwordx4 v[152:155], v[120:121], off offset:256
	global_load_dwordx4 v[148:151], v[122:123], off
	global_load_dwordx4 v[144:147], v[122:123], off offset:256
	global_load_dwordx4 v[128:131], v[240:241], off
	s_nop 0
	global_load_dwordx4 v[120:123], v[240:241], off offset:256
	global_load_dwordx4 v[108:111], v[96:97], off
	s_nop 0
	global_load_dwordx4 v[96:99], v[96:97], off offset:256
	s_lshl_b32 s20, s34, 2
	s_or_b32 s20, s20, s65
	s_ashr_i32 s21, s20, 31
	s_lshl_b64 s[20:21], s[20:21], 17
	s_waitcnt vmcnt(0)
	v_lshlrev_b32_e32 v240, 16, v228
	v_and_b32_e32 v241, 0xffff0000, v228
	v_lshlrev_b32_e32 v228, 16, v229
	v_and_b32_e32 v229, 0xffff0000, v229
	v_lshlrev_b32_e32 v242, 16, v230
	v_and_b32_e32 v243, 0xffff0000, v230
	v_lshlrev_b32_e32 v244, 16, v232
	v_and_b32_e32 v245, 0xffff0000, v232
	v_lshlrev_b32_e32 v232, 16, v233
	v_and_b32_e32 v233, 0xffff0000, v233
	v_lshlrev_b32_e32 v246, 16, v234
	v_and_b32_e32 v247, 0xffff0000, v234
	v_lshlrev_b32_e32 v234, 16, v235
	v_and_b32_e32 v235, 0xffff0000, v235
	v_pk_add_f32 v[142:143], v[142:143], v[228:229]
	v_pk_add_f32 v[140:141], v[140:141], v[240:241]
	v_lshlrev_b32_e32 v230, 16, v231
	v_and_b32_e32 v231, 0xffff0000, v231
	v_pk_add_f32 v[136:137], v[136:137], v[242:243]
	v_pk_add_f32 v[228:229], v[134:135], v[232:233]
	v_pk_add_f32 v[232:233], v[126:127], v[234:235]
	v_pk_add_f32 v[234:235], v[124:125], v[246:247]
	v_mul_f32_e32 v124, v141, v141
	v_mul_f32_e32 v125, v143, v143
	v_pk_add_f32 v[138:139], v[138:139], v[230:231]
	v_pk_add_f32 v[230:231], v[132:133], v[244:245]
	v_mul_f32_e32 v126, v137, v137
	v_fmac_f32_e32 v124, v140, v140
	v_fmac_f32_e32 v125, v142, v142
	v_mul_f32_e32 v127, v139, v139
	v_cvt_pk_bf16_f32 v132, v140, v141
	v_cvt_pk_bf16_f32 v133, v142, v143
	v_cvt_pk_bf16_f32 v134, v136, v137
	v_cvt_pk_bf16_f32 v135, v138, v139
	v_mul_f32_e32 v137, v231, v231
	v_mul_f32_e32 v139, v229, v229
	v_fmac_f32_e32 v126, v136, v136
	v_add_f32_e32 v124, v124, v125
	v_fmac_f32_e32 v137, v230, v230
	v_fmac_f32_e32 v139, v228, v228
	v_add_f32_e32 v124, v126, v124
	v_mul_f32_e32 v126, v235, v235
	v_add_f32_e32 v125, v137, v139
	v_fmac_f32_e32 v126, v234, v234
	v_add_f32_e32 v125, v126, v125
	v_mul_f32_e32 v126, v233, v233
	v_fmac_f32_e32 v127, v138, v138
	v_fmac_f32_e32 v126, v232, v232
	v_add_f32_e32 v124, v127, v124
	v_add_f32_e32 v125, v126, v125
	v_and_b32_e32 v126, 64, v226
	v_add_f32_e32 v125, v124, v125
	v_add_u32_e32 v138, 64, v126
	v_lshl_add_u64 v[126:127], s[36:37], 0, v[238:239]
	v_lshl_add_u64 v[136:137], v[126:127], 0, v[236:237]
	v_mov_b32_e32 v139, v125
	s_nop 1
	v_permlane16_swap_b32_e32 v139, v125
	global_store_dwordx4 v[136:137], v[132:135], off
	s_waitcnt lgkmcnt(0)
	v_add_f32_e32 v126, v125, v139
	v_cvt_pk_bf16_f32 v132, v230, v231
	v_cvt_pk_bf16_f32 v133, v228, v229
	v_cvt_pk_bf16_f32 v134, v234, v235
	v_cvt_pk_bf16_f32 v135, v232, v233
	global_store_dwordx4 v[136:137], v[132:135], off offset:256
	s_nop 0
	v_mov_b32_e32 v127, v126
	s_nop 1
	v_permlane32_swap_b32_e32 v127, v126
	s_and_saveexec_b64 s[34:35], s[4:5]
	s_cbranch_execz .LBB0_710
	s_add_u32 s54, s63, s20
	s_addc_u32 s55, s64, s21
	v_lshl_add_u64 v[132:133], v[202:203], 2, s[54:55]
	s_waitcnt lgkmcnt(0)
	v_add_f32_e32 v126, v126, v127
	global_store_dword v[132:133], v126, off
; __device__ __forceinline__ unsigned cvt_pk_bf16(float lo, float hi) { unsigned r; asm volatile("v_cvt_pk_bf16_f32 %0, %1, %2" : "=v"(r) : "v"(lo), "v"(hi)); return r; }
;     __device__ __forceinline__ void operator()(const f32x4 (&acc)[2][2][4][2], const pg8::Unit& u, int wr, int wc, int fr, int fq) const {
;     ...
;             for (int m = 0; m < 4; ++m) { const size_t ro = (size_t)(row0 + ai * 128 + m * 16) * D + col0; float sq = 0.f;
; #pragma unroll
;                 for (int bj = 0; bj < 2; ++bj) { const u32x4 xb = xin[ai][m][bj];
;                     const f32x4 x0 = (f32x4){bf_lo(xb.x), bf_hi(xb.x), bf_lo(xb.y), bf_hi(xb.y)} + acc[ai][bj][m][0] * s, x1 = (f32x4){bf_lo(xb.z), bf_hi(xb.z), bf_lo(xb.w), bf_hi(xb.w)} + acc[ai][bj][m][1] * s;
;                     sq += (x0[0] * x0[0] + x0[1] * x0[1]) + (x0[2] * x0[2] + x0[3] * x0[3]) + (x1[0] * x1[0] + x1[1] * x1[1]) + (x1[2] * x1[2] + x1[3] * x1[3]);
;                     u32x4 w; w.x = cvt_pk_bf16(x0[0], x0[1]); w.y = cvt_pk_bf16(x0[2], x0[3]); w.z = cvt_pk_bf16(x1[0], x1[1]); w.w = cvt_pk_bf16(x1[2], x1[3]);
;                     *(u32x4*)(XB + ro + bj * 128) = w; }
;                 sq += __shfl_xor(sq, 16); sq += __shfl_xor(sq, 32);
;                 if (fq == 0) SSo[(size_t)(u.pn * 4 + wc) * T + row0 + ai * 128 + m * 16] = sq; }
.LBB0_710:
	s_or_b64 exec, exec, s[34:35]
	v_lshlrev_b32_e32 v126, 16, v180
	s_waitcnt lgkmcnt(0)
	v_and_b32_e32 v127, 0xffff0000, v180
	v_lshlrev_b32_e32 v132, 16, v181
	v_and_b32_e32 v133, 0xffff0000, v181
	v_pk_add_f32 v[118:119], v[118:119], v[132:133]
	v_pk_add_f32 v[116:117], v[116:117], v[126:127]
	v_lshlrev_b32_e32 v126, 16, v182
	v_and_b32_e32 v127, 0xffff0000, v182
	v_lshlrev_b32_e32 v132, 16, v183
	v_and_b32_e32 v133, 0xffff0000, v183
	v_pk_add_f32 v[132:133], v[114:115], v[132:133]
	v_pk_add_f32 v[114:115], v[112:113], v[126:127]
	v_mul_f32_e32 v112, v117, v117
	v_mul_f32_e32 v113, v119, v119
	v_fmac_f32_e32 v112, v116, v116
	v_fmac_f32_e32 v113, v118, v118
	v_add_f32_e32 v112, v112, v113
	v_mul_f32_e32 v113, v115, v115
	v_fmac_f32_e32 v113, v114, v114
	v_add_f32_e32 v112, v113, v112
	v_mul_f32_e32 v113, v133, v133
	v_fmac_f32_e32 v113, v132, v132
	v_add_f32_e32 v126, v113, v112
	v_cvt_pk_bf16_f32 v112, v116, v117
	v_cvt_pk_bf16_f32 v113, v118, v119
	v_lshlrev_b32_e32 v116, 16, v176
	v_and_b32_e32 v117, 0xffff0000, v176
	v_lshlrev_b32_e32 v118, 16, v177
	v_and_b32_e32 v119, 0xffff0000, v177
	v_pk_add_f32 v[106:107], v[106:107], v[118:119]
	v_pk_add_f32 v[104:105], v[104:105], v[116:117]
	v_lshlrev_b32_e32 v116, 16, v178
	v_and_b32_e32 v117, 0xffff0000, v178
	v_pk_add_f32 v[116:117], v[100:101], v[116:117]
	v_mul_f32_e32 v100, v105, v105
	v_mul_f32_e32 v101, v107, v107
	v_fmac_f32_e32 v100, v104, v104
	v_fmac_f32_e32 v101, v106, v106
	v_lshlrev_b32_e32 v118, 16, v179
	v_and_b32_e32 v119, 0xffff0000, v179
	v_add_f32_e32 v100, v100, v101
	v_mul_f32_e32 v101, v117, v117
	v_pk_add_f32 v[118:119], v[102:103], v[118:119]
	v_fmac_f32_e32 v101, v116, v116
	v_add_f32_e32 v100, v101, v100
	v_mul_f32_e32 v101, v119, v119
	v_fmac_f32_e32 v101, v118, v118
	v_add_f32_e32 v100, v101, v100
	v_add_f32_e32 v103, v126, v100
	v_cvt_pk_bf16_f32 v114, v114, v115
	v_cvt_pk_bf16_f32 v115, v132, v133
	v_mov_b32_e32 v132, v103
	s_nop 1
	v_permlane16_swap_b32_e32 v132, v103
	v_lshl_add_u64 v[100:101], s[36:37], 0, v[218:219]
	v_lshl_add_u64 v[126:127], v[204:205], 1, v[100:101]
	global_store_dwordx4 v[126:127], v[112:115], off
	v_cvt_pk_bf16_f32 v102, v104, v105
	s_waitcnt lgkmcnt(0)
	v_add_f32_e32 v100, v103, v132
	v_mov_b32_e32 v101, v100
	s_nop 1
	v_permlane32_swap_b32_e32 v101, v100
	v_cvt_pk_bf16_f32 v103, v106, v107
	v_cvt_pk_bf16_f32 v104, v116, v117
	v_cvt_pk_bf16_f32 v105, v118, v119
	global_store_dwordx4 v[126:127], v[102:105], off offset:256
	s_and_saveexec_b64 s[34:35], s[4:5]
	s_cbranch_execz .LBB0_712
	s_add_u32 s54, s63, s20
	s_addc_u32 s55, s64, s21
	v_lshl_add_u64 v[102:103], v[202:203], 2, s[54:55]
	s_waitcnt lgkmcnt(0)
	v_add_f32_e32 v100, v100, v101
	global_store_dword v[102:103], v100, off offset:64
.LBB0_712:
	s_or_b64 exec, exec, s[34:35]
	v_lshlrev_b32_e32 v100, 16, v172
	s_waitcnt lgkmcnt(0)
	v_and_b32_e32 v101, 0xffff0000, v172
	v_lshlrev_b32_e32 v102, 16, v173
	v_and_b32_e32 v103, 0xffff0000, v173
	v_pk_add_f32 v[94:95], v[94:95], v[102:103]
	v_pk_add_f32 v[92:93], v[92:93], v[100:101]
	v_lshlrev_b32_e32 v100, 16, v174
	v_and_b32_e32 v101, 0xffff0000, v174
	v_lshlrev_b32_e32 v102, 16, v175
	v_and_b32_e32 v103, 0xffff0000, v175
	v_pk_add_f32 v[102:103], v[90:91], v[102:103]
	v_pk_add_f32 v[90:91], v[88:89], v[100:101]
	v_mul_f32_e32 v88, v93, v93
	v_mul_f32_e32 v89, v95, v95
	v_fmac_f32_e32 v88, v92, v92
	v_fmac_f32_e32 v89, v94, v94
	v_add_f32_e32 v88, v88, v89
	v_mul_f32_e32 v89, v91, v91
	v_fmac_f32_e32 v89, v90, v90
	v_add_f32_e32 v88, v89, v88
	v_mul_f32_e32 v89, v103, v103
	v_fmac_f32_e32 v89, v102, v102
	v_add_f32_e32 v100, v89, v88
	v_cvt_pk_bf16_f32 v88, v92, v93
	v_cvt_pk_bf16_f32 v89, v94, v95
	v_lshlrev_b32_e32 v92, 16, v168
	v_and_b32_e32 v93, 0xffff0000, v168
	v_lshlrev_b32_e32 v94, 16, v169
	v_and_b32_e32 v95, 0xffff0000, v169
	v_pk_add_f32 v[86:87], v[86:87], v[94:95]
	v_pk_add_f32 v[84:85], v[84:85], v[92:93]
	v_lshlrev_b32_e32 v92, 16, v170
	v_and_b32_e32 v93, 0xffff0000, v170
	v_pk_add_f32 v[92:93], v[80:81], v[92:93]
	v_mul_f32_e32 v80, v85, v85
	v_mul_f32_e32 v81, v87, v87
	v_fmac_f32_e32 v80, v84, v84
	v_fmac_f32_e32 v81, v86, v86
	v_lshlrev_b32_e32 v94, 16, v171
	v_and_b32_e32 v95, 0xffff0000, v171
	v_add_f32_e32 v80, v80, v81
	v_mul_f32_e32 v81, v93, v93
	v_pk_add_f32 v[94:95], v[82:83], v[94:95]
	v_fmac_f32_e32 v81, v92, v92
	v_add_f32_e32 v80, v81, v80
	v_mul_f32_e32 v81, v95, v95
	v_fmac_f32_e32 v81, v94, v94
	v_add_f32_e32 v80, v81, v80
	v_add_f32_e32 v83, v100, v80
	v_cvt_pk_bf16_f32 v90, v90, v91
	v_cvt_pk_bf16_f32 v91, v102, v103
	v_mov_b32_e32 v102, v83
	s_nop 1
	v_permlane16_swap_b32_e32 v102, v83
	v_lshl_add_u64 v[80:81], s[36:37], 0, v[216:217]
	v_lshl_add_u64 v[100:101], v[204:205], 1, v[80:81]
	global_store_dwordx4 v[100:101], v[88:91], off
	v_cvt_pk_bf16_f32 v82, v84, v85
	s_waitcnt lgkmcnt(0)
	v_add_f32_e32 v80, v83, v102
	v_mov_b32_e32 v81, v80
	s_nop 1
	v_permlane32_swap_b32_e32 v81, v80
	v_cvt_pk_bf16_f32 v83, v86, v87
	v_cvt_pk_bf16_f32 v84, v92, v93
	v_cvt_pk_bf16_f32 v85, v94, v95
	global_store_dwordx4 v[100:101], v[82:85], off offset:256
	s_and_saveexec_b64 s[34:35], s[4:5]
	s_cbranch_execz .LBB0_714
	s_add_u32 s54, s63, s20
	s_addc_u32 s55, s64, s21
	v_lshl_add_u64 v[82:83], v[202:203], 2, s[54:55]
	s_waitcnt lgkmcnt(0)
	v_add_f32_e32 v80, v80, v81
	global_store_dword v[82:83], v80, off offset:128
; __device__ __forceinline__ unsigned cvt_pk_bf16(float lo, float hi) { unsigned r; asm volatile("v_cvt_pk_bf16_f32 %0, %1, %2" : "=v"(r) : "v"(lo), "v"(hi)); return r; }
;     __device__ __forceinline__ void operator()(const f32x4 (&acc)[2][2][4][2], const pg8::Unit& u, int wr, int wc, int fr, int fq) const {
;     ...
;             for (int m = 0; m < 4; ++m) { const size_t ro = (size_t)(row0 + ai * 128 + m * 16) * D + col0; float sq = 0.f;
; #pragma unroll
;                 for (int bj = 0; bj < 2; ++bj) { const u32x4 xb = xin[ai][m][bj];
;                     const f32x4 x0 = (f32x4){bf_lo(xb.x), bf_hi(xb.x), bf_lo(xb.y), bf_hi(xb.y)} + acc[ai][bj][m][0] * s, x1 = (f32x4){bf_lo(xb.z), bf_hi(xb.z), bf_lo(xb.w), bf_hi(xb.w)} + acc[ai][bj][m][1] * s;
;                     sq += (x0[0] * x0[0] + x0[1] * x0[1]) + (x0[2] * x0[2] + x0[3] * x0[3]) + (x1[0] * x1[0] + x1[1] * x1[1]) + (x1[2] * x1[2] + x1[3] * x1[3]);
;                     u32x4 w; w.x = cvt_pk_bf16(x0[0], x0[1]); w.y = cvt_pk_bf16(x0[2], x0[3]); w.z = cvt_pk_bf16(x1[0], x1[1]); w.w = cvt_pk_bf16(x1[2], x1[3]);
;                     *(u32x4*)(XB + ro + bj * 128) = w; }
;                 sq += __shfl_xor(sq, 16); sq += __shfl_xor(sq, 32);
;                 if (fq == 0) SSo[(size_t)(u.pn * 4 + wc) * T + row0 + ai * 128 + m * 16] = sq; }
.LBB0_714:
	s_or_b64 exec, exec, s[34:35]
	v_lshlrev_b32_e32 v80, 16, v164
	s_waitcnt lgkmcnt(0)
	v_and_b32_e32 v81, 0xffff0000, v164
	v_lshlrev_b32_e32 v82, 16, v165
	v_and_b32_e32 v83, 0xffff0000, v165
	v_pk_add_f32 v[78:79], v[78:79], v[82:83]
	v_pk_add_f32 v[76:77], v[76:77], v[80:81]
	v_lshlrev_b32_e32 v80, 16, v166
	v_and_b32_e32 v81, 0xffff0000, v166
	v_lshlrev_b32_e32 v82, 16, v167
	v_and_b32_e32 v83, 0xffff0000, v167
	v_pk_add_f32 v[82:83], v[74:75], v[82:83]
	v_pk_add_f32 v[74:75], v[72:73], v[80:81]
	v_mul_f32_e32 v72, v77, v77
	v_mul_f32_e32 v73, v79, v79
	v_fmac_f32_e32 v72, v76, v76
	v_fmac_f32_e32 v73, v78, v78
	v_add_f32_e32 v72, v72, v73
	v_mul_f32_e32 v73, v75, v75
	v_fmac_f32_e32 v73, v74, v74
	v_add_f32_e32 v72, v73, v72
	v_mul_f32_e32 v73, v83, v83
	v_fmac_f32_e32 v73, v82, v82
	v_add_f32_e32 v80, v73, v72
	v_cvt_pk_bf16_f32 v72, v76, v77
	v_cvt_pk_bf16_f32 v73, v78, v79
	v_lshlrev_b32_e32 v76, 16, v160
	v_and_b32_e32 v77, 0xffff0000, v160
	v_lshlrev_b32_e32 v78, 16, v161
	v_and_b32_e32 v79, 0xffff0000, v161
	v_pk_add_f32 v[70:71], v[70:71], v[78:79]
	v_pk_add_f32 v[68:69], v[68:69], v[76:77]
	v_lshlrev_b32_e32 v76, 16, v162
	v_and_b32_e32 v77, 0xffff0000, v162
	v_pk_add_f32 v[76:77], v[64:65], v[76:77]
	v_mul_f32_e32 v64, v69, v69
	v_mul_f32_e32 v65, v71, v71
	v_fmac_f32_e32 v64, v68, v68
	v_fmac_f32_e32 v65, v70, v70
	v_lshlrev_b32_e32 v78, 16, v163
	v_and_b32_e32 v79, 0xffff0000, v163
	v_add_f32_e32 v64, v64, v65
	v_mul_f32_e32 v65, v77, v77
	v_pk_add_f32 v[78:79], v[66:67], v[78:79]
	v_fmac_f32_e32 v65, v76, v76
	v_add_f32_e32 v64, v65, v64
	v_mul_f32_e32 v65, v79, v79
	v_fmac_f32_e32 v65, v78, v78
	v_add_f32_e32 v64, v65, v64
	v_add_f32_e32 v67, v80, v64
	v_cvt_pk_bf16_f32 v74, v74, v75
	v_cvt_pk_bf16_f32 v75, v82, v83
	v_mov_b32_e32 v82, v67
	s_nop 1
	v_permlane16_swap_b32_e32 v82, v67
	v_lshl_add_u64 v[64:65], s[36:37], 0, v[214:215]
	v_lshl_add_u64 v[80:81], v[204:205], 1, v[64:65]
	global_store_dwordx4 v[80:81], v[72:75], off
	v_cvt_pk_bf16_f32 v66, v68, v69
	s_waitcnt lgkmcnt(0)
	v_add_f32_e32 v64, v67, v82
	v_mov_b32_e32 v65, v64
	s_nop 1
	v_permlane32_swap_b32_e32 v65, v64
	v_cvt_pk_bf16_f32 v67, v70, v71
	v_cvt_pk_bf16_f32 v68, v76, v77
	v_cvt_pk_bf16_f32 v69, v78, v79
	global_store_dwordx4 v[80:81], v[66:69], off offset:256
	s_and_saveexec_b64 s[34:35], s[4:5]
	s_cbranch_execz .LBB0_716
	s_add_u32 s54, s63, s20
	s_addc_u32 s55, s64, s21
	v_lshl_add_u64 v[66:67], v[202:203], 2, s[54:55]
	s_waitcnt lgkmcnt(0)
	v_add_f32_e32 v64, v64, v65
	global_store_dword v[66:67], v64, off offset:192
.LBB0_716:
	s_or_b64 exec, exec, s[34:35]
	v_lshlrev_b32_e32 v64, 16, v156
	s_waitcnt lgkmcnt(0)
	v_and_b32_e32 v65, 0xffff0000, v156
	v_lshlrev_b32_e32 v66, 16, v157
	v_and_b32_e32 v67, 0xffff0000, v157
	v_pk_add_f32 v[62:63], v[62:63], v[66:67]
	v_pk_add_f32 v[60:61], v[60:61], v[64:65]
	v_lshlrev_b32_e32 v64, 16, v158
	v_and_b32_e32 v65, 0xffff0000, v158
	v_lshlrev_b32_e32 v66, 16, v159
	v_and_b32_e32 v67, 0xffff0000, v159
	v_pk_add_f32 v[66:67], v[58:59], v[66:67]
	v_pk_add_f32 v[58:59], v[56:57], v[64:65]
	v_mul_f32_e32 v56, v61, v61
	v_mul_f32_e32 v57, v63, v63
	v_fmac_f32_e32 v56, v60, v60
	v_fmac_f32_e32 v57, v62, v62
	v_add_f32_e32 v56, v56, v57
	v_mul_f32_e32 v57, v59, v59
	v_fmac_f32_e32 v57, v58, v58
	v_add_f32_e32 v56, v57, v56
	v_mul_f32_e32 v57, v67, v67
	v_fmac_f32_e32 v57, v66, v66
	v_add_f32_e32 v64, v57, v56
	v_cvt_pk_bf16_f32 v56, v60, v61
	v_cvt_pk_bf16_f32 v57, v62, v63
	v_lshlrev_b32_e32 v60, 16, v152
	v_and_b32_e32 v61, 0xffff0000, v152
	v_lshlrev_b32_e32 v62, 16, v153
	v_and_b32_e32 v63, 0xffff0000, v153
	v_pk_add_f32 v[54:55], v[54:55], v[62:63]
	v_pk_add_f32 v[52:53], v[52:53], v[60:61]
	v_lshlrev_b32_e32 v60, 16, v154
	v_and_b32_e32 v61, 0xffff0000, v154
	v_pk_add_f32 v[60:61], v[48:49], v[60:61]
	v_mul_f32_e32 v48, v53, v53
	v_mul_f32_e32 v49, v55, v55
	v_fmac_f32_e32 v48, v52, v52
	v_fmac_f32_e32 v49, v54, v54
	v_lshlrev_b32_e32 v62, 16, v155
	v_and_b32_e32 v63, 0xffff0000, v155
	v_add_f32_e32 v48, v48, v49
	v_mul_f32_e32 v49, v61, v61
	v_pk_add_f32 v[62:63], v[50:51], v[62:63]
	v_fmac_f32_e32 v49, v60, v60
	v_add_f32_e32 v48, v49, v48
	v_mul_f32_e32 v49, v63, v63
	v_fmac_f32_e32 v49, v62, v62
	v_add_f32_e32 v48, v49, v48
	v_add_f32_e32 v51, v64, v48
	v_cvt_pk_bf16_f32 v58, v58, v59
	v_cvt_pk_bf16_f32 v59, v66, v67
	v_mov_b32_e32 v66, v51
	s_nop 1
	v_permlane16_swap_b32_e32 v66, v51
	v_lshl_add_u64 v[48:49], s[36:37], 0, v[212:213]
	v_lshl_add_u64 v[64:65], v[204:205], 1, v[48:49]
	global_store_dwordx4 v[64:65], v[56:59], off
	v_cvt_pk_bf16_f32 v50, v52, v53
	s_waitcnt lgkmcnt(0)
	v_add_f32_e32 v48, v51, v66
	v_mov_b32_e32 v49, v48
	s_nop 1
	v_permlane32_swap_b32_e32 v49, v48
	v_cvt_pk_bf16_f32 v51, v54, v55
	v_cvt_pk_bf16_f32 v52, v60, v61
	v_cvt_pk_bf16_f32 v53, v62, v63
	global_store_dwordx4 v[64:65], v[50:53], off offset:256
	s_and_saveexec_b64 s[34:35], s[4:5]
	s_cbranch_execz .LBB0_718
	s_add_u32 s54, s63, s20
	s_addc_u32 s55, s64, s21
	v_lshl_add_u64 v[50:51], v[202:203], 2, s[54:55]
	s_waitcnt lgkmcnt(0)
	v_add_f32_e32 v48, v48, v49
	global_store_dword v[50:51], v48, off offset:512
; __device__ __forceinline__ unsigned cvt_pk_bf16(float lo, float hi) { unsigned r; asm volatile("v_cvt_pk_bf16_f32 %0, %1, %2" : "=v"(r) : "v"(lo), "v"(hi)); return r; }
;     __device__ __forceinline__ void operator()(const f32x4 (&acc)[2][2][4][2], const pg8::Unit& u, int wr, int wc, int fr, int fq) const {
;     ...
;             for (int m = 0; m < 4; ++m) { const size_t ro = (size_t)(row0 + ai * 128 + m * 16) * D + col0; float sq = 0.f;
; #pragma unroll
;                 for (int bj = 0; bj < 2; ++bj) { const u32x4 xb = xin[ai][m][bj];
;                     const f32x4 x0 = (f32x4){bf_lo(xb.x), bf_hi(xb.x), bf_lo(xb.y), bf_hi(xb.y)} + acc[ai][bj][m][0] * s, x1 = (f32x4){bf_lo(xb.z), bf_hi(xb.z), bf_lo(xb.w), bf_hi(xb.w)} + acc[ai][bj][m][1] * s;
;                     sq += (x0[0] * x0[0] + x0[1] * x0[1]) + (x0[2] * x0[2] + x0[3] * x0[3]) + (x1[0] * x1[0] + x1[1] * x1[1]) + (x1[2] * x1[2] + x1[3] * x1[3]);
;                     u32x4 w; w.x = cvt_pk_bf16(x0[0], x0[1]); w.y = cvt_pk_bf16(x0[2], x0[3]); w.z = cvt_pk_bf16(x1[0], x1[1]); w.w = cvt_pk_bf16(x1[2], x1[3]);
;                     *(u32x4*)(XB + ro + bj * 128) = w; }
;                 sq += __shfl_xor(sq, 16); sq += __shfl_xor(sq, 32);
;                 if (fq == 0) SSo[(size_t)(u.pn * 4 + wc) * T + row0 + ai * 128 + m * 16] = sq; }
.LBB0_718:
	s_or_b64 exec, exec, s[34:35]
	v_lshlrev_b32_e32 v48, 16, v148
	s_waitcnt lgkmcnt(0)
	v_and_b32_e32 v49, 0xffff0000, v148
	v_lshlrev_b32_e32 v50, 16, v149
	v_and_b32_e32 v51, 0xffff0000, v149
	v_pk_add_f32 v[46:47], v[46:47], v[50:51]
	v_pk_add_f32 v[44:45], v[44:45], v[48:49]
	v_lshlrev_b32_e32 v48, 16, v150
	v_and_b32_e32 v49, 0xffff0000, v150
	v_lshlrev_b32_e32 v50, 16, v151
	v_and_b32_e32 v51, 0xffff0000, v151
	v_pk_add_f32 v[50:51], v[42:43], v[50:51]
	v_pk_add_f32 v[42:43], v[40:41], v[48:49]
	v_mul_f32_e32 v40, v45, v45
	v_mul_f32_e32 v41, v47, v47
	v_fmac_f32_e32 v40, v44, v44
	v_fmac_f32_e32 v41, v46, v46
	v_add_f32_e32 v40, v40, v41
	v_mul_f32_e32 v41, v43, v43
	v_fmac_f32_e32 v41, v42, v42
	v_add_f32_e32 v40, v41, v40
	v_mul_f32_e32 v41, v51, v51
	v_fmac_f32_e32 v41, v50, v50
	v_add_f32_e32 v48, v41, v40
	v_cvt_pk_bf16_f32 v40, v44, v45
	v_cvt_pk_bf16_f32 v41, v46, v47
	v_lshlrev_b32_e32 v44, 16, v144
	v_and_b32_e32 v45, 0xffff0000, v144
	v_lshlrev_b32_e32 v46, 16, v145
	v_and_b32_e32 v47, 0xffff0000, v145
	v_pk_add_f32 v[38:39], v[38:39], v[46:47]
	v_pk_add_f32 v[36:37], v[36:37], v[44:45]
	v_lshlrev_b32_e32 v44, 16, v146
	v_and_b32_e32 v45, 0xffff0000, v146
	v_pk_add_f32 v[44:45], v[32:33], v[44:45]
	v_mul_f32_e32 v32, v37, v37
	v_mul_f32_e32 v33, v39, v39
	v_fmac_f32_e32 v32, v36, v36
	v_fmac_f32_e32 v33, v38, v38
	v_lshlrev_b32_e32 v46, 16, v147
	v_and_b32_e32 v47, 0xffff0000, v147
	v_add_f32_e32 v32, v32, v33
	v_mul_f32_e32 v33, v45, v45
	v_pk_add_f32 v[46:47], v[34:35], v[46:47]
	v_fmac_f32_e32 v33, v44, v44
	v_add_f32_e32 v32, v33, v32
	v_mul_f32_e32 v33, v47, v47
	v_fmac_f32_e32 v33, v46, v46
	v_add_f32_e32 v32, v33, v32
	v_add_f32_e32 v35, v48, v32
	v_cvt_pk_bf16_f32 v42, v42, v43
	v_cvt_pk_bf16_f32 v43, v50, v51
	v_mov_b32_e32 v50, v35
	s_nop 1
	v_permlane16_swap_b32_e32 v50, v35
	v_lshl_add_u64 v[32:33], s[36:37], 0, v[210:211]
	v_lshl_add_u64 v[48:49], v[204:205], 1, v[32:33]
	global_store_dwordx4 v[48:49], v[40:43], off
	v_cvt_pk_bf16_f32 v34, v36, v37
	s_waitcnt lgkmcnt(0)
	v_add_f32_e32 v32, v35, v50
	v_mov_b32_e32 v33, v32
	s_nop 1
	v_permlane32_swap_b32_e32 v33, v32
	v_cvt_pk_bf16_f32 v35, v38, v39
	v_cvt_pk_bf16_f32 v36, v44, v45
	v_cvt_pk_bf16_f32 v37, v46, v47
	global_store_dwordx4 v[48:49], v[34:37], off offset:256
	s_and_saveexec_b64 s[34:35], s[4:5]
	s_cbranch_execz .LBB0_720
	s_add_u32 s54, s63, s20
	s_addc_u32 s55, s64, s21
	v_lshl_add_u64 v[34:35], v[202:203], 2, s[54:55]
	s_waitcnt lgkmcnt(0)
	v_add_f32_e32 v32, v32, v33
	global_store_dword v[34:35], v32, off offset:576
; __device__ __forceinline__ unsigned cvt_pk_bf16(float lo, float hi) { unsigned r; asm volatile("v_cvt_pk_bf16_f32 %0, %1, %2" : "=v"(r) : "v"(lo), "v"(hi)); return r; }
;     __device__ __forceinline__ void operator()(const f32x4 (&acc)[2][2][4][2], const pg8::Unit& u, int wr, int wc, int fr, int fq) const {
;     ...
;             for (int m = 0; m < 4; ++m) { const size_t ro = (size_t)(row0 + ai * 128 + m * 16) * D + col0; float sq = 0.f;
; #pragma unroll
;                 for (int bj = 0; bj < 2; ++bj) { const u32x4 xb = xin[ai][m][bj];
;                     const f32x4 x0 = (f32x4){bf_lo(xb.x), bf_hi(xb.x), bf_lo(xb.y), bf_hi(xb.y)} + acc[ai][bj][m][0] * s, x1 = (f32x4){bf_lo(xb.z), bf_hi(xb.z), bf_lo(xb.w), bf_hi(xb.w)} + acc[ai][bj][m][1] * s;
;                     sq += (x0[0] * x0[0] + x0[1] * x0[1]) + (x0[2] * x0[2] + x0[3] * x0[3]) + (x1[0] * x1[0] + x1[1] * x1[1]) + (x1[2] * x1[2] + x1[3] * x1[3]);
;                     u32x4 w; w.x = cvt_pk_bf16(x0[0], x0[1]); w.y = cvt_pk_bf16(x0[2], x0[3]); w.z = cvt_pk_bf16(x1[0], x1[1]); w.w = cvt_pk_bf16(x1[2], x1[3]);
;                     *(u32x4*)(XB + ro + bj * 128) = w; }
;                 sq += __shfl_xor(sq, 16); sq += __shfl_xor(sq, 32);
;                 if (fq == 0) SSo[(size_t)(u.pn * 4 + wc) * T + row0 + ai * 128 + m * 16] = sq; }
.LBB0_720:
	s_or_b64 exec, exec, s[34:35]
	v_lshlrev_b32_e32 v32, 16, v128
	s_waitcnt lgkmcnt(0)
	v_and_b32_e32 v33, 0xffff0000, v128
	v_lshlrev_b32_e32 v34, 16, v129
	v_and_b32_e32 v35, 0xffff0000, v129
	v_pk_add_f32 v[30:31], v[30:31], v[34:35]
	v_pk_add_f32 v[28:29], v[28:29], v[32:33]
	v_lshlrev_b32_e32 v32, 16, v130
	v_and_b32_e32 v33, 0xffff0000, v130
	v_lshlrev_b32_e32 v34, 16, v131
	v_and_b32_e32 v35, 0xffff0000, v131
	v_pk_add_f32 v[34:35], v[26:27], v[34:35]
	v_pk_add_f32 v[26:27], v[24:25], v[32:33]
	v_mul_f32_e32 v24, v29, v29
	v_mul_f32_e32 v25, v31, v31
	v_fmac_f32_e32 v24, v28, v28
	v_fmac_f32_e32 v25, v30, v30
	v_add_f32_e32 v24, v24, v25
	v_mul_f32_e32 v25, v27, v27
	v_fmac_f32_e32 v25, v26, v26
	v_add_f32_e32 v24, v25, v24
	v_mul_f32_e32 v25, v35, v35
	v_fmac_f32_e32 v25, v34, v34
	v_add_f32_e32 v32, v25, v24
	v_cvt_pk_bf16_f32 v24, v28, v29
	v_cvt_pk_bf16_f32 v25, v30, v31
	v_lshlrev_b32_e32 v28, 16, v120
	v_and_b32_e32 v29, 0xffff0000, v120
	v_lshlrev_b32_e32 v30, 16, v121
	v_and_b32_e32 v31, 0xffff0000, v121
	v_pk_add_f32 v[22:23], v[22:23], v[30:31]
	v_pk_add_f32 v[20:21], v[20:21], v[28:29]
	v_lshlrev_b32_e32 v28, 16, v122
	v_and_b32_e32 v29, 0xffff0000, v122
	v_pk_add_f32 v[28:29], v[16:17], v[28:29]
	v_mul_f32_e32 v16, v21, v21
	v_mul_f32_e32 v17, v23, v23
	v_fmac_f32_e32 v16, v20, v20
	v_fmac_f32_e32 v17, v22, v22
	v_lshlrev_b32_e32 v30, 16, v123
	v_and_b32_e32 v31, 0xffff0000, v123
	v_add_f32_e32 v16, v16, v17
	v_mul_f32_e32 v17, v29, v29
	v_pk_add_f32 v[30:31], v[18:19], v[30:31]
	v_fmac_f32_e32 v17, v28, v28
	v_add_f32_e32 v16, v17, v16
	v_mul_f32_e32 v17, v31, v31
	v_fmac_f32_e32 v17, v30, v30
	v_add_f32_e32 v16, v17, v16
	v_add_f32_e32 v19, v32, v16
	v_cvt_pk_bf16_f32 v26, v26, v27
	v_cvt_pk_bf16_f32 v27, v34, v35
	v_mov_b32_e32 v34, v19
	s_nop 1
	v_permlane16_swap_b32_e32 v34, v19
	v_lshl_add_u64 v[16:17], s[36:37], 0, v[208:209]
	v_lshl_add_u64 v[32:33], v[204:205], 1, v[16:17]
	global_store_dwordx4 v[32:33], v[24:27], off
	v_cvt_pk_bf16_f32 v18, v20, v21
	s_waitcnt lgkmcnt(0)
	v_add_f32_e32 v16, v19, v34
	v_mov_b32_e32 v17, v16
	s_nop 1
	v_permlane32_swap_b32_e32 v17, v16
	v_cvt_pk_bf16_f32 v19, v22, v23
	v_cvt_pk_bf16_f32 v20, v28, v29
	v_cvt_pk_bf16_f32 v21, v30, v31
	global_store_dwordx4 v[32:33], v[18:21], off offset:256
	s_and_saveexec_b64 s[34:35], s[4:5]
	s_cbranch_execz .LBB0_722
	s_add_u32 s54, s63, s20
	s_addc_u32 s55, s64, s21
	v_lshl_add_u64 v[18:19], v[202:203], 2, s[54:55]
	s_waitcnt lgkmcnt(0)
	v_add_f32_e32 v16, v16, v17
	global_store_dword v[18:19], v16, off offset:640
.LBB0_722:
	s_or_b64 exec, exec, s[34:35]
	v_lshlrev_b32_e32 v16, 16, v108
	s_waitcnt lgkmcnt(0)
	v_and_b32_e32 v17, 0xffff0000, v108
	v_lshlrev_b32_e32 v18, 16, v109
	v_and_b32_e32 v19, 0xffff0000, v109
	v_pk_add_f32 v[14:15], v[14:15], v[18:19]
	v_pk_add_f32 v[12:13], v[12:13], v[16:17]
	v_lshlrev_b32_e32 v16, 16, v110
	v_and_b32_e32 v17, 0xffff0000, v110
	v_lshlrev_b32_e32 v18, 16, v111
	v_and_b32_e32 v19, 0xffff0000, v111
	v_pk_add_f32 v[18:19], v[10:11], v[18:19]
	v_pk_add_f32 v[10:11], v[8:9], v[16:17]
	v_mul_f32_e32 v8, v13, v13
	v_mul_f32_e32 v9, v15, v15
	v_fmac_f32_e32 v8, v12, v12
	v_fmac_f32_e32 v9, v14, v14
	v_add_f32_e32 v8, v8, v9
	v_mul_f32_e32 v9, v11, v11
	v_fmac_f32_e32 v9, v10, v10
	v_add_f32_e32 v8, v9, v8
	v_mul_f32_e32 v9, v19, v19
	v_fmac_f32_e32 v9, v18, v18
	v_add_f32_e32 v16, v9, v8
	v_cvt_pk_bf16_f32 v8, v12, v13
	v_cvt_pk_bf16_f32 v9, v14, v15
	v_lshlrev_b32_e32 v12, 16, v96
	v_and_b32_e32 v13, 0xffff0000, v96
	v_lshlrev_b32_e32 v14, 16, v97
	v_and_b32_e32 v15, 0xffff0000, v97
	v_pk_add_f32 v[6:7], v[6:7], v[14:15]
	v_pk_add_f32 v[4:5], v[4:5], v[12:13]
	v_lshlrev_b32_e32 v12, 16, v98
	v_and_b32_e32 v13, 0xffff0000, v98
	v_pk_add_f32 v[12:13], v[0:1], v[12:13]
	v_mul_f32_e32 v0, v5, v5
	v_mul_f32_e32 v1, v7, v7
	v_fmac_f32_e32 v0, v4, v4
	v_fmac_f32_e32 v1, v6, v6
	v_lshlrev_b32_e32 v14, 16, v99
	v_and_b32_e32 v15, 0xffff0000, v99
	v_add_f32_e32 v0, v0, v1
	v_mul_f32_e32 v1, v13, v13
	v_pk_add_f32 v[14:15], v[2:3], v[14:15]
	v_fmac_f32_e32 v1, v12, v12
	v_add_f32_e32 v0, v1, v0
	v_mul_f32_e32 v1, v15, v15
	v_fmac_f32_e32 v1, v14, v14
	v_add_f32_e32 v0, v1, v0
	v_add_f32_e32 v3, v16, v0
	v_cvt_pk_bf16_f32 v10, v10, v11
	v_cvt_pk_bf16_f32 v11, v18, v19
	v_mov_b32_e32 v18, v3
	s_nop 1
	v_permlane16_swap_b32_e32 v18, v3
	v_lshl_add_u64 v[0:1], s[36:37], 0, v[206:207]
	v_lshl_add_u64 v[16:17], v[204:205], 1, v[0:1]
	global_store_dwordx4 v[16:17], v[8:11], off
	v_cvt_pk_bf16_f32 v2, v4, v5
	s_waitcnt lgkmcnt(0)
	v_add_f32_e32 v0, v3, v18
	v_mov_b32_e32 v1, v0
	s_nop 1
	v_permlane32_swap_b32_e32 v1, v0
	v_cvt_pk_bf16_f32 v3, v6, v7
	v_cvt_pk_bf16_f32 v4, v12, v13
	v_cvt_pk_bf16_f32 v5, v14, v15
	global_store_dwordx4 v[16:17], v[2:5], off offset:256
	s_and_saveexec_b64 s[34:35], s[4:5]
	s_cbranch_execz .LBB0_724
	s_add_u32 s20, s63, s20
	s_addc_u32 s21, s64, s21
	v_lshl_add_u64 v[2:3], v[202:203], 2, s[20:21]
	s_waitcnt lgkmcnt(0)
	v_add_f32_e32 v0, v0, v1
	global_store_dword v[2:3], v0, off offset:704

; __device__ __forceinline__ unsigned cvt_pk_bf16(float lo, float hi) { unsigned r; asm volatile("v_cvt_pk_bf16_f32 %0, %1, %2" : "=v"(r) : "v"(lo), "v"(hi)); return r; }
;     __device__ __forceinline__ void operator()(const f32x4 (&acc)[2][2][4][2], const pg8::Unit& u, int wr, int wc, int fr, int fq) const {
;         const int row0 = u.pm * 256 + wr * 64 + fr, col0 = u.pn * 256 + wc * 32 + 8 * fq;
;         u32x4 xin[2][4][2];
; #pragma unroll
;         for (int ai = 0; ai < 2; ++ai)
; #pragma unroll
;             for (int m = 0; m < 4; ++m)
; #pragma unroll
;                 for (int bj = 0; bj < 2; ++bj) xin[ai][m][bj] = *(const u32x4*)(XB + (size_t)(row0 + ai * 128 + m * 16) * D + col0 + bj * 128);
; #pragma unroll
;         for (int ai = 0; ai < 2; ++ai)
; #pragma unroll
;             for (int m = 0; m < 4; ++m) { const size_t ro = (size_t)(row0 + ai * 128 + m * 16) * D + col0; float sq = 0.f;
; #pragma unroll
;                 for (int bj = 0; bj < 2; ++bj) { const u32x4 xb = xin[ai][m][bj];
;                     const f32x4 x0 = (f32x4){bf_lo(xb.x), bf_hi(xb.x), bf_lo(xb.y), bf_hi(xb.y)} + acc[ai][bj][m][0] * s, x1 = (f32x4){bf_lo(xb.z), bf_hi(xb.z), bf_lo(xb.w), bf_hi(xb.w)} + acc[ai][bj][m][1] * s;
;                     sq += (x0[0] * x0[0] + x0[1] * x0[1]) + (x0[2] * x0[2] + x0[3] * x0[3]) + (x1[0] * x1[0] + x1[1] * x1[1]) + (x1[2] * x1[2] + x1[3] * x1[3]);
;                     u32x4 w; w.x = cvt_pk_bf16(x0[0], x0[1]); w.y = cvt_pk_bf16(x0[2], x0[3]); w.z = cvt_pk_bf16(x1[0], x1[1]); w.w = cvt_pk_bf16(x1[2], x1[3]);
;                     *(u32x4*)(XB + ro + bj * 128) = w; }
;                 sq += __shfl_xor(sq, 16); sq += __shfl_xor(sq, 32);
;                 if (fq == 0) SSo[(size_t)(u.pn * 4 + wc) * T + row0 + ai * 128 + m * 16] = sq; }
.LBB0_898:
	v_lshl_or_b32 v204, s68, 8, v222
	v_lshl_add_u32 v202, s69, 8, v220
	v_ashrrev_i32_e32 v205, 31, v204
	v_lshlrev_b64 v[236:237], 1, v[204:205]
	v_ashrrev_i32_e32 v203, 31, v202
	v_lshl_add_u64 v[96:97], s[36:37], 0, v[236:237]
	v_lshlrev_b64 v[238:239], 11, v[202:203]
	v_lshl_add_u64 v[98:99], v[96:97], 0, v[238:239]
	global_load_dwordx4 v[228:231], v[98:99], off
	global_load_dwordx4 v[232:235], v[98:99], off offset:256
	v_or_b32_e32 v98, 16, v202
	v_or_b32_e32 v108, 32, v202
	v_or_b32_e32 v110, 48, v202
	v_ashrrev_i32_e32 v99, 31, v98
	v_ashrrev_i32_e32 v109, 31, v108
	v_ashrrev_i32_e32 v111, 31, v110
	v_lshlrev_b64 v[218:219], 11, v[98:99]
	v_lshlrev_b64 v[216:217], 11, v[108:109]
	v_lshlrev_b64 v[214:215], 11, v[110:111]
	v_lshl_add_u64 v[212:213], v[238:239], 0, s[16:17]
	v_lshl_add_u64 v[210:211], v[238:239], 0, s[18:19]
	v_lshl_add_u64 v[208:209], v[238:239], 0, s[38:39]
	v_lshl_add_u64 v[206:207], v[238:239], 0, s[44:45]
	v_lshl_add_u64 v[98:99], v[96:97], 0, v[218:219]
	v_lshl_add_u64 v[108:109], v[96:97], 0, v[216:217]
	v_lshl_add_u64 v[110:111], v[96:97], 0, v[214:215]
	v_lshl_add_u64 v[120:121], v[96:97], 0, v[212:213]
	v_lshl_add_u64 v[122:123], v[96:97], 0, v[210:211]
	v_lshl_add_u64 v[240:241], v[96:97], 0, v[208:209]
	v_lshl_add_u64 v[96:97], v[96:97], 0, v[206:207]
	global_load_dwordx4 v[180:183], v[98:99], off
	global_load_dwordx4 v[176:179], v[98:99], off offset:256
	global_load_dwordx4 v[172:175], v[108:109], off
	global_load_dwordx4 v[168:171], v[108:109], off offset:256
	global_load_dwordx4 v[164:167], v[110:111], off
	global_load_dwordx4 v[160:163], v[110:111], off offset:256
	global_load_dwordx4 v[156:159], v[120:121], off
	global_load_dwordx4 v[152:155], v[120:121], off offset:256
	global_load_dwordx4 v[148:151], v[122:123], off
	global_load_dwordx4 v[144:147], v[122:123], off offset:256
	global_load_dwordx4 v[128:131], v[240:241], off
	s_nop 0
	global_load_dwordx4 v[120:123], v[240:241], off offset:256
	global_load_dwordx4 v[108:111], v[96:97], off
	s_nop 0
	global_load_dwordx4 v[96:99], v[96:97], off offset:256
	s_lshl_b32 s20, s68, 2
	s_or_b32 s20, s20, s58
	s_ashr_i32 s21, s20, 31
	s_lshl_b64 s[20:21], s[20:21], 17
	s_waitcnt vmcnt(0)
	v_lshlrev_b32_e32 v240, 16, v228
	v_and_b32_e32 v241, 0xffff0000, v228
	v_lshlrev_b32_e32 v228, 16, v229
	v_and_b32_e32 v229, 0xffff0000, v229
	v_lshlrev_b32_e32 v242, 16, v230
	v_and_b32_e32 v243, 0xffff0000, v230
	v_lshlrev_b32_e32 v244, 16, v232
	v_and_b32_e32 v245, 0xffff0000, v232
	v_lshlrev_b32_e32 v232, 16, v233
	v_and_b32_e32 v233, 0xffff0000, v233
	v_lshlrev_b32_e32 v246, 16, v234
	v_and_b32_e32 v247, 0xffff0000, v234
	v_lshlrev_b32_e32 v234, 16, v235
	v_and_b32_e32 v235, 0xffff0000, v235
	v_pk_fma_f32 v[142:143], v[142:143], 0.5, v[228:229] op_sel_hi:[1,0,1]
	v_pk_fma_f32 v[140:141], v[140:141], 0.5, v[240:241] op_sel_hi:[1,0,1]
	v_lshlrev_b32_e32 v230, 16, v231
	v_and_b32_e32 v231, 0xffff0000, v231
	v_pk_fma_f32 v[136:137], v[136:137], 0.5, v[242:243] op_sel_hi:[1,0,1]
	v_pk_fma_f32 v[228:229], v[134:135], 0.5, v[232:233] op_sel_hi:[1,0,1]
	v_pk_fma_f32 v[232:233], v[126:127], 0.5, v[234:235] op_sel_hi:[1,0,1]
	v_pk_fma_f32 v[234:235], v[124:125], 0.5, v[246:247] op_sel_hi:[1,0,1]
	v_mul_f32_e32 v124, v141, v141
	v_mul_f32_e32 v125, v143, v143
	v_pk_fma_f32 v[138:139], v[138:139], 0.5, v[230:231] op_sel_hi:[1,0,1]
	v_pk_fma_f32 v[230:231], v[132:133], 0.5, v[244:245] op_sel_hi:[1,0,1]
	v_mul_f32_e32 v126, v137, v137
	v_fmac_f32_e32 v124, v140, v140
	v_fmac_f32_e32 v125, v142, v142
	v_mul_f32_e32 v127, v139, v139
	v_cvt_pk_bf16_f32 v132, v140, v141
	v_cvt_pk_bf16_f32 v133, v142, v143
	v_cvt_pk_bf16_f32 v134, v136, v137
	v_cvt_pk_bf16_f32 v135, v138, v139
	v_mul_f32_e32 v137, v231, v231
	v_mul_f32_e32 v139, v229, v229
	v_fmac_f32_e32 v126, v136, v136
	v_add_f32_e32 v124, v124, v125
	v_fmac_f32_e32 v137, v230, v230
	v_fmac_f32_e32 v139, v228, v228
	v_add_f32_e32 v124, v126, v124
	v_mul_f32_e32 v126, v235, v235
	v_add_f32_e32 v125, v137, v139
	v_fmac_f32_e32 v126, v234, v234
	v_add_f32_e32 v125, v126, v125
	v_mul_f32_e32 v126, v233, v233
	v_fmac_f32_e32 v127, v138, v138
	v_fmac_f32_e32 v126, v232, v232
	v_add_f32_e32 v124, v127, v124
	v_add_f32_e32 v125, v126, v125
	v_and_b32_e32 v126, 64, v226
	v_add_f32_e32 v125, v124, v125
	v_add_u32_e32 v138, 64, v126
	v_lshl_add_u64 v[126:127], s[36:37], 0, v[238:239]
	v_lshl_add_u64 v[136:137], v[126:127], 0, v[236:237]
	v_mov_b32_e32 v139, v125
	s_nop 1
	v_permlane16_swap_b32_e32 v139, v125
	global_store_dwordx4 v[136:137], v[132:135], off
	s_waitcnt lgkmcnt(0)
	v_add_f32_e32 v126, v125, v139
	v_cvt_pk_bf16_f32 v132, v230, v231
	v_cvt_pk_bf16_f32 v133, v228, v229
	v_cvt_pk_bf16_f32 v134, v234, v235
	v_cvt_pk_bf16_f32 v135, v232, v233
	global_store_dwordx4 v[136:137], v[132:135], off offset:256
	s_nop 0
	v_mov_b32_e32 v127, v126
	s_nop 1
	v_permlane32_swap_b32_e32 v127, v126
	s_and_saveexec_b64 s[34:35], s[4:5]
	s_cbranch_execz .LBB0_900
	s_add_u32 s48, s56, s20
	s_addc_u32 s49, s57, s21
	v_lshl_add_u64 v[132:133], v[202:203], 2, s[48:49]
	s_waitcnt lgkmcnt(0)
	v_add_f32_e32 v126, v126, v127
	global_store_dword v[132:133], v126, off
; __device__ __forceinline__ unsigned cvt_pk_bf16(float lo, float hi) { unsigned r; asm volatile("v_cvt_pk_bf16_f32 %0, %1, %2" : "=v"(r) : "v"(lo), "v"(hi)); return r; }
;     __device__ __forceinline__ void operator()(const f32x4 (&acc)[2][2][4][2], const pg8::Unit& u, int wr, int wc, int fr, int fq) const {
;     ...
;             for (int m = 0; m < 4; ++m) { const size_t ro = (size_t)(row0 + ai * 128 + m * 16) * D + col0; float sq = 0.f;
; #pragma unroll
;                 for (int bj = 0; bj < 2; ++bj) { const u32x4 xb = xin[ai][m][bj];
;                     const f32x4 x0 = (f32x4){bf_lo(xb.x), bf_hi(xb.x), bf_lo(xb.y), bf_hi(xb.y)} + acc[ai][bj][m][0] * s, x1 = (f32x4){bf_lo(xb.z), bf_hi(xb.z), bf_lo(xb.w), bf_hi(xb.w)} + acc[ai][bj][m][1] * s;
;                     sq += (x0[0] * x0[0] + x0[1] * x0[1]) + (x0[2] * x0[2] + x0[3] * x0[3]) + (x1[0] * x1[0] + x1[1] * x1[1]) + (x1[2] * x1[2] + x1[3] * x1[3]);
;                     u32x4 w; w.x = cvt_pk_bf16(x0[0], x0[1]); w.y = cvt_pk_bf16(x0[2], x0[3]); w.z = cvt_pk_bf16(x1[0], x1[1]); w.w = cvt_pk_bf16(x1[2], x1[3]);
;                     *(u32x4*)(XB + ro + bj * 128) = w; }
;                 sq += __shfl_xor(sq, 16); sq += __shfl_xor(sq, 32);
;                 if (fq == 0) SSo[(size_t)(u.pn * 4 + wc) * T + row0 + ai * 128 + m * 16] = sq; }
.LBB0_900:
	s_or_b64 exec, exec, s[34:35]
	v_lshlrev_b32_e32 v126, 16, v180
	s_waitcnt lgkmcnt(0)
	v_and_b32_e32 v127, 0xffff0000, v180
	v_lshlrev_b32_e32 v132, 16, v181
	v_and_b32_e32 v133, 0xffff0000, v181
	v_pk_fma_f32 v[118:119], v[118:119], 0.5, v[132:133] op_sel_hi:[1,0,1]
	v_pk_fma_f32 v[116:117], v[116:117], 0.5, v[126:127] op_sel_hi:[1,0,1]
	v_lshlrev_b32_e32 v126, 16, v182
	v_and_b32_e32 v127, 0xffff0000, v182
	v_lshlrev_b32_e32 v132, 16, v183
	v_and_b32_e32 v133, 0xffff0000, v183
	v_pk_fma_f32 v[132:133], v[114:115], 0.5, v[132:133] op_sel_hi:[1,0,1]
	v_pk_fma_f32 v[114:115], v[112:113], 0.5, v[126:127] op_sel_hi:[1,0,1]
	v_mul_f32_e32 v112, v117, v117
	v_mul_f32_e32 v113, v119, v119
	v_fmac_f32_e32 v112, v116, v116
	v_fmac_f32_e32 v113, v118, v118
	v_add_f32_e32 v112, v112, v113
	v_mul_f32_e32 v113, v115, v115
	v_fmac_f32_e32 v113, v114, v114
	v_add_f32_e32 v112, v113, v112
	v_mul_f32_e32 v113, v133, v133
	v_fmac_f32_e32 v113, v132, v132
	v_add_f32_e32 v126, v113, v112
	v_cvt_pk_bf16_f32 v112, v116, v117
	v_cvt_pk_bf16_f32 v113, v118, v119
	v_lshlrev_b32_e32 v116, 16, v176
	v_and_b32_e32 v117, 0xffff0000, v176
	v_lshlrev_b32_e32 v118, 16, v177
	v_and_b32_e32 v119, 0xffff0000, v177
	v_pk_fma_f32 v[106:107], v[106:107], 0.5, v[118:119] op_sel_hi:[1,0,1]
	v_pk_fma_f32 v[104:105], v[104:105], 0.5, v[116:117] op_sel_hi:[1,0,1]
	v_lshlrev_b32_e32 v116, 16, v178
	v_and_b32_e32 v117, 0xffff0000, v178
	v_pk_fma_f32 v[116:117], v[100:101], 0.5, v[116:117] op_sel_hi:[1,0,1]
	v_mul_f32_e32 v100, v105, v105
	v_mul_f32_e32 v101, v107, v107
	v_fmac_f32_e32 v100, v104, v104
	v_fmac_f32_e32 v101, v106, v106
	v_lshlrev_b32_e32 v118, 16, v179
	v_and_b32_e32 v119, 0xffff0000, v179
	v_add_f32_e32 v100, v100, v101
	v_mul_f32_e32 v101, v117, v117
	v_pk_fma_f32 v[118:119], v[102:103], 0.5, v[118:119] op_sel_hi:[1,0,1]
	v_fmac_f32_e32 v101, v116, v116
	v_add_f32_e32 v100, v101, v100
	v_mul_f32_e32 v101, v119, v119
	v_fmac_f32_e32 v101, v118, v118
	v_add_f32_e32 v100, v101, v100
	v_add_f32_e32 v103, v126, v100
	v_cvt_pk_bf16_f32 v114, v114, v115
	v_cvt_pk_bf16_f32 v115, v132, v133
	v_mov_b32_e32 v132, v103
	s_nop 1
	v_permlane16_swap_b32_e32 v132, v103
	v_lshl_add_u64 v[100:101], s[36:37], 0, v[218:219]
	v_lshl_add_u64 v[126:127], v[204:205], 1, v[100:101]
	global_store_dwordx4 v[126:127], v[112:115], off
	v_cvt_pk_bf16_f32 v102, v104, v105
	s_waitcnt lgkmcnt(0)
	v_add_f32_e32 v100, v103, v132
	v_mov_b32_e32 v101, v100
	s_nop 1
	v_permlane32_swap_b32_e32 v101, v100
	v_cvt_pk_bf16_f32 v103, v106, v107
	v_cvt_pk_bf16_f32 v104, v116, v117
	v_cvt_pk_bf16_f32 v105, v118, v119
	global_store_dwordx4 v[126:127], v[102:105], off offset:256
	s_and_saveexec_b64 s[34:35], s[4:5]
	s_cbranch_execz .LBB0_902
	s_add_u32 s48, s56, s20
	s_addc_u32 s49, s57, s21
	v_lshl_add_u64 v[102:103], v[202:203], 2, s[48:49]
	s_waitcnt lgkmcnt(0)
	v_add_f32_e32 v100, v100, v101
	global_store_dword v[102:103], v100, off offset:64
.LBB0_902:
	s_or_b64 exec, exec, s[34:35]
	v_lshlrev_b32_e32 v100, 16, v172
	s_waitcnt lgkmcnt(0)
	v_and_b32_e32 v101, 0xffff0000, v172
	v_lshlrev_b32_e32 v102, 16, v173
	v_and_b32_e32 v103, 0xffff0000, v173
	v_pk_fma_f32 v[94:95], v[94:95], 0.5, v[102:103] op_sel_hi:[1,0,1]
	v_pk_fma_f32 v[92:93], v[92:93], 0.5, v[100:101] op_sel_hi:[1,0,1]
	v_lshlrev_b32_e32 v100, 16, v174
	v_and_b32_e32 v101, 0xffff0000, v174
	v_lshlrev_b32_e32 v102, 16, v175
	v_and_b32_e32 v103, 0xffff0000, v175
	v_pk_fma_f32 v[102:103], v[90:91], 0.5, v[102:103] op_sel_hi:[1,0,1]
	v_pk_fma_f32 v[90:91], v[88:89], 0.5, v[100:101] op_sel_hi:[1,0,1]
	v_mul_f32_e32 v88, v93, v93
	v_mul_f32_e32 v89, v95, v95
	v_fmac_f32_e32 v88, v92, v92
	v_fmac_f32_e32 v89, v94, v94
	v_add_f32_e32 v88, v88, v89
	v_mul_f32_e32 v89, v91, v91
	v_fmac_f32_e32 v89, v90, v90
	v_add_f32_e32 v88, v89, v88
	v_mul_f32_e32 v89, v103, v103
	v_fmac_f32_e32 v89, v102, v102
	v_add_f32_e32 v100, v89, v88
	v_cvt_pk_bf16_f32 v88, v92, v93
	v_cvt_pk_bf16_f32 v89, v94, v95
	v_lshlrev_b32_e32 v92, 16, v168
	v_and_b32_e32 v93, 0xffff0000, v168
	v_lshlrev_b32_e32 v94, 16, v169
	v_and_b32_e32 v95, 0xffff0000, v169
	v_pk_fma_f32 v[86:87], v[86:87], 0.5, v[94:95] op_sel_hi:[1,0,1]
	v_pk_fma_f32 v[84:85], v[84:85], 0.5, v[92:93] op_sel_hi:[1,0,1]
	v_lshlrev_b32_e32 v92, 16, v170
	v_and_b32_e32 v93, 0xffff0000, v170
	v_pk_fma_f32 v[92:93], v[80:81], 0.5, v[92:93] op_sel_hi:[1,0,1]
	v_mul_f32_e32 v80, v85, v85
	v_mul_f32_e32 v81, v87, v87
	v_fmac_f32_e32 v80, v84, v84
	v_fmac_f32_e32 v81, v86, v86
	v_lshlrev_b32_e32 v94, 16, v171
	v_and_b32_e32 v95, 0xffff0000, v171
	v_add_f32_e32 v80, v80, v81
	v_mul_f32_e32 v81, v93, v93
	v_pk_fma_f32 v[94:95], v[82:83], 0.5, v[94:95] op_sel_hi:[1,0,1]
	v_fmac_f32_e32 v81, v92, v92
	v_add_f32_e32 v80, v81, v80
	v_mul_f32_e32 v81, v95, v95
	v_fmac_f32_e32 v81, v94, v94
	v_add_f32_e32 v80, v81, v80
	v_add_f32_e32 v83, v100, v80
	v_cvt_pk_bf16_f32 v90, v90, v91
	v_cvt_pk_bf16_f32 v91, v102, v103
	v_mov_b32_e32 v102, v83
	s_nop 1
	v_permlane16_swap_b32_e32 v102, v83
	v_lshl_add_u64 v[80:81], s[36:37], 0, v[216:217]
	v_lshl_add_u64 v[100:101], v[204:205], 1, v[80:81]
	global_store_dwordx4 v[100:101], v[88:91], off
	v_cvt_pk_bf16_f32 v82, v84, v85
	s_waitcnt lgkmcnt(0)
	v_add_f32_e32 v80, v83, v102
	v_mov_b32_e32 v81, v80
	s_nop 1
	v_permlane32_swap_b32_e32 v81, v80
	v_cvt_pk_bf16_f32 v83, v86, v87
	v_cvt_pk_bf16_f32 v84, v92, v93
	v_cvt_pk_bf16_f32 v85, v94, v95
	global_store_dwordx4 v[100:101], v[82:85], off offset:256
	s_and_saveexec_b64 s[34:35], s[4:5]
	s_cbranch_execz .LBB0_904
	s_add_u32 s48, s56, s20
	s_addc_u32 s49, s57, s21
	v_lshl_add_u64 v[82:83], v[202:203], 2, s[48:49]
	s_waitcnt lgkmcnt(0)
	v_add_f32_e32 v80, v80, v81
	global_store_dword v[82:83], v80, off offset:128
; __device__ __forceinline__ unsigned cvt_pk_bf16(float lo, float hi) { unsigned r; asm volatile("v_cvt_pk_bf16_f32 %0, %1, %2" : "=v"(r) : "v"(lo), "v"(hi)); return r; }
;     __device__ __forceinline__ void operator()(const f32x4 (&acc)[2][2][4][2], const pg8::Unit& u, int wr, int wc, int fr, int fq) const {
;     ...
;             for (int m = 0; m < 4; ++m) { const size_t ro = (size_t)(row0 + ai * 128 + m * 16) * D + col0; float sq = 0.f;
; #pragma unroll
;                 for (int bj = 0; bj < 2; ++bj) { const u32x4 xb = xin[ai][m][bj];
;                     const f32x4 x0 = (f32x4){bf_lo(xb.x), bf_hi(xb.x), bf_lo(xb.y), bf_hi(xb.y)} + acc[ai][bj][m][0] * s, x1 = (f32x4){bf_lo(xb.z), bf_hi(xb.z), bf_lo(xb.w), bf_hi(xb.w)} + acc[ai][bj][m][1] * s;
;                     sq += (x0[0] * x0[0] + x0[1] * x0[1]) + (x0[2] * x0[2] + x0[3] * x0[3]) + (x1[0] * x1[0] + x1[1] * x1[1]) + (x1[2] * x1[2] + x1[3] * x1[3]);
;                     u32x4 w; w.x = cvt_pk_bf16(x0[0], x0[1]); w.y = cvt_pk_bf16(x0[2], x0[3]); w.z = cvt_pk_bf16(x1[0], x1[1]); w.w = cvt_pk_bf16(x1[2], x1[3]);
;                     *(u32x4*)(XB + ro + bj * 128) = w; }
;                 sq += __shfl_xor(sq, 16); sq += __shfl_xor(sq, 32);
;                 if (fq == 0) SSo[(size_t)(u.pn * 4 + wc) * T + row0 + ai * 128 + m * 16] = sq; }
.LBB0_904:
	s_or_b64 exec, exec, s[34:35]
	v_lshlrev_b32_e32 v80, 16, v164
	s_waitcnt lgkmcnt(0)
	v_and_b32_e32 v81, 0xffff0000, v164
	v_lshlrev_b32_e32 v82, 16, v165
	v_and_b32_e32 v83, 0xffff0000, v165
	v_pk_fma_f32 v[78:79], v[78:79], 0.5, v[82:83] op_sel_hi:[1,0,1]
	v_pk_fma_f32 v[76:77], v[76:77], 0.5, v[80:81] op_sel_hi:[1,0,1]
	v_lshlrev_b32_e32 v80, 16, v166
	v_and_b32_e32 v81, 0xffff0000, v166
	v_lshlrev_b32_e32 v82, 16, v167
	v_and_b32_e32 v83, 0xffff0000, v167
	v_pk_fma_f32 v[82:83], v[74:75], 0.5, v[82:83] op_sel_hi:[1,0,1]
	v_pk_fma_f32 v[74:75], v[72:73], 0.5, v[80:81] op_sel_hi:[1,0,1]
	v_mul_f32_e32 v72, v77, v77
	v_mul_f32_e32 v73, v79, v79
	v_fmac_f32_e32 v72, v76, v76
	v_fmac_f32_e32 v73, v78, v78
	v_add_f32_e32 v72, v72, v73
	v_mul_f32_e32 v73, v75, v75
	v_fmac_f32_e32 v73, v74, v74
	v_add_f32_e32 v72, v73, v72
	v_mul_f32_e32 v73, v83, v83
	v_fmac_f32_e32 v73, v82, v82
	v_add_f32_e32 v80, v73, v72
	v_cvt_pk_bf16_f32 v72, v76, v77
	v_cvt_pk_bf16_f32 v73, v78, v79
	v_lshlrev_b32_e32 v76, 16, v160
	v_and_b32_e32 v77, 0xffff0000, v160
	v_lshlrev_b32_e32 v78, 16, v161
	v_and_b32_e32 v79, 0xffff0000, v161
	v_pk_fma_f32 v[70:71], v[70:71], 0.5, v[78:79] op_sel_hi:[1,0,1]
	v_pk_fma_f32 v[68:69], v[68:69], 0.5, v[76:77] op_sel_hi:[1,0,1]
	v_lshlrev_b32_e32 v76, 16, v162
	v_and_b32_e32 v77, 0xffff0000, v162
	v_pk_fma_f32 v[76:77], v[64:65], 0.5, v[76:77] op_sel_hi:[1,0,1]
	v_mul_f32_e32 v64, v69, v69
	v_mul_f32_e32 v65, v71, v71
	v_fmac_f32_e32 v64, v68, v68
	v_fmac_f32_e32 v65, v70, v70
	v_lshlrev_b32_e32 v78, 16, v163
	v_and_b32_e32 v79, 0xffff0000, v163
	v_add_f32_e32 v64, v64, v65
	v_mul_f32_e32 v65, v77, v77
	v_pk_fma_f32 v[78:79], v[66:67], 0.5, v[78:79] op_sel_hi:[1,0,1]
	v_fmac_f32_e32 v65, v76, v76
	v_add_f32_e32 v64, v65, v64
	v_mul_f32_e32 v65, v79, v79
	v_fmac_f32_e32 v65, v78, v78
	v_add_f32_e32 v64, v65, v64
	v_add_f32_e32 v67, v80, v64
	v_cvt_pk_bf16_f32 v74, v74, v75
	v_cvt_pk_bf16_f32 v75, v82, v83
	v_mov_b32_e32 v82, v67
	s_nop 1
	v_permlane16_swap_b32_e32 v82, v67
	v_lshl_add_u64 v[64:65], s[36:37], 0, v[214:215]
	v_lshl_add_u64 v[80:81], v[204:205], 1, v[64:65]
	global_store_dwordx4 v[80:81], v[72:75], off
	v_cvt_pk_bf16_f32 v66, v68, v69
	s_waitcnt lgkmcnt(0)
	v_add_f32_e32 v64, v67, v82
	v_mov_b32_e32 v65, v64
	s_nop 1
	v_permlane32_swap_b32_e32 v65, v64
	v_cvt_pk_bf16_f32 v67, v70, v71
	v_cvt_pk_bf16_f32 v68, v76, v77
	v_cvt_pk_bf16_f32 v69, v78, v79
	global_store_dwordx4 v[80:81], v[66:69], off offset:256
	s_and_saveexec_b64 s[34:35], s[4:5]
	s_cbranch_execz .LBB0_906
	s_add_u32 s48, s56, s20
	s_addc_u32 s49, s57, s21
	v_lshl_add_u64 v[66:67], v[202:203], 2, s[48:49]
	s_waitcnt lgkmcnt(0)
	v_add_f32_e32 v64, v64, v65
	global_store_dword v[66:67], v64, off offset:192
.LBB0_906:
	s_or_b64 exec, exec, s[34:35]
	v_lshlrev_b32_e32 v64, 16, v156
	s_waitcnt lgkmcnt(0)
	v_and_b32_e32 v65, 0xffff0000, v156
	v_lshlrev_b32_e32 v66, 16, v157
	v_and_b32_e32 v67, 0xffff0000, v157
	v_pk_fma_f32 v[62:63], v[62:63], 0.5, v[66:67] op_sel_hi:[1,0,1]
	v_pk_fma_f32 v[60:61], v[60:61], 0.5, v[64:65] op_sel_hi:[1,0,1]
	v_lshlrev_b32_e32 v64, 16, v158
	v_and_b32_e32 v65, 0xffff0000, v158
	v_lshlrev_b32_e32 v66, 16, v159
	v_and_b32_e32 v67, 0xffff0000, v159
	v_pk_fma_f32 v[66:67], v[58:59], 0.5, v[66:67] op_sel_hi:[1,0,1]
	v_pk_fma_f32 v[58:59], v[56:57], 0.5, v[64:65] op_sel_hi:[1,0,1]
	v_mul_f32_e32 v56, v61, v61
	v_mul_f32_e32 v57, v63, v63
	v_fmac_f32_e32 v56, v60, v60
	v_fmac_f32_e32 v57, v62, v62
	v_add_f32_e32 v56, v56, v57
	v_mul_f32_e32 v57, v59, v59
	v_fmac_f32_e32 v57, v58, v58
	v_add_f32_e32 v56, v57, v56
	v_mul_f32_e32 v57, v67, v67
	v_fmac_f32_e32 v57, v66, v66
	v_add_f32_e32 v64, v57, v56
	v_cvt_pk_bf16_f32 v56, v60, v61
	v_cvt_pk_bf16_f32 v57, v62, v63
	v_lshlrev_b32_e32 v60, 16, v152
	v_and_b32_e32 v61, 0xffff0000, v152
	v_lshlrev_b32_e32 v62, 16, v153
	v_and_b32_e32 v63, 0xffff0000, v153
	v_pk_fma_f32 v[54:55], v[54:55], 0.5, v[62:63] op_sel_hi:[1,0,1]
	v_pk_fma_f32 v[52:53], v[52:53], 0.5, v[60:61] op_sel_hi:[1,0,1]
	v_lshlrev_b32_e32 v60, 16, v154
	v_and_b32_e32 v61, 0xffff0000, v154
	v_pk_fma_f32 v[60:61], v[48:49], 0.5, v[60:61] op_sel_hi:[1,0,1]
	v_mul_f32_e32 v48, v53, v53
	v_mul_f32_e32 v49, v55, v55
	v_fmac_f32_e32 v48, v52, v52
	v_fmac_f32_e32 v49, v54, v54
	v_lshlrev_b32_e32 v62, 16, v155
	v_and_b32_e32 v63, 0xffff0000, v155
	v_add_f32_e32 v48, v48, v49
	v_mul_f32_e32 v49, v61, v61
	v_pk_fma_f32 v[62:63], v[50:51], 0.5, v[62:63] op_sel_hi:[1,0,1]
	v_fmac_f32_e32 v49, v60, v60
	v_add_f32_e32 v48, v49, v48
	v_mul_f32_e32 v49, v63, v63
	v_fmac_f32_e32 v49, v62, v62
	v_add_f32_e32 v48, v49, v48
	v_add_f32_e32 v51, v64, v48
	v_cvt_pk_bf16_f32 v58, v58, v59
	v_cvt_pk_bf16_f32 v59, v66, v67
	v_mov_b32_e32 v66, v51
	s_nop 1
	v_permlane16_swap_b32_e32 v66, v51
	v_lshl_add_u64 v[48:49], s[36:37], 0, v[212:213]
	v_lshl_add_u64 v[64:65], v[204:205], 1, v[48:49]
	global_store_dwordx4 v[64:65], v[56:59], off
	v_cvt_pk_bf16_f32 v50, v52, v53
	s_waitcnt lgkmcnt(0)
	v_add_f32_e32 v48, v51, v66
	v_mov_b32_e32 v49, v48
	s_nop 1
	v_permlane32_swap_b32_e32 v49, v48
	v_cvt_pk_bf16_f32 v51, v54, v55
	v_cvt_pk_bf16_f32 v52, v60, v61
	v_cvt_pk_bf16_f32 v53, v62, v63
	global_store_dwordx4 v[64:65], v[50:53], off offset:256
	s_and_saveexec_b64 s[34:35], s[4:5]
	s_cbranch_execz .LBB0_908
	s_add_u32 s48, s56, s20
	s_addc_u32 s49, s57, s21
	v_lshl_add_u64 v[50:51], v[202:203], 2, s[48:49]
	s_waitcnt lgkmcnt(0)
	v_add_f32_e32 v48, v48, v49
	global_store_dword v[50:51], v48, off offset:512
; __device__ __forceinline__ unsigned cvt_pk_bf16(float lo, float hi) { unsigned r; asm volatile("v_cvt_pk_bf16_f32 %0, %1, %2" : "=v"(r) : "v"(lo), "v"(hi)); return r; }
;     __device__ __forceinline__ void operator()(const f32x4 (&acc)[2][2][4][2], const pg8::Unit& u, int wr, int wc, int fr, int fq) const {
;     ...
;             for (int m = 0; m < 4; ++m) { const size_t ro = (size_t)(row0 + ai * 128 + m * 16) * D + col0; float sq = 0.f;
; #pragma unroll
;                 for (int bj = 0; bj < 2; ++bj) { const u32x4 xb = xin[ai][m][bj];
;                     const f32x4 x0 = (f32x4){bf_lo(xb.x), bf_hi(xb.x), bf_lo(xb.y), bf_hi(xb.y)} + acc[ai][bj][m][0] * s, x1 = (f32x4){bf_lo(xb.z), bf_hi(xb.z), bf_lo(xb.w), bf_hi(xb.w)} + acc[ai][bj][m][1] * s;
;                     sq += (x0[0] * x0[0] + x0[1] * x0[1]) + (x0[2] * x0[2] + x0[3] * x0[3]) + (x1[0] * x1[0] + x1[1] * x1[1]) + (x1[2] * x1[2] + x1[3] * x1[3]);
;                     u32x4 w; w.x = cvt_pk_bf16(x0[0], x0[1]); w.y = cvt_pk_bf16(x0[2], x0[3]); w.z = cvt_pk_bf16(x1[0], x1[1]); w.w = cvt_pk_bf16(x1[2], x1[3]);
;                     *(u32x4*)(XB + ro + bj * 128) = w; }
;                 sq += __shfl_xor(sq, 16); sq += __shfl_xor(sq, 32);
;                 if (fq == 0) SSo[(size_t)(u.pn * 4 + wc) * T + row0 + ai * 128 + m * 16] = sq; }
.LBB0_908:
	s_or_b64 exec, exec, s[34:35]
	v_lshlrev_b32_e32 v48, 16, v148
	s_waitcnt lgkmcnt(0)
	v_and_b32_e32 v49, 0xffff0000, v148
	v_lshlrev_b32_e32 v50, 16, v149
	v_and_b32_e32 v51, 0xffff0000, v149
	v_pk_fma_f32 v[46:47], v[46:47], 0.5, v[50:51] op_sel_hi:[1,0,1]
	v_pk_fma_f32 v[44:45], v[44:45], 0.5, v[48:49] op_sel_hi:[1,0,1]
	v_lshlrev_b32_e32 v48, 16, v150
	v_and_b32_e32 v49, 0xffff0000, v150
	v_lshlrev_b32_e32 v50, 16, v151
	v_and_b32_e32 v51, 0xffff0000, v151
	v_pk_fma_f32 v[50:51], v[42:43], 0.5, v[50:51] op_sel_hi:[1,0,1]
	v_pk_fma_f32 v[42:43], v[40:41], 0.5, v[48:49] op_sel_hi:[1,0,1]
	v_mul_f32_e32 v40, v45, v45
	v_mul_f32_e32 v41, v47, v47
	v_fmac_f32_e32 v40, v44, v44
	v_fmac_f32_e32 v41, v46, v46
	v_add_f32_e32 v40, v40, v41
	v_mul_f32_e32 v41, v43, v43
	v_fmac_f32_e32 v41, v42, v42
	v_add_f32_e32 v40, v41, v40
	v_mul_f32_e32 v41, v51, v51
	v_fmac_f32_e32 v41, v50, v50
	v_add_f32_e32 v48, v41, v40
	v_cvt_pk_bf16_f32 v40, v44, v45
	v_cvt_pk_bf16_f32 v41, v46, v47
	v_lshlrev_b32_e32 v44, 16, v144
	v_and_b32_e32 v45, 0xffff0000, v144
	v_lshlrev_b32_e32 v46, 16, v145
	v_and_b32_e32 v47, 0xffff0000, v145
	v_pk_fma_f32 v[38:39], v[38:39], 0.5, v[46:47] op_sel_hi:[1,0,1]
	v_pk_fma_f32 v[36:37], v[36:37], 0.5, v[44:45] op_sel_hi:[1,0,1]
	v_lshlrev_b32_e32 v44, 16, v146
	v_and_b32_e32 v45, 0xffff0000, v146
	v_pk_fma_f32 v[44:45], v[32:33], 0.5, v[44:45] op_sel_hi:[1,0,1]
	v_mul_f32_e32 v32, v37, v37
	v_mul_f32_e32 v33, v39, v39
	v_fmac_f32_e32 v32, v36, v36
	v_fmac_f32_e32 v33, v38, v38
	v_lshlrev_b32_e32 v46, 16, v147
	v_and_b32_e32 v47, 0xffff0000, v147
	v_add_f32_e32 v32, v32, v33
	v_mul_f32_e32 v33, v45, v45
	v_pk_fma_f32 v[46:47], v[34:35], 0.5, v[46:47] op_sel_hi:[1,0,1]
	v_fmac_f32_e32 v33, v44, v44
	v_add_f32_e32 v32, v33, v32
	v_mul_f32_e32 v33, v47, v47
	v_fmac_f32_e32 v33, v46, v46
	v_add_f32_e32 v32, v33, v32
	v_add_f32_e32 v35, v48, v32
	v_cvt_pk_bf16_f32 v42, v42, v43
	v_cvt_pk_bf16_f32 v43, v50, v51
	v_mov_b32_e32 v50, v35
	s_nop 1
	v_permlane16_swap_b32_e32 v50, v35
	v_lshl_add_u64 v[32:33], s[36:37], 0, v[210:211]
	v_lshl_add_u64 v[48:49], v[204:205], 1, v[32:33]
	global_store_dwordx4 v[48:49], v[40:43], off
	v_cvt_pk_bf16_f32 v34, v36, v37
	s_waitcnt lgkmcnt(0)
	v_add_f32_e32 v32, v35, v50
	v_mov_b32_e32 v33, v32
	s_nop 1
	v_permlane32_swap_b32_e32 v33, v32
	v_cvt_pk_bf16_f32 v35, v38, v39
	v_cvt_pk_bf16_f32 v36, v44, v45
	v_cvt_pk_bf16_f32 v37, v46, v47
	global_store_dwordx4 v[48:49], v[34:37], off offset:256
	s_and_saveexec_b64 s[34:35], s[4:5]
	s_cbranch_execz .LBB0_910
	s_add_u32 s48, s56, s20
	s_addc_u32 s49, s57, s21
	v_lshl_add_u64 v[34:35], v[202:203], 2, s[48:49]
	s_waitcnt lgkmcnt(0)
	v_add_f32_e32 v32, v32, v33
	global_store_dword v[34:35], v32, off offset:576
; __device__ __forceinline__ unsigned cvt_pk_bf16(float lo, float hi) { unsigned r; asm volatile("v_cvt_pk_bf16_f32 %0, %1, %2" : "=v"(r) : "v"(lo), "v"(hi)); return r; }
;     __device__ __forceinline__ void operator()(const f32x4 (&acc)[2][2][4][2], const pg8::Unit& u, int wr, int wc, int fr, int fq) const {
;     ...
;             for (int m = 0; m < 4; ++m) { const size_t ro = (size_t)(row0 + ai * 128 + m * 16) * D + col0; float sq = 0.f;
; #pragma unroll
;                 for (int bj = 0; bj < 2; ++bj) { const u32x4 xb = xin[ai][m][bj];
;                     const f32x4 x0 = (f32x4){bf_lo(xb.x), bf_hi(xb.x), bf_lo(xb.y), bf_hi(xb.y)} + acc[ai][bj][m][0] * s, x1 = (f32x4){bf_lo(xb.z), bf_hi(xb.z), bf_lo(xb.w), bf_hi(xb.w)} + acc[ai][bj][m][1] * s;
;                     sq += (x0[0] * x0[0] + x0[1] * x0[1]) + (x0[2] * x0[2] + x0[3] * x0[3]) + (x1[0] * x1[0] + x1[1] * x1[1]) + (x1[2] * x1[2] + x1[3] * x1[3]);
;                     u32x4 w; w.x = cvt_pk_bf16(x0[0], x0[1]); w.y = cvt_pk_bf16(x0[2], x0[3]); w.z = cvt_pk_bf16(x1[0], x1[1]); w.w = cvt_pk_bf16(x1[2], x1[3]);
;                     *(u32x4*)(XB + ro + bj * 128) = w; }
;                 sq += __shfl_xor(sq, 16); sq += __shfl_xor(sq, 32);
;                 if (fq == 0) SSo[(size_t)(u.pn * 4 + wc) * T + row0 + ai * 128 + m * 16] = sq; }
.LBB0_910:
	s_or_b64 exec, exec, s[34:35]
	v_lshlrev_b32_e32 v32, 16, v128
	s_waitcnt lgkmcnt(0)
	v_and_b32_e32 v33, 0xffff0000, v128
	v_lshlrev_b32_e32 v34, 16, v129
	v_and_b32_e32 v35, 0xffff0000, v129
	v_pk_fma_f32 v[30:31], v[30:31], 0.5, v[34:35] op_sel_hi:[1,0,1]
	v_pk_fma_f32 v[28:29], v[28:29], 0.5, v[32:33] op_sel_hi:[1,0,1]
	v_lshlrev_b32_e32 v32, 16, v130
	v_and_b32_e32 v33, 0xffff0000, v130
	v_lshlrev_b32_e32 v34, 16, v131
	v_and_b32_e32 v35, 0xffff0000, v131
	v_pk_fma_f32 v[34:35], v[26:27], 0.5, v[34:35] op_sel_hi:[1,0,1]
	v_pk_fma_f32 v[26:27], v[24:25], 0.5, v[32:33] op_sel_hi:[1,0,1]
	v_mul_f32_e32 v24, v29, v29
	v_mul_f32_e32 v25, v31, v31
	v_fmac_f32_e32 v24, v28, v28
	v_fmac_f32_e32 v25, v30, v30
	v_add_f32_e32 v24, v24, v25
	v_mul_f32_e32 v25, v27, v27
	v_fmac_f32_e32 v25, v26, v26
	v_add_f32_e32 v24, v25, v24
	v_mul_f32_e32 v25, v35, v35
	v_fmac_f32_e32 v25, v34, v34
	v_add_f32_e32 v32, v25, v24
	v_cvt_pk_bf16_f32 v24, v28, v29
	v_cvt_pk_bf16_f32 v25, v30, v31
	v_lshlrev_b32_e32 v28, 16, v120
	v_and_b32_e32 v29, 0xffff0000, v120
	v_lshlrev_b32_e32 v30, 16, v121
	v_and_b32_e32 v31, 0xffff0000, v121
	v_pk_fma_f32 v[22:23], v[22:23], 0.5, v[30:31] op_sel_hi:[1,0,1]
	v_pk_fma_f32 v[20:21], v[20:21], 0.5, v[28:29] op_sel_hi:[1,0,1]
	v_lshlrev_b32_e32 v28, 16, v122
	v_and_b32_e32 v29, 0xffff0000, v122
	v_pk_fma_f32 v[28:29], v[16:17], 0.5, v[28:29] op_sel_hi:[1,0,1]
	v_mul_f32_e32 v16, v21, v21
	v_mul_f32_e32 v17, v23, v23
	v_fmac_f32_e32 v16, v20, v20
	v_fmac_f32_e32 v17, v22, v22
	v_lshlrev_b32_e32 v30, 16, v123
	v_and_b32_e32 v31, 0xffff0000, v123
	v_add_f32_e32 v16, v16, v17
	v_mul_f32_e32 v17, v29, v29
	v_pk_fma_f32 v[30:31], v[18:19], 0.5, v[30:31] op_sel_hi:[1,0,1]
	v_fmac_f32_e32 v17, v28, v28
	v_add_f32_e32 v16, v17, v16
	v_mul_f32_e32 v17, v31, v31
	v_fmac_f32_e32 v17, v30, v30
	v_add_f32_e32 v16, v17, v16
	v_add_f32_e32 v19, v32, v16
	v_cvt_pk_bf16_f32 v26, v26, v27
	v_cvt_pk_bf16_f32 v27, v34, v35
	v_mov_b32_e32 v34, v19
	s_nop 1
	v_permlane16_swap_b32_e32 v34, v19
	v_lshl_add_u64 v[16:17], s[36:37], 0, v[208:209]
	v_lshl_add_u64 v[32:33], v[204:205], 1, v[16:17]
	global_store_dwordx4 v[32:33], v[24:27], off
	v_cvt_pk_bf16_f32 v18, v20, v21
	s_waitcnt lgkmcnt(0)
	v_add_f32_e32 v16, v19, v34
	v_mov_b32_e32 v17, v16
	s_nop 1
	v_permlane32_swap_b32_e32 v17, v16
	v_cvt_pk_bf16_f32 v19, v22, v23
	v_cvt_pk_bf16_f32 v20, v28, v29
	v_cvt_pk_bf16_f32 v21, v30, v31
	global_store_dwordx4 v[32:33], v[18:21], off offset:256
	s_and_saveexec_b64 s[34:35], s[4:5]
	s_cbranch_execz .LBB0_912
	s_add_u32 s48, s56, s20
	s_addc_u32 s49, s57, s21
	v_lshl_add_u64 v[18:19], v[202:203], 2, s[48:49]
	s_waitcnt lgkmcnt(0)
	v_add_f32_e32 v16, v16, v17
	global_store_dword v[18:19], v16, off offset:640
.LBB0_912:
	s_or_b64 exec, exec, s[34:35]
	v_lshlrev_b32_e32 v16, 16, v108
	s_waitcnt lgkmcnt(0)
	v_and_b32_e32 v17, 0xffff0000, v108
	v_lshlrev_b32_e32 v18, 16, v109
	v_and_b32_e32 v19, 0xffff0000, v109
	v_pk_fma_f32 v[14:15], v[14:15], 0.5, v[18:19] op_sel_hi:[1,0,1]
	v_pk_fma_f32 v[12:13], v[12:13], 0.5, v[16:17] op_sel_hi:[1,0,1]
	v_lshlrev_b32_e32 v16, 16, v110
	v_and_b32_e32 v17, 0xffff0000, v110
	v_lshlrev_b32_e32 v18, 16, v111
	v_and_b32_e32 v19, 0xffff0000, v111
	v_pk_fma_f32 v[18:19], v[10:11], 0.5, v[18:19] op_sel_hi:[1,0,1]
	v_pk_fma_f32 v[10:11], v[8:9], 0.5, v[16:17] op_sel_hi:[1,0,1]
	v_mul_f32_e32 v8, v13, v13
	v_mul_f32_e32 v9, v15, v15
	v_fmac_f32_e32 v8, v12, v12
	v_fmac_f32_e32 v9, v14, v14
	v_add_f32_e32 v8, v8, v9
	v_mul_f32_e32 v9, v11, v11
	v_fmac_f32_e32 v9, v10, v10
	v_add_f32_e32 v8, v9, v8
	v_mul_f32_e32 v9, v19, v19
	v_fmac_f32_e32 v9, v18, v18
	v_add_f32_e32 v16, v9, v8
	v_cvt_pk_bf16_f32 v8, v12, v13
	v_cvt_pk_bf16_f32 v9, v14, v15
	v_lshlrev_b32_e32 v12, 16, v96
	v_and_b32_e32 v13, 0xffff0000, v96
	v_lshlrev_b32_e32 v14, 16, v97
	v_and_b32_e32 v15, 0xffff0000, v97
	v_pk_fma_f32 v[6:7], v[6:7], 0.5, v[14:15] op_sel_hi:[1,0,1]
	v_pk_fma_f32 v[4:5], v[4:5], 0.5, v[12:13] op_sel_hi:[1,0,1]
	v_lshlrev_b32_e32 v12, 16, v98
	v_and_b32_e32 v13, 0xffff0000, v98
	v_pk_fma_f32 v[12:13], v[0:1], 0.5, v[12:13] op_sel_hi:[1,0,1]
	v_mul_f32_e32 v0, v5, v5
	v_mul_f32_e32 v1, v7, v7
	v_fmac_f32_e32 v0, v4, v4
	v_fmac_f32_e32 v1, v6, v6
	v_lshlrev_b32_e32 v14, 16, v99
	v_and_b32_e32 v15, 0xffff0000, v99
	v_add_f32_e32 v0, v0, v1
	v_mul_f32_e32 v1, v13, v13
	v_pk_fma_f32 v[14:15], v[2:3], 0.5, v[14:15] op_sel_hi:[1,0,1]
	v_fmac_f32_e32 v1, v12, v12
	v_add_f32_e32 v0, v1, v0
	v_mul_f32_e32 v1, v15, v15
	v_fmac_f32_e32 v1, v14, v14
	v_add_f32_e32 v0, v1, v0
	v_add_f32_e32 v3, v16, v0
	v_cvt_pk_bf16_f32 v10, v10, v11
	v_cvt_pk_bf16_f32 v11, v18, v19
	v_mov_b32_e32 v18, v3
	s_nop 1
	v_permlane16_swap_b32_e32 v18, v3
	v_lshl_add_u64 v[0:1], s[36:37], 0, v[206:207]
	v_lshl_add_u64 v[16:17], v[204:205], 1, v[0:1]
	global_store_dwordx4 v[16:17], v[8:11], off
	v_cvt_pk_bf16_f32 v2, v4, v5
	s_waitcnt lgkmcnt(0)
	v_add_f32_e32 v0, v3, v18
	v_mov_b32_e32 v1, v0
	s_nop 1
	v_permlane32_swap_b32_e32 v1, v0
	v_cvt_pk_bf16_f32 v3, v6, v7
	v_cvt_pk_bf16_f32 v4, v12, v13
	v_cvt_pk_bf16_f32 v5, v14, v15
	global_store_dwordx4 v[16:17], v[2:5], off offset:256
	s_and_saveexec_b64 s[34:35], s[4:5]
	s_cbranch_execz .LBB0_914
	s_add_u32 s20, s56, s20
	s_addc_u32 s21, s57, s21
	v_lshl_add_u64 v[2:3], v[202:203], 2, s[20:21]
	s_waitcnt lgkmcnt(0)
	v_add_f32_e32 v0, v0, v1
	global_store_dword v[2:3], v0, off offset:704

; __device__ __forceinline__ unsigned cvt_pk_bf16(float lo, float hi) { unsigned r; asm volatile("v_cvt_pk_bf16_f32 %0, %1, %2" : "=v"(r) : "v"(lo), "v"(hi)); return r; }
;     __device__ __forceinline__ void operator()(const f32x4 (&acc)[2][2][4][2], const pg8::Unit& u, int wr, int wc, int fr, int fq) const {
;         const int row0 = u.pm * 256 + wr * 64 + fr, col0 = u.pn * 256 + wc * 32 + 8 * fq;
;         u32x4 xin[2][4][2];
; #pragma unroll
;         for (int ai = 0; ai < 2; ++ai)
; #pragma unroll
;             for (int m = 0; m < 4; ++m)
; #pragma unroll
;                 for (int bj = 0; bj < 2; ++bj) xin[ai][m][bj] = *(const u32x4*)(XB + (size_t)(row0 + ai * 128 + m * 16) * D + col0 + bj * 128);
; #pragma unroll
;         for (int ai = 0; ai < 2; ++ai)
; #pragma unroll
;             for (int m = 0; m < 4; ++m) { const size_t ro = (size_t)(row0 + ai * 128 + m * 16) * D + col0; float sq = 0.f;
; #pragma unroll
;                 for (int bj = 0; bj < 2; ++bj) { const u32x4 xb = xin[ai][m][bj];
;                     const f32x4 x0 = (f32x4){bf_lo(xb.x), bf_hi(xb.x), bf_lo(xb.y), bf_hi(xb.y)} + acc[ai][bj][m][0] * s, x1 = (f32x4){bf_lo(xb.z), bf_hi(xb.z), bf_lo(xb.w), bf_hi(xb.w)} + acc[ai][bj][m][1] * s;
;                     sq += (x0[0] * x0[0] + x0[1] * x0[1]) + (x0[2] * x0[2] + x0[3] * x0[3]) + (x1[0] * x1[0] + x1[1] * x1[1]) + (x1[2] * x1[2] + x1[3] * x1[3]);
;                     u32x4 w; w.x = cvt_pk_bf16(x0[0], x0[1]); w.y = cvt_pk_bf16(x0[2], x0[3]); w.z = cvt_pk_bf16(x1[0], x1[1]); w.w = cvt_pk_bf16(x1[2], x1[3]);
;                     *(u32x4*)(XB + ro + bj * 128) = w; }
;                 sq += __shfl_xor(sq, 16); sq += __shfl_xor(sq, 32);
;                 if (fq == 0) SSo[(size_t)(u.pn * 4 + wc) * T + row0 + ai * 128 + m * 16] = sq; }
.LBB0_1638:
	v_lshl_or_b32 v204, s34, 8, v222
	v_lshl_add_u32 v202, s52, 8, v220
	v_ashrrev_i32_e32 v205, 31, v204
	v_lshlrev_b64 v[236:237], 1, v[204:205]
	v_ashrrev_i32_e32 v203, 31, v202
	v_lshl_add_u64 v[96:97], s[36:37], 0, v[236:237]
	v_lshlrev_b64 v[238:239], 11, v[202:203]
	v_lshl_add_u64 v[98:99], v[96:97], 0, v[238:239]
	global_load_dwordx4 v[228:231], v[98:99], off
	global_load_dwordx4 v[232:235], v[98:99], off offset:256
	v_or_b32_e32 v98, 16, v202
	v_or_b32_e32 v108, 32, v202
	v_or_b32_e32 v110, 48, v202
	v_ashrrev_i32_e32 v99, 31, v98
	v_ashrrev_i32_e32 v109, 31, v108
	v_ashrrev_i32_e32 v111, 31, v110
	v_lshlrev_b64 v[218:219], 11, v[98:99]
	v_lshlrev_b64 v[216:217], 11, v[108:109]
	v_lshlrev_b64 v[214:215], 11, v[110:111]
	v_lshl_add_u64 v[212:213], v[238:239], 0, s[8:9]
	v_lshl_add_u64 v[210:211], v[238:239], 0, s[16:17]
	v_lshl_add_u64 v[208:209], v[238:239], 0, s[38:39]
	v_lshl_add_u64 v[206:207], v[238:239], 0, s[42:43]
	v_lshl_add_u64 v[98:99], v[96:97], 0, v[218:219]
	v_lshl_add_u64 v[108:109], v[96:97], 0, v[216:217]
	v_lshl_add_u64 v[110:111], v[96:97], 0, v[214:215]
	v_lshl_add_u64 v[120:121], v[96:97], 0, v[212:213]
	v_lshl_add_u64 v[122:123], v[96:97], 0, v[210:211]
	v_lshl_add_u64 v[240:241], v[96:97], 0, v[208:209]
	v_lshl_add_u64 v[96:97], v[96:97], 0, v[206:207]
	global_load_dwordx4 v[180:183], v[98:99], off
	global_load_dwordx4 v[176:179], v[98:99], off offset:256
	global_load_dwordx4 v[172:175], v[108:109], off
	global_load_dwordx4 v[168:171], v[108:109], off offset:256
	global_load_dwordx4 v[164:167], v[110:111], off
	global_load_dwordx4 v[160:163], v[110:111], off offset:256
	global_load_dwordx4 v[156:159], v[120:121], off
	global_load_dwordx4 v[152:155], v[120:121], off offset:256
	global_load_dwordx4 v[148:151], v[122:123], off
	global_load_dwordx4 v[144:147], v[122:123], off offset:256
	global_load_dwordx4 v[128:131], v[240:241], off
	s_nop 0
	global_load_dwordx4 v[120:123], v[240:241], off offset:256
	global_load_dwordx4 v[108:111], v[96:97], off
	s_nop 0
	global_load_dwordx4 v[96:99], v[96:97], off offset:256
	s_lshl_b32 s20, s34, 2
	s_or_b32 s20, s20, s65
	s_ashr_i32 s21, s20, 31
	s_lshl_b64 s[20:21], s[20:21], 17
	s_waitcnt vmcnt(0)
	v_lshlrev_b32_e32 v240, 16, v228
	v_and_b32_e32 v241, 0xffff0000, v228
	v_lshlrev_b32_e32 v228, 16, v229
	v_and_b32_e32 v229, 0xffff0000, v229
	v_lshlrev_b32_e32 v242, 16, v230
	v_and_b32_e32 v243, 0xffff0000, v230
	v_lshlrev_b32_e32 v244, 16, v232
	v_and_b32_e32 v245, 0xffff0000, v232
	v_lshlrev_b32_e32 v232, 16, v233
	v_and_b32_e32 v233, 0xffff0000, v233
	v_lshlrev_b32_e32 v246, 16, v234
	v_and_b32_e32 v247, 0xffff0000, v234
	v_lshlrev_b32_e32 v234, 16, v235
	v_and_b32_e32 v235, 0xffff0000, v235
	v_pk_add_f32 v[142:143], v[142:143], v[228:229]
	v_pk_add_f32 v[140:141], v[140:141], v[240:241]
	v_lshlrev_b32_e32 v230, 16, v231
	v_and_b32_e32 v231, 0xffff0000, v231
	v_pk_add_f32 v[136:137], v[136:137], v[242:243]
	v_pk_add_f32 v[228:229], v[134:135], v[232:233]
	v_pk_add_f32 v[232:233], v[126:127], v[234:235]
	v_pk_add_f32 v[234:235], v[124:125], v[246:247]
	v_mul_f32_e32 v124, v141, v141
	v_mul_f32_e32 v125, v143, v143
	v_pk_add_f32 v[138:139], v[138:139], v[230:231]
	v_pk_add_f32 v[230:231], v[132:133], v[244:245]
	v_mul_f32_e32 v126, v137, v137
	v_fmac_f32_e32 v124, v140, v140
	v_fmac_f32_e32 v125, v142, v142
	v_mul_f32_e32 v127, v139, v139
	v_cvt_pk_bf16_f32 v132, v140, v141
	v_cvt_pk_bf16_f32 v133, v142, v143
	v_cvt_pk_bf16_f32 v134, v136, v137
	v_cvt_pk_bf16_f32 v135, v138, v139
	v_mul_f32_e32 v137, v231, v231
	v_mul_f32_e32 v139, v229, v229
	v_fmac_f32_e32 v126, v136, v136
	v_add_f32_e32 v124, v124, v125
	v_fmac_f32_e32 v137, v230, v230
	v_fmac_f32_e32 v139, v228, v228
	v_add_f32_e32 v124, v126, v124
	v_mul_f32_e32 v126, v235, v235
	v_add_f32_e32 v125, v137, v139
	v_fmac_f32_e32 v126, v234, v234
	v_add_f32_e32 v125, v126, v125
	v_mul_f32_e32 v126, v233, v233
	v_fmac_f32_e32 v127, v138, v138
	v_fmac_f32_e32 v126, v232, v232
	v_add_f32_e32 v124, v127, v124
	v_add_f32_e32 v125, v126, v125
	v_and_b32_e32 v126, 64, v226
	v_add_f32_e32 v125, v124, v125
	v_add_u32_e32 v138, 64, v126
	v_lshl_add_u64 v[126:127], s[36:37], 0, v[238:239]
	v_lshl_add_u64 v[136:137], v[126:127], 0, v[236:237]
	v_mov_b32_e32 v139, v125
	s_nop 1
	v_permlane16_swap_b32_e32 v139, v125
	global_store_dwordx4 v[136:137], v[132:135], off
	s_waitcnt lgkmcnt(0)
	v_add_f32_e32 v126, v125, v139
	v_cvt_pk_bf16_f32 v132, v230, v231
	v_cvt_pk_bf16_f32 v133, v228, v229
	v_cvt_pk_bf16_f32 v134, v234, v235
	v_cvt_pk_bf16_f32 v135, v232, v233
	global_store_dwordx4 v[136:137], v[132:135], off offset:256
	s_nop 0
	v_mov_b32_e32 v127, v126
	s_nop 1
	v_permlane32_swap_b32_e32 v127, v126
	s_and_saveexec_b64 s[34:35], s[4:5]
	s_cbranch_execz .LBB0_1640
	s_add_u32 s54, s63, s20
	s_addc_u32 s55, s64, s21
	v_lshl_add_u64 v[132:133], v[202:203], 2, s[54:55]
	s_waitcnt lgkmcnt(0)
	v_add_f32_e32 v126, v126, v127
	global_store_dword v[132:133], v126, off

; __device__ __forceinline__ unsigned cvt_pk_bf16(float lo, float hi) { unsigned r; asm volatile("v_cvt_pk_bf16_f32 %0, %1, %2" : "=v"(r) : "v"(lo), "v"(hi)); return r; }
;     __device__ __forceinline__ void operator()(const f32x4 (&acc)[2][2][4][2], const pg8::Unit& u, int wr, int wc, int fr, int fq) const {
;         const int row0 = u.pm * 256 + wr * 64 + fr, col0 = u.pn * 256 + wc * 32 + 8 * fq;
;         u32x4 xin[2][4][2];
; #pragma unroll
;         for (int ai = 0; ai < 2; ++ai)
; #pragma unroll
;             for (int m = 0; m < 4; ++m)
; #pragma unroll
;                 for (int bj = 0; bj < 2; ++bj) xin[ai][m][bj] = *(const u32x4*)(XB + (size_t)(row0 + ai * 128 + m * 16) * D + col0 + bj * 128);
; #pragma unroll
;         for (int ai = 0; ai < 2; ++ai)
; #pragma unroll
;             for (int m = 0; m < 4; ++m) { const size_t ro = (size_t)(row0 + ai * 128 + m * 16) * D + col0; float sq = 0.f;
; #pragma unroll
;                 for (int bj = 0; bj < 2; ++bj) { const u32x4 xb = xin[ai][m][bj];
;                     const f32x4 x0 = (f32x4){bf_lo(xb.x), bf_hi(xb.x), bf_lo(xb.y), bf_hi(xb.y)} + acc[ai][bj][m][0] * s, x1 = (f32x4){bf_lo(xb.z), bf_hi(xb.z), bf_lo(xb.w), bf_hi(xb.w)} + acc[ai][bj][m][1] * s;
;                     sq += (x0[0] * x0[0] + x0[1] * x0[1]) + (x0[2] * x0[2] + x0[3] * x0[3]) + (x1[0] * x1[0] + x1[1] * x1[1]) + (x1[2] * x1[2] + x1[3] * x1[3]);
;                     u32x4 w; w.x = cvt_pk_bf16(x0[0], x0[1]); w.y = cvt_pk_bf16(x0[2], x0[3]); w.z = cvt_pk_bf16(x1[0], x1[1]); w.w = cvt_pk_bf16(x1[2], x1[3]);
;                     *(u32x4*)(XB + ro + bj * 128) = w; }
;                 sq += __shfl_xor(sq, 16); sq += __shfl_xor(sq, 32);
;                 if (fq == 0) SSo[(size_t)(u.pn * 4 + wc) * T + row0 + ai * 128 + m * 16] = sq; }
.LBB0_1828:
	v_lshl_or_b32 v204, s66, 8, v221
	v_lshl_add_u32 v202, s67, 8, v220
	v_ashrrev_i32_e32 v205, 31, v204
	v_lshlrev_b64 v[234:235], 1, v[204:205]
	v_ashrrev_i32_e32 v203, 31, v202
	v_lshl_add_u64 v[96:97], s[36:37], 0, v[234:235]
	v_lshlrev_b64 v[236:237], 11, v[202:203]
	v_lshl_add_u64 v[98:99], v[96:97], 0, v[236:237]
	global_load_dwordx4 v[226:229], v[98:99], off
	global_load_dwordx4 v[230:233], v[98:99], off offset:256
	v_or_b32_e32 v98, 16, v202
	v_or_b32_e32 v108, 32, v202
	v_or_b32_e32 v110, 48, v202
	v_ashrrev_i32_e32 v99, 31, v98
	v_ashrrev_i32_e32 v109, 31, v108
	v_ashrrev_i32_e32 v111, 31, v110
	v_lshlrev_b64 v[218:219], 11, v[98:99]
	v_lshlrev_b64 v[216:217], 11, v[108:109]
	v_lshlrev_b64 v[214:215], 11, v[110:111]
	v_lshl_add_u64 v[212:213], v[236:237], 0, s[16:17]
	v_lshl_add_u64 v[210:211], v[236:237], 0, s[18:19]
	v_lshl_add_u64 v[208:209], v[236:237], 0, s[38:39]
	v_lshl_add_u64 v[206:207], v[236:237], 0, s[42:43]
	v_lshl_add_u64 v[98:99], v[96:97], 0, v[218:219]
	v_lshl_add_u64 v[108:109], v[96:97], 0, v[216:217]
	v_lshl_add_u64 v[110:111], v[96:97], 0, v[214:215]
	v_lshl_add_u64 v[120:121], v[96:97], 0, v[212:213]
	v_lshl_add_u64 v[122:123], v[96:97], 0, v[210:211]
	v_lshl_add_u64 v[238:239], v[96:97], 0, v[208:209]
	v_lshl_add_u64 v[96:97], v[96:97], 0, v[206:207]
	global_load_dwordx4 v[180:183], v[98:99], off
	global_load_dwordx4 v[176:179], v[98:99], off offset:256
	global_load_dwordx4 v[172:175], v[108:109], off
	global_load_dwordx4 v[168:171], v[108:109], off offset:256
	global_load_dwordx4 v[164:167], v[110:111], off
	global_load_dwordx4 v[160:163], v[110:111], off offset:256
	global_load_dwordx4 v[156:159], v[120:121], off
	global_load_dwordx4 v[152:155], v[120:121], off offset:256
	global_load_dwordx4 v[148:151], v[122:123], off
	global_load_dwordx4 v[144:147], v[122:123], off offset:256
	global_load_dwordx4 v[128:131], v[238:239], off
	s_nop 0
	global_load_dwordx4 v[120:123], v[238:239], off offset:256
	global_load_dwordx4 v[108:111], v[96:97], off
	s_nop 0
	global_load_dwordx4 v[96:99], v[96:97], off offset:256
	s_lshl_b32 s20, s66, 2
	s_or_b32 s20, s20, s56
	s_ashr_i32 s21, s20, 31
	s_lshl_b64 s[20:21], s[20:21], 17
	s_waitcnt vmcnt(0)
	v_lshlrev_b32_e32 v238, 16, v226
	v_and_b32_e32 v239, 0xffff0000, v226
	v_lshlrev_b32_e32 v226, 16, v227
	v_and_b32_e32 v227, 0xffff0000, v227
	v_lshlrev_b32_e32 v240, 16, v228
	v_and_b32_e32 v241, 0xffff0000, v228
	v_lshlrev_b32_e32 v242, 16, v230
	v_and_b32_e32 v243, 0xffff0000, v230
	v_lshlrev_b32_e32 v230, 16, v231
	v_and_b32_e32 v231, 0xffff0000, v231
	v_lshlrev_b32_e32 v244, 16, v232
	v_and_b32_e32 v245, 0xffff0000, v232
	v_lshlrev_b32_e32 v232, 16, v233
	v_and_b32_e32 v233, 0xffff0000, v233
	v_pk_fma_f32 v[142:143], v[142:143], 0.5, v[226:227] op_sel_hi:[1,0,1]
	v_pk_fma_f32 v[140:141], v[140:141], 0.5, v[238:239] op_sel_hi:[1,0,1]
	v_lshlrev_b32_e32 v228, 16, v229
	v_and_b32_e32 v229, 0xffff0000, v229
	v_pk_fma_f32 v[136:137], v[136:137], 0.5, v[240:241] op_sel_hi:[1,0,1]
	v_pk_fma_f32 v[226:227], v[134:135], 0.5, v[230:231] op_sel_hi:[1,0,1]
	v_pk_fma_f32 v[230:231], v[126:127], 0.5, v[232:233] op_sel_hi:[1,0,1]
	v_pk_fma_f32 v[232:233], v[124:125], 0.5, v[244:245] op_sel_hi:[1,0,1]
	v_mul_f32_e32 v124, v141, v141
	v_mul_f32_e32 v125, v143, v143
	v_pk_fma_f32 v[138:139], v[138:139], 0.5, v[228:229] op_sel_hi:[1,0,1]
	v_pk_fma_f32 v[228:229], v[132:133], 0.5, v[242:243] op_sel_hi:[1,0,1]
	v_mul_f32_e32 v126, v137, v137
	v_fmac_f32_e32 v124, v140, v140
	v_fmac_f32_e32 v125, v142, v142
	v_mul_f32_e32 v127, v139, v139
	v_cvt_pk_bf16_f32 v132, v140, v141
	v_cvt_pk_bf16_f32 v133, v142, v143
	v_cvt_pk_bf16_f32 v134, v136, v137
	v_cvt_pk_bf16_f32 v135, v138, v139
	v_mul_f32_e32 v137, v229, v229
	v_mul_f32_e32 v139, v227, v227
	v_fmac_f32_e32 v126, v136, v136
	v_add_f32_e32 v124, v124, v125
	v_fmac_f32_e32 v137, v228, v228
	v_fmac_f32_e32 v139, v226, v226
	v_add_f32_e32 v124, v126, v124
	v_mul_f32_e32 v126, v233, v233
	v_add_f32_e32 v125, v137, v139
	v_fmac_f32_e32 v126, v232, v232
	v_add_f32_e32 v125, v126, v125
	v_mul_f32_e32 v126, v231, v231
	v_fmac_f32_e32 v127, v138, v138
	v_fmac_f32_e32 v126, v230, v230
	v_add_f32_e32 v124, v127, v124
	v_add_f32_e32 v125, v126, v125
	v_and_b32_e32 v126, 64, v225
	v_add_f32_e32 v125, v124, v125
	v_add_u32_e32 v138, 64, v126
	v_lshl_add_u64 v[126:127], s[36:37], 0, v[236:237]
	v_lshl_add_u64 v[136:137], v[126:127], 0, v[234:235]
	v_mov_b32_e32 v139, v125
	s_nop 1
	v_permlane16_swap_b32_e32 v139, v125
	global_store_dwordx4 v[136:137], v[132:135], off
	s_waitcnt lgkmcnt(0)
	v_add_f32_e32 v126, v125, v139
	v_cvt_pk_bf16_f32 v132, v228, v229
	v_cvt_pk_bf16_f32 v133, v226, v227
	v_cvt_pk_bf16_f32 v134, v232, v233
	v_cvt_pk_bf16_f32 v135, v230, v231
	global_store_dwordx4 v[136:137], v[132:135], off offset:256
	s_nop 0
	v_mov_b32_e32 v127, v126
	s_nop 1
	v_permlane32_swap_b32_e32 v127, v126
	s_and_saveexec_b64 s[34:35], s[4:5]
	s_cbranch_execz .LBB0_1830
	s_add_u32 s46, s54, s20
	s_addc_u32 s47, s55, s21
	v_lshl_add_u64 v[132:133], v[202:203], 2, s[46:47]
	s_waitcnt lgkmcnt(0)
	v_add_f32_e32 v126, v126, v127
	global_store_dword v[132:133], v126, off
; __device__ __forceinline__ unsigned cvt_pk_bf16(float lo, float hi) { unsigned r; asm volatile("v_cvt_pk_bf16_f32 %0, %1, %2" : "=v"(r) : "v"(lo), "v"(hi)); return r; }
;     __device__ __forceinline__ void operator()(const f32x4 (&acc)[2][2][4][2], const pg8::Unit& u, int wr, int wc, int fr, int fq) const {
;     ...
;             for (int m = 0; m < 4; ++m) { const size_t ro = (size_t)(row0 + ai * 128 + m * 16) * D + col0; float sq = 0.f;
; #pragma unroll
;                 for (int bj = 0; bj < 2; ++bj) { const u32x4 xb = xin[ai][m][bj];
;                     const f32x4 x0 = (f32x4){bf_lo(xb.x), bf_hi(xb.x), bf_lo(xb.y), bf_hi(xb.y)} + acc[ai][bj][m][0] * s, x1 = (f32x4){bf_lo(xb.z), bf_hi(xb.z), bf_lo(xb.w), bf_hi(xb.w)} + acc[ai][bj][m][1] * s;
;                     sq += (x0[0] * x0[0] + x0[1] * x0[1]) + (x0[2] * x0[2] + x0[3] * x0[3]) + (x1[0] * x1[0] + x1[1] * x1[1]) + (x1[2] * x1[2] + x1[3] * x1[3]);
;                     u32x4 w; w.x = cvt_pk_bf16(x0[0], x0[1]); w.y = cvt_pk_bf16(x0[2], x0[3]); w.z = cvt_pk_bf16(x1[0], x1[1]); w.w = cvt_pk_bf16(x1[2], x1[3]);
;                     *(u32x4*)(XB + ro + bj * 128) = w; }
;                 sq += __shfl_xor(sq, 16); sq += __shfl_xor(sq, 32);
;                 if (fq == 0) SSo[(size_t)(u.pn * 4 + wc) * T + row0 + ai * 128 + m * 16] = sq; }
.LBB0_1830:
	s_or_b64 exec, exec, s[34:35]
	v_lshlrev_b32_e32 v126, 16, v180
	s_waitcnt lgkmcnt(0)
	v_and_b32_e32 v127, 0xffff0000, v180
	v_lshlrev_b32_e32 v132, 16, v181
	v_and_b32_e32 v133, 0xffff0000, v181
	v_pk_fma_f32 v[118:119], v[118:119], 0.5, v[132:133] op_sel_hi:[1,0,1]
	v_pk_fma_f32 v[116:117], v[116:117], 0.5, v[126:127] op_sel_hi:[1,0,1]
	v_lshlrev_b32_e32 v126, 16, v182
	v_and_b32_e32 v127, 0xffff0000, v182
	v_lshlrev_b32_e32 v132, 16, v183
	v_and_b32_e32 v133, 0xffff0000, v183
	v_pk_fma_f32 v[132:133], v[114:115], 0.5, v[132:133] op_sel_hi:[1,0,1]
	v_pk_fma_f32 v[114:115], v[112:113], 0.5, v[126:127] op_sel_hi:[1,0,1]
	v_mul_f32_e32 v112, v117, v117
	v_mul_f32_e32 v113, v119, v119
	v_fmac_f32_e32 v112, v116, v116
	v_fmac_f32_e32 v113, v118, v118
	v_add_f32_e32 v112, v112, v113
	v_mul_f32_e32 v113, v115, v115
	v_fmac_f32_e32 v113, v114, v114
	v_add_f32_e32 v112, v113, v112
	v_mul_f32_e32 v113, v133, v133
	v_fmac_f32_e32 v113, v132, v132
	v_add_f32_e32 v126, v113, v112
	v_cvt_pk_bf16_f32 v112, v116, v117
	v_cvt_pk_bf16_f32 v113, v118, v119
	v_lshlrev_b32_e32 v116, 16, v176
	v_and_b32_e32 v117, 0xffff0000, v176
	v_lshlrev_b32_e32 v118, 16, v177
	v_and_b32_e32 v119, 0xffff0000, v177
	v_pk_fma_f32 v[106:107], v[106:107], 0.5, v[118:119] op_sel_hi:[1,0,1]
	v_pk_fma_f32 v[104:105], v[104:105], 0.5, v[116:117] op_sel_hi:[1,0,1]
	v_lshlrev_b32_e32 v116, 16, v178
	v_and_b32_e32 v117, 0xffff0000, v178
	v_pk_fma_f32 v[116:117], v[100:101], 0.5, v[116:117] op_sel_hi:[1,0,1]
	v_mul_f32_e32 v100, v105, v105
	v_mul_f32_e32 v101, v107, v107
	v_fmac_f32_e32 v100, v104, v104
	v_fmac_f32_e32 v101, v106, v106
	v_lshlrev_b32_e32 v118, 16, v179
	v_and_b32_e32 v119, 0xffff0000, v179
	v_add_f32_e32 v100, v100, v101
	v_mul_f32_e32 v101, v117, v117
	v_pk_fma_f32 v[118:119], v[102:103], 0.5, v[118:119] op_sel_hi:[1,0,1]
	v_fmac_f32_e32 v101, v116, v116
	v_add_f32_e32 v100, v101, v100
	v_mul_f32_e32 v101, v119, v119
	v_fmac_f32_e32 v101, v118, v118
	v_add_f32_e32 v100, v101, v100
	v_add_f32_e32 v103, v126, v100
	v_cvt_pk_bf16_f32 v114, v114, v115
	v_cvt_pk_bf16_f32 v115, v132, v133
	v_mov_b32_e32 v132, v103
	s_nop 1
	v_permlane16_swap_b32_e32 v132, v103
	v_lshl_add_u64 v[100:101], s[36:37], 0, v[218:219]
	v_lshl_add_u64 v[126:127], v[204:205], 1, v[100:101]
	global_store_dwordx4 v[126:127], v[112:115], off
	v_cvt_pk_bf16_f32 v102, v104, v105
	s_waitcnt lgkmcnt(0)
	v_add_f32_e32 v100, v103, v132
	v_mov_b32_e32 v101, v100
	s_nop 1
	v_permlane32_swap_b32_e32 v101, v100
	v_cvt_pk_bf16_f32 v103, v106, v107
	v_cvt_pk_bf16_f32 v104, v116, v117
	v_cvt_pk_bf16_f32 v105, v118, v119
	global_store_dwordx4 v[126:127], v[102:105], off offset:256
	s_and_saveexec_b64 s[34:35], s[4:5]
	s_cbranch_execz .LBB0_1832
	s_add_u32 s46, s54, s20
	s_addc_u32 s47, s55, s21
	v_lshl_add_u64 v[102:103], v[202:203], 2, s[46:47]
	s_waitcnt lgkmcnt(0)
	v_add_f32_e32 v100, v100, v101
	global_store_dword v[102:103], v100, off offset:64
.LBB0_1832:
	s_or_b64 exec, exec, s[34:35]
	v_lshlrev_b32_e32 v100, 16, v172
	s_waitcnt lgkmcnt(0)
	v_and_b32_e32 v101, 0xffff0000, v172
	v_lshlrev_b32_e32 v102, 16, v173
	v_and_b32_e32 v103, 0xffff0000, v173
	v_pk_fma_f32 v[94:95], v[94:95], 0.5, v[102:103] op_sel_hi:[1,0,1]
	v_pk_fma_f32 v[92:93], v[92:93], 0.5, v[100:101] op_sel_hi:[1,0,1]
	v_lshlrev_b32_e32 v100, 16, v174
	v_and_b32_e32 v101, 0xffff0000, v174
	v_lshlrev_b32_e32 v102, 16, v175
	v_and_b32_e32 v103, 0xffff0000, v175
	v_pk_fma_f32 v[102:103], v[90:91], 0.5, v[102:103] op_sel_hi:[1,0,1]
	v_pk_fma_f32 v[90:91], v[88:89], 0.5, v[100:101] op_sel_hi:[1,0,1]
	v_mul_f32_e32 v88, v93, v93
	v_mul_f32_e32 v89, v95, v95
	v_fmac_f32_e32 v88, v92, v92
	v_fmac_f32_e32 v89, v94, v94
	v_add_f32_e32 v88, v88, v89
	v_mul_f32_e32 v89, v91, v91
	v_fmac_f32_e32 v89, v90, v90
	v_add_f32_e32 v88, v89, v88
	v_mul_f32_e32 v89, v103, v103
	v_fmac_f32_e32 v89, v102, v102
	v_add_f32_e32 v100, v89, v88
	v_cvt_pk_bf16_f32 v88, v92, v93
	v_cvt_pk_bf16_f32 v89, v94, v95
	v_lshlrev_b32_e32 v92, 16, v168
	v_and_b32_e32 v93, 0xffff0000, v168
	v_lshlrev_b32_e32 v94, 16, v169
	v_and_b32_e32 v95, 0xffff0000, v169
	v_pk_fma_f32 v[86:87], v[86:87], 0.5, v[94:95] op_sel_hi:[1,0,1]
	v_pk_fma_f32 v[84:85], v[84:85], 0.5, v[92:93] op_sel_hi:[1,0,1]
	v_lshlrev_b32_e32 v92, 16, v170
	v_and_b32_e32 v93, 0xffff0000, v170
	v_pk_fma_f32 v[92:93], v[80:81], 0.5, v[92:93] op_sel_hi:[1,0,1]
	v_mul_f32_e32 v80, v85, v85
	v_mul_f32_e32 v81, v87, v87
	v_fmac_f32_e32 v80, v84, v84
	v_fmac_f32_e32 v81, v86, v86
	v_lshlrev_b32_e32 v94, 16, v171
	v_and_b32_e32 v95, 0xffff0000, v171
	v_add_f32_e32 v80, v80, v81
	v_mul_f32_e32 v81, v93, v93
	v_pk_fma_f32 v[94:95], v[82:83], 0.5, v[94:95] op_sel_hi:[1,0,1]
	v_fmac_f32_e32 v81, v92, v92
	v_add_f32_e32 v80, v81, v80
	v_mul_f32_e32 v81, v95, v95
	v_fmac_f32_e32 v81, v94, v94
	v_add_f32_e32 v80, v81, v80
	v_add_f32_e32 v83, v100, v80
	v_cvt_pk_bf16_f32 v90, v90, v91
	v_cvt_pk_bf16_f32 v91, v102, v103
	v_mov_b32_e32 v102, v83
	s_nop 1
	v_permlane16_swap_b32_e32 v102, v83
	v_lshl_add_u64 v[80:81], s[36:37], 0, v[216:217]
	v_lshl_add_u64 v[100:101], v[204:205], 1, v[80:81]
	global_store_dwordx4 v[100:101], v[88:91], off
	v_cvt_pk_bf16_f32 v82, v84, v85
	s_waitcnt lgkmcnt(0)
	v_add_f32_e32 v80, v83, v102
	v_mov_b32_e32 v81, v80
	s_nop 1
	v_permlane32_swap_b32_e32 v81, v80
	v_cvt_pk_bf16_f32 v83, v86, v87
	v_cvt_pk_bf16_f32 v84, v92, v93
	v_cvt_pk_bf16_f32 v85, v94, v95
	global_store_dwordx4 v[100:101], v[82:85], off offset:256
	s_and_saveexec_b64 s[34:35], s[4:5]
	s_cbranch_execz .LBB0_1834
	s_add_u32 s46, s54, s20
	s_addc_u32 s47, s55, s21
	v_lshl_add_u64 v[82:83], v[202:203], 2, s[46:47]
	s_waitcnt lgkmcnt(0)
	v_add_f32_e32 v80, v80, v81
	global_store_dword v[82:83], v80, off offset:128
; __device__ __forceinline__ unsigned cvt_pk_bf16(float lo, float hi) { unsigned r; asm volatile("v_cvt_pk_bf16_f32 %0, %1, %2" : "=v"(r) : "v"(lo), "v"(hi)); return r; }
;     __device__ __forceinline__ void operator()(const f32x4 (&acc)[2][2][4][2], const pg8::Unit& u, int wr, int wc, int fr, int fq) const {
;     ...
;             for (int m = 0; m < 4; ++m) { const size_t ro = (size_t)(row0 + ai * 128 + m * 16) * D + col0; float sq = 0.f;
; #pragma unroll
;                 for (int bj = 0; bj < 2; ++bj) { const u32x4 xb = xin[ai][m][bj];
;                     const f32x4 x0 = (f32x4){bf_lo(xb.x), bf_hi(xb.x), bf_lo(xb.y), bf_hi(xb.y)} + acc[ai][bj][m][0] * s, x1 = (f32x4){bf_lo(xb.z), bf_hi(xb.z), bf_lo(xb.w), bf_hi(xb.w)} + acc[ai][bj][m][1] * s;
;                     sq += (x0[0] * x0[0] + x0[1] * x0[1]) + (x0[2] * x0[2] + x0[3] * x0[3]) + (x1[0] * x1[0] + x1[1] * x1[1]) + (x1[2] * x1[2] + x1[3] * x1[3]);
;                     u32x4 w; w.x = cvt_pk_bf16(x0[0], x0[1]); w.y = cvt_pk_bf16(x0[2], x0[3]); w.z = cvt_pk_bf16(x1[0], x1[1]); w.w = cvt_pk_bf16(x1[2], x1[3]);
;                     *(u32x4*)(XB + ro + bj * 128) = w; }
;                 sq += __shfl_xor(sq, 16); sq += __shfl_xor(sq, 32);
;                 if (fq == 0) SSo[(size_t)(u.pn * 4 + wc) * T + row0 + ai * 128 + m * 16] = sq; }
.LBB0_1834:
	s_or_b64 exec, exec, s[34:35]
	v_lshlrev_b32_e32 v80, 16, v164
	s_waitcnt lgkmcnt(0)
	v_and_b32_e32 v81, 0xffff0000, v164
	v_lshlrev_b32_e32 v82, 16, v165
	v_and_b32_e32 v83, 0xffff0000, v165
	v_pk_fma_f32 v[78:79], v[78:79], 0.5, v[82:83] op_sel_hi:[1,0,1]
	v_pk_fma_f32 v[76:77], v[76:77], 0.5, v[80:81] op_sel_hi:[1,0,1]
	v_lshlrev_b32_e32 v80, 16, v166
	v_and_b32_e32 v81, 0xffff0000, v166
	v_lshlrev_b32_e32 v82, 16, v167
	v_and_b32_e32 v83, 0xffff0000, v167
	v_pk_fma_f32 v[82:83], v[74:75], 0.5, v[82:83] op_sel_hi:[1,0,1]
	v_pk_fma_f32 v[74:75], v[72:73], 0.5, v[80:81] op_sel_hi:[1,0,1]
	v_mul_f32_e32 v72, v77, v77
	v_mul_f32_e32 v73, v79, v79
	v_fmac_f32_e32 v72, v76, v76
	v_fmac_f32_e32 v73, v78, v78
	v_add_f32_e32 v72, v72, v73
	v_mul_f32_e32 v73, v75, v75
	v_fmac_f32_e32 v73, v74, v74
	v_add_f32_e32 v72, v73, v72
	v_mul_f32_e32 v73, v83, v83
	v_fmac_f32_e32 v73, v82, v82
	v_add_f32_e32 v80, v73, v72
	v_cvt_pk_bf16_f32 v72, v76, v77
	v_cvt_pk_bf16_f32 v73, v78, v79
	v_lshlrev_b32_e32 v76, 16, v160
	v_and_b32_e32 v77, 0xffff0000, v160
	v_lshlrev_b32_e32 v78, 16, v161
	v_and_b32_e32 v79, 0xffff0000, v161
	v_pk_fma_f32 v[70:71], v[70:71], 0.5, v[78:79] op_sel_hi:[1,0,1]
	v_pk_fma_f32 v[68:69], v[68:69], 0.5, v[76:77] op_sel_hi:[1,0,1]
	v_lshlrev_b32_e32 v76, 16, v162
	v_and_b32_e32 v77, 0xffff0000, v162
	v_pk_fma_f32 v[76:77], v[64:65], 0.5, v[76:77] op_sel_hi:[1,0,1]
	v_mul_f32_e32 v64, v69, v69
	v_mul_f32_e32 v65, v71, v71
	v_fmac_f32_e32 v64, v68, v68
	v_fmac_f32_e32 v65, v70, v70
	v_lshlrev_b32_e32 v78, 16, v163
	v_and_b32_e32 v79, 0xffff0000, v163
	v_add_f32_e32 v64, v64, v65
	v_mul_f32_e32 v65, v77, v77
	v_pk_fma_f32 v[78:79], v[66:67], 0.5, v[78:79] op_sel_hi:[1,0,1]
	v_fmac_f32_e32 v65, v76, v76
	v_add_f32_e32 v64, v65, v64
	v_mul_f32_e32 v65, v79, v79
	v_fmac_f32_e32 v65, v78, v78
	v_add_f32_e32 v64, v65, v64
	v_add_f32_e32 v67, v80, v64
	v_cvt_pk_bf16_f32 v74, v74, v75
	v_cvt_pk_bf16_f32 v75, v82, v83
	v_mov_b32_e32 v82, v67
	s_nop 1
	v_permlane16_swap_b32_e32 v82, v67
	v_lshl_add_u64 v[64:65], s[36:37], 0, v[214:215]
	v_lshl_add_u64 v[80:81], v[204:205], 1, v[64:65]
	global_store_dwordx4 v[80:81], v[72:75], off
	v_cvt_pk_bf16_f32 v66, v68, v69
	s_waitcnt lgkmcnt(0)
	v_add_f32_e32 v64, v67, v82
	v_mov_b32_e32 v65, v64
	s_nop 1
	v_permlane32_swap_b32_e32 v65, v64
	v_cvt_pk_bf16_f32 v67, v70, v71
	v_cvt_pk_bf16_f32 v68, v76, v77
	v_cvt_pk_bf16_f32 v69, v78, v79
	global_store_dwordx4 v[80:81], v[66:69], off offset:256
	s_and_saveexec_b64 s[34:35], s[4:5]
	s_cbranch_execz .LBB0_1836
	s_add_u32 s46, s54, s20
	s_addc_u32 s47, s55, s21
	v_lshl_add_u64 v[66:67], v[202:203], 2, s[46:47]
	s_waitcnt lgkmcnt(0)
	v_add_f32_e32 v64, v64, v65
	global_store_dword v[66:67], v64, off offset:192
.LBB0_1836:
	s_or_b64 exec, exec, s[34:35]
	v_lshlrev_b32_e32 v64, 16, v156
	s_waitcnt lgkmcnt(0)
	v_and_b32_e32 v65, 0xffff0000, v156
	v_lshlrev_b32_e32 v66, 16, v157
	v_and_b32_e32 v67, 0xffff0000, v157
	v_pk_fma_f32 v[62:63], v[62:63], 0.5, v[66:67] op_sel_hi:[1,0,1]
	v_pk_fma_f32 v[60:61], v[60:61], 0.5, v[64:65] op_sel_hi:[1,0,1]
	v_lshlrev_b32_e32 v64, 16, v158
	v_and_b32_e32 v65, 0xffff0000, v158
	v_lshlrev_b32_e32 v66, 16, v159
	v_and_b32_e32 v67, 0xffff0000, v159
	v_pk_fma_f32 v[66:67], v[58:59], 0.5, v[66:67] op_sel_hi:[1,0,1]
	v_pk_fma_f32 v[58:59], v[56:57], 0.5, v[64:65] op_sel_hi:[1,0,1]
	v_mul_f32_e32 v56, v61, v61
	v_mul_f32_e32 v57, v63, v63
	v_fmac_f32_e32 v56, v60, v60
	v_fmac_f32_e32 v57, v62, v62
	v_add_f32_e32 v56, v56, v57
	v_mul_f32_e32 v57, v59, v59
	v_fmac_f32_e32 v57, v58, v58
	v_add_f32_e32 v56, v57, v56
	v_mul_f32_e32 v57, v67, v67
	v_fmac_f32_e32 v57, v66, v66
	v_add_f32_e32 v64, v57, v56
	v_cvt_pk_bf16_f32 v56, v60, v61
	v_cvt_pk_bf16_f32 v57, v62, v63
	v_lshlrev_b32_e32 v60, 16, v152
	v_and_b32_e32 v61, 0xffff0000, v152
	v_lshlrev_b32_e32 v62, 16, v153
	v_and_b32_e32 v63, 0xffff0000, v153
	v_pk_fma_f32 v[54:55], v[54:55], 0.5, v[62:63] op_sel_hi:[1,0,1]
	v_pk_fma_f32 v[52:53], v[52:53], 0.5, v[60:61] op_sel_hi:[1,0,1]
	v_lshlrev_b32_e32 v60, 16, v154
	v_and_b32_e32 v61, 0xffff0000, v154
	v_pk_fma_f32 v[60:61], v[48:49], 0.5, v[60:61] op_sel_hi:[1,0,1]
	v_mul_f32_e32 v48, v53, v53
	v_mul_f32_e32 v49, v55, v55
	v_fmac_f32_e32 v48, v52, v52
	v_fmac_f32_e32 v49, v54, v54
	v_lshlrev_b32_e32 v62, 16, v155
	v_and_b32_e32 v63, 0xffff0000, v155
	v_add_f32_e32 v48, v48, v49
	v_mul_f32_e32 v49, v61, v61
	v_pk_fma_f32 v[62:63], v[50:51], 0.5, v[62:63] op_sel_hi:[1,0,1]
	v_fmac_f32_e32 v49, v60, v60
	v_add_f32_e32 v48, v49, v48
	v_mul_f32_e32 v49, v63, v63
	v_fmac_f32_e32 v49, v62, v62
	v_add_f32_e32 v48, v49, v48
	v_add_f32_e32 v51, v64, v48
	v_cvt_pk_bf16_f32 v58, v58, v59
	v_cvt_pk_bf16_f32 v59, v66, v67
	v_mov_b32_e32 v66, v51
	s_nop 1
	v_permlane16_swap_b32_e32 v66, v51
	v_lshl_add_u64 v[48:49], s[36:37], 0, v[212:213]
	v_lshl_add_u64 v[64:65], v[204:205], 1, v[48:49]
	global_store_dwordx4 v[64:65], v[56:59], off
	v_cvt_pk_bf16_f32 v50, v52, v53
	s_waitcnt lgkmcnt(0)
	v_add_f32_e32 v48, v51, v66
	v_mov_b32_e32 v49, v48
	s_nop 1
	v_permlane32_swap_b32_e32 v49, v48
	v_cvt_pk_bf16_f32 v51, v54, v55
	v_cvt_pk_bf16_f32 v52, v60, v61
	v_cvt_pk_bf16_f32 v53, v62, v63
	global_store_dwordx4 v[64:65], v[50:53], off offset:256
	s_and_saveexec_b64 s[34:35], s[4:5]
	s_cbranch_execz .LBB0_1838
	s_add_u32 s46, s54, s20
	s_addc_u32 s47, s55, s21
	v_lshl_add_u64 v[50:51], v[202:203], 2, s[46:47]
	s_waitcnt lgkmcnt(0)
	v_add_f32_e32 v48, v48, v49
	global_store_dword v[50:51], v48, off offset:512
; __device__ __forceinline__ unsigned cvt_pk_bf16(float lo, float hi) { unsigned r; asm volatile("v_cvt_pk_bf16_f32 %0, %1, %2" : "=v"(r) : "v"(lo), "v"(hi)); return r; }
;     __device__ __forceinline__ void operator()(const f32x4 (&acc)[2][2][4][2], const pg8::Unit& u, int wr, int wc, int fr, int fq) const {
;     ...
;             for (int m = 0; m < 4; ++m) { const size_t ro = (size_t)(row0 + ai * 128 + m * 16) * D + col0; float sq = 0.f;
; #pragma unroll
;                 for (int bj = 0; bj < 2; ++bj) { const u32x4 xb = xin[ai][m][bj];
;                     const f32x4 x0 = (f32x4){bf_lo(xb.x), bf_hi(xb.x), bf_lo(xb.y), bf_hi(xb.y)} + acc[ai][bj][m][0] * s, x1 = (f32x4){bf_lo(xb.z), bf_hi(xb.z), bf_lo(xb.w), bf_hi(xb.w)} + acc[ai][bj][m][1] * s;
;                     sq += (x0[0] * x0[0] + x0[1] * x0[1]) + (x0[2] * x0[2] + x0[3] * x0[3]) + (x1[0] * x1[0] + x1[1] * x1[1]) + (x1[2] * x1[2] + x1[3] * x1[3]);
;                     u32x4 w; w.x = cvt_pk_bf16(x0[0], x0[1]); w.y = cvt_pk_bf16(x0[2], x0[3]); w.z = cvt_pk_bf16(x1[0], x1[1]); w.w = cvt_pk_bf16(x1[2], x1[3]);
;                     *(u32x4*)(XB + ro + bj * 128) = w; }
;                 sq += __shfl_xor(sq, 16); sq += __shfl_xor(sq, 32);
;                 if (fq == 0) SSo[(size_t)(u.pn * 4 + wc) * T + row0 + ai * 128 + m * 16] = sq; }
.LBB0_1838:
	s_or_b64 exec, exec, s[34:35]
	v_lshlrev_b32_e32 v48, 16, v148
	s_waitcnt lgkmcnt(0)
	v_and_b32_e32 v49, 0xffff0000, v148
	v_lshlrev_b32_e32 v50, 16, v149
	v_and_b32_e32 v51, 0xffff0000, v149
	v_pk_fma_f32 v[46:47], v[46:47], 0.5, v[50:51] op_sel_hi:[1,0,1]
	v_pk_fma_f32 v[44:45], v[44:45], 0.5, v[48:49] op_sel_hi:[1,0,1]
	v_lshlrev_b32_e32 v48, 16, v150
	v_and_b32_e32 v49, 0xffff0000, v150
	v_lshlrev_b32_e32 v50, 16, v151
	v_and_b32_e32 v51, 0xffff0000, v151
	v_pk_fma_f32 v[50:51], v[42:43], 0.5, v[50:51] op_sel_hi:[1,0,1]
	v_pk_fma_f32 v[42:43], v[40:41], 0.5, v[48:49] op_sel_hi:[1,0,1]
	v_mul_f32_e32 v40, v45, v45
	v_mul_f32_e32 v41, v47, v47
	v_fmac_f32_e32 v40, v44, v44
	v_fmac_f32_e32 v41, v46, v46
	v_add_f32_e32 v40, v40, v41
	v_mul_f32_e32 v41, v43, v43
	v_fmac_f32_e32 v41, v42, v42
	v_add_f32_e32 v40, v41, v40
	v_mul_f32_e32 v41, v51, v51
	v_fmac_f32_e32 v41, v50, v50
	v_add_f32_e32 v48, v41, v40
	v_cvt_pk_bf16_f32 v40, v44, v45
	v_cvt_pk_bf16_f32 v41, v46, v47
	v_lshlrev_b32_e32 v44, 16, v144
	v_and_b32_e32 v45, 0xffff0000, v144
	v_lshlrev_b32_e32 v46, 16, v145
	v_and_b32_e32 v47, 0xffff0000, v145
	v_pk_fma_f32 v[38:39], v[38:39], 0.5, v[46:47] op_sel_hi:[1,0,1]
	v_pk_fma_f32 v[36:37], v[36:37], 0.5, v[44:45] op_sel_hi:[1,0,1]
	v_lshlrev_b32_e32 v44, 16, v146
	v_and_b32_e32 v45, 0xffff0000, v146
	v_pk_fma_f32 v[44:45], v[32:33], 0.5, v[44:45] op_sel_hi:[1,0,1]
	v_mul_f32_e32 v32, v37, v37
	v_mul_f32_e32 v33, v39, v39
	v_fmac_f32_e32 v32, v36, v36
	v_fmac_f32_e32 v33, v38, v38
	v_lshlrev_b32_e32 v46, 16, v147
	v_and_b32_e32 v47, 0xffff0000, v147
	v_add_f32_e32 v32, v32, v33
	v_mul_f32_e32 v33, v45, v45
	v_pk_fma_f32 v[46:47], v[34:35], 0.5, v[46:47] op_sel_hi:[1,0,1]
	v_fmac_f32_e32 v33, v44, v44
	v_add_f32_e32 v32, v33, v32
	v_mul_f32_e32 v33, v47, v47
	v_fmac_f32_e32 v33, v46, v46
	v_add_f32_e32 v32, v33, v32
	v_add_f32_e32 v35, v48, v32
	v_cvt_pk_bf16_f32 v42, v42, v43
	v_cvt_pk_bf16_f32 v43, v50, v51
	v_mov_b32_e32 v50, v35
	s_nop 1
	v_permlane16_swap_b32_e32 v50, v35
	v_lshl_add_u64 v[32:33], s[36:37], 0, v[210:211]
	v_lshl_add_u64 v[48:49], v[204:205], 1, v[32:33]
	global_store_dwordx4 v[48:49], v[40:43], off
	v_cvt_pk_bf16_f32 v34, v36, v37
	s_waitcnt lgkmcnt(0)
	v_add_f32_e32 v32, v35, v50
	v_mov_b32_e32 v33, v32
	s_nop 1
	v_permlane32_swap_b32_e32 v33, v32
	v_cvt_pk_bf16_f32 v35, v38, v39
	v_cvt_pk_bf16_f32 v36, v44, v45
	v_cvt_pk_bf16_f32 v37, v46, v47
	global_store_dwordx4 v[48:49], v[34:37], off offset:256
	s_and_saveexec_b64 s[34:35], s[4:5]
	s_cbranch_execz .LBB0_1840
	s_add_u32 s46, s54, s20
	s_addc_u32 s47, s55, s21
	v_lshl_add_u64 v[34:35], v[202:203], 2, s[46:47]
	s_waitcnt lgkmcnt(0)
	v_add_f32_e32 v32, v32, v33
	global_store_dword v[34:35], v32, off offset:576
; __device__ __forceinline__ unsigned cvt_pk_bf16(float lo, float hi) { unsigned r; asm volatile("v_cvt_pk_bf16_f32 %0, %1, %2" : "=v"(r) : "v"(lo), "v"(hi)); return r; }
;     __device__ __forceinline__ void operator()(const f32x4 (&acc)[2][2][4][2], const pg8::Unit& u, int wr, int wc, int fr, int fq) const {
;     ...
;             for (int m = 0; m < 4; ++m) { const size_t ro = (size_t)(row0 + ai * 128 + m * 16) * D + col0; float sq = 0.f;
; #pragma unroll
;                 for (int bj = 0; bj < 2; ++bj) { const u32x4 xb = xin[ai][m][bj];
;                     const f32x4 x0 = (f32x4){bf_lo(xb.x), bf_hi(xb.x), bf_lo(xb.y), bf_hi(xb.y)} + acc[ai][bj][m][0] * s, x1 = (f32x4){bf_lo(xb.z), bf_hi(xb.z), bf_lo(xb.w), bf_hi(xb.w)} + acc[ai][bj][m][1] * s;
;                     sq += (x0[0] * x0[0] + x0[1] * x0[1]) + (x0[2] * x0[2] + x0[3] * x0[3]) + (x1[0] * x1[0] + x1[1] * x1[1]) + (x1[2] * x1[2] + x1[3] * x1[3]);
;                     u32x4 w; w.x = cvt_pk_bf16(x0[0], x0[1]); w.y = cvt_pk_bf16(x0[2], x0[3]); w.z = cvt_pk_bf16(x1[0], x1[1]); w.w = cvt_pk_bf16(x1[2], x1[3]);
;                     *(u32x4*)(XB + ro + bj * 128) = w; }
;                 sq += __shfl_xor(sq, 16); sq += __shfl_xor(sq, 32);
;                 if (fq == 0) SSo[(size_t)(u.pn * 4 + wc) * T + row0 + ai * 128 + m * 16] = sq; }
.LBB0_1840:
	s_or_b64 exec, exec, s[34:35]
	v_lshlrev_b32_e32 v32, 16, v128
	s_waitcnt lgkmcnt(0)
	v_and_b32_e32 v33, 0xffff0000, v128
	v_lshlrev_b32_e32 v34, 16, v129
	v_and_b32_e32 v35, 0xffff0000, v129
	v_pk_fma_f32 v[30:31], v[30:31], 0.5, v[34:35] op_sel_hi:[1,0,1]
	v_pk_fma_f32 v[28:29], v[28:29], 0.5, v[32:33] op_sel_hi:[1,0,1]
	v_lshlrev_b32_e32 v32, 16, v130
	v_and_b32_e32 v33, 0xffff0000, v130
	v_lshlrev_b32_e32 v34, 16, v131
	v_and_b32_e32 v35, 0xffff0000, v131
	v_pk_fma_f32 v[34:35], v[26:27], 0.5, v[34:35] op_sel_hi:[1,0,1]
	v_pk_fma_f32 v[26:27], v[24:25], 0.5, v[32:33] op_sel_hi:[1,0,1]
	v_mul_f32_e32 v24, v29, v29
	v_mul_f32_e32 v25, v31, v31
	v_fmac_f32_e32 v24, v28, v28
	v_fmac_f32_e32 v25, v30, v30
	v_add_f32_e32 v24, v24, v25
	v_mul_f32_e32 v25, v27, v27
	v_fmac_f32_e32 v25, v26, v26
	v_add_f32_e32 v24, v25, v24
	v_mul_f32_e32 v25, v35, v35
	v_fmac_f32_e32 v25, v34, v34
	v_add_f32_e32 v32, v25, v24
	v_cvt_pk_bf16_f32 v24, v28, v29
	v_cvt_pk_bf16_f32 v25, v30, v31
	v_lshlrev_b32_e32 v28, 16, v120
	v_and_b32_e32 v29, 0xffff0000, v120
	v_lshlrev_b32_e32 v30, 16, v121
	v_and_b32_e32 v31, 0xffff0000, v121
	v_pk_fma_f32 v[22:23], v[22:23], 0.5, v[30:31] op_sel_hi:[1,0,1]
	v_pk_fma_f32 v[20:21], v[20:21], 0.5, v[28:29] op_sel_hi:[1,0,1]
	v_lshlrev_b32_e32 v28, 16, v122
	v_and_b32_e32 v29, 0xffff0000, v122
	v_pk_fma_f32 v[28:29], v[16:17], 0.5, v[28:29] op_sel_hi:[1,0,1]
	v_mul_f32_e32 v16, v21, v21
	v_mul_f32_e32 v17, v23, v23
	v_fmac_f32_e32 v16, v20, v20
	v_fmac_f32_e32 v17, v22, v22
	v_lshlrev_b32_e32 v30, 16, v123
	v_and_b32_e32 v31, 0xffff0000, v123
	v_add_f32_e32 v16, v16, v17
	v_mul_f32_e32 v17, v29, v29
	v_pk_fma_f32 v[30:31], v[18:19], 0.5, v[30:31] op_sel_hi:[1,0,1]
	v_fmac_f32_e32 v17, v28, v28
	v_add_f32_e32 v16, v17, v16
	v_mul_f32_e32 v17, v31, v31
	v_fmac_f32_e32 v17, v30, v30
	v_add_f32_e32 v16, v17, v16
	v_add_f32_e32 v19, v32, v16
	v_cvt_pk_bf16_f32 v26, v26, v27
	v_cvt_pk_bf16_f32 v27, v34, v35
	v_mov_b32_e32 v34, v19
	s_nop 1
	v_permlane16_swap_b32_e32 v34, v19
	v_lshl_add_u64 v[16:17], s[36:37], 0, v[208:209]
	v_lshl_add_u64 v[32:33], v[204:205], 1, v[16:17]
	global_store_dwordx4 v[32:33], v[24:27], off
	v_cvt_pk_bf16_f32 v18, v20, v21
	s_waitcnt lgkmcnt(0)
	v_add_f32_e32 v16, v19, v34
	v_mov_b32_e32 v17, v16
	s_nop 1
	v_permlane32_swap_b32_e32 v17, v16
	v_cvt_pk_bf16_f32 v19, v22, v23
	v_cvt_pk_bf16_f32 v20, v28, v29
	v_cvt_pk_bf16_f32 v21, v30, v31
	global_store_dwordx4 v[32:33], v[18:21], off offset:256
	s_and_saveexec_b64 s[34:35], s[4:5]
	s_cbranch_execz .LBB0_1842
	s_add_u32 s46, s54, s20
	s_addc_u32 s47, s55, s21
	v_lshl_add_u64 v[18:19], v[202:203], 2, s[46:47]
	s_waitcnt lgkmcnt(0)
	v_add_f32_e32 v16, v16, v17
	global_store_dword v[18:19], v16, off offset:640
.LBB0_1842:
	s_or_b64 exec, exec, s[34:35]
	v_lshlrev_b32_e32 v16, 16, v108
	s_waitcnt lgkmcnt(0)
	v_and_b32_e32 v17, 0xffff0000, v108
	v_lshlrev_b32_e32 v18, 16, v109
	v_and_b32_e32 v19, 0xffff0000, v109
	v_pk_fma_f32 v[14:15], v[14:15], 0.5, v[18:19] op_sel_hi:[1,0,1]
	v_pk_fma_f32 v[12:13], v[12:13], 0.5, v[16:17] op_sel_hi:[1,0,1]
	v_lshlrev_b32_e32 v16, 16, v110
	v_and_b32_e32 v17, 0xffff0000, v110
	v_lshlrev_b32_e32 v18, 16, v111
	v_and_b32_e32 v19, 0xffff0000, v111
	v_pk_fma_f32 v[18:19], v[10:11], 0.5, v[18:19] op_sel_hi:[1,0,1]
	v_pk_fma_f32 v[10:11], v[8:9], 0.5, v[16:17] op_sel_hi:[1,0,1]
	v_mul_f32_e32 v8, v13, v13
	v_mul_f32_e32 v9, v15, v15
	v_fmac_f32_e32 v8, v12, v12
	v_fmac_f32_e32 v9, v14, v14
	v_add_f32_e32 v8, v8, v9
	v_mul_f32_e32 v9, v11, v11
	v_fmac_f32_e32 v9, v10, v10
	v_add_f32_e32 v8, v9, v8
	v_mul_f32_e32 v9, v19, v19
	v_fmac_f32_e32 v9, v18, v18
	v_add_f32_e32 v16, v9, v8
	v_cvt_pk_bf16_f32 v8, v12, v13
	v_cvt_pk_bf16_f32 v9, v14, v15
	v_lshlrev_b32_e32 v12, 16, v96
	v_and_b32_e32 v13, 0xffff0000, v96
	v_lshlrev_b32_e32 v14, 16, v97
	v_and_b32_e32 v15, 0xffff0000, v97
	v_pk_fma_f32 v[6:7], v[6:7], 0.5, v[14:15] op_sel_hi:[1,0,1]
	v_pk_fma_f32 v[4:5], v[4:5], 0.5, v[12:13] op_sel_hi:[1,0,1]
	v_lshlrev_b32_e32 v12, 16, v98
	v_and_b32_e32 v13, 0xffff0000, v98
	v_pk_fma_f32 v[12:13], v[0:1], 0.5, v[12:13] op_sel_hi:[1,0,1]
	v_mul_f32_e32 v0, v5, v5
	v_mul_f32_e32 v1, v7, v7
	v_fmac_f32_e32 v0, v4, v4
	v_fmac_f32_e32 v1, v6, v6
	v_lshlrev_b32_e32 v14, 16, v99
	v_and_b32_e32 v15, 0xffff0000, v99
	v_add_f32_e32 v0, v0, v1
	v_mul_f32_e32 v1, v13, v13
	v_pk_fma_f32 v[14:15], v[2:3], 0.5, v[14:15] op_sel_hi:[1,0,1]
	v_fmac_f32_e32 v1, v12, v12
	v_add_f32_e32 v0, v1, v0
	v_mul_f32_e32 v1, v15, v15
	v_fmac_f32_e32 v1, v14, v14
	v_add_f32_e32 v0, v1, v0
	v_add_f32_e32 v3, v16, v0
	v_cvt_pk_bf16_f32 v10, v10, v11
	v_cvt_pk_bf16_f32 v11, v18, v19
	v_mov_b32_e32 v18, v3
	s_nop 1
	v_permlane16_swap_b32_e32 v18, v3
	v_lshl_add_u64 v[0:1], s[36:37], 0, v[206:207]
	v_lshl_add_u64 v[16:17], v[204:205], 1, v[0:1]
	global_store_dwordx4 v[16:17], v[8:11], off
	v_cvt_pk_bf16_f32 v2, v4, v5
	s_waitcnt lgkmcnt(0)
	v_add_f32_e32 v0, v3, v18
	v_mov_b32_e32 v1, v0
	s_nop 1
	v_permlane32_swap_b32_e32 v1, v0
	v_cvt_pk_bf16_f32 v3, v6, v7
	v_cvt_pk_bf16_f32 v4, v12, v13
	v_cvt_pk_bf16_f32 v5, v14, v15
	global_store_dwordx4 v[16:17], v[2:5], off offset:256
	s_and_saveexec_b64 s[34:35], s[4:5]
	s_cbranch_execz .LBB0_1844
	s_add_u32 s20, s54, s20
	s_addc_u32 s21, s55, s21
	v_lshl_add_u64 v[2:3], v[202:203], 2, s[20:21]
	s_waitcnt lgkmcnt(0)
	v_add_f32_e32 v0, v0, v1
	global_store_dword v[2:3], v0, off offset:704
